# strategy 4: all per-segment s_setprio flips removed from K-loops, one static s_setprio 1 for waves 0-3 at entry (saddr DMA + peeled K-loop + P3 rebalance/epilogue kept; no early barrier)
# speedup vs baseline: 1.0025x; 1.0025x over previous
.LBB0_11:
	s_or_b64 exec, exec, s[0:1]
	s_lshr_b32 s0, s3, 6
	s_cmp_lt_u32 s0, 4
	s_cbranch_scc0 .Lprio_static_skip
	s_setprio 1
.Lprio_static_skip:
	s_add_u32 s60, s96, 0x4200000
	s_addc_u32 s33, s97, 0
	s_add_u32 s88, s96, 0x100000
	s_addc_u32 s1, s97, 0
	s_add_u32 s68, s96, 0x300000
	v_writelane_b32 v253, s1, 32
	s_addc_u32 s1, s97, 0
	s_lshl_b32 s3, s28, 3
	v_writelane_b32 v253, s1, 33
	s_add_i32 s3, s3, s0
	v_and_b32_e32 v190, 63, v188
	v_writelane_b32 v253, s0, 34
	s_cmpk_lg_i32 s34, 0x100
	s_mov_b64 s[0:1], -1
	s_cbranch_scc0 .LBB0_54
	s_cmpk_gt_i32 s3, 0x167f
	s_cbranch_scc1 .LBB0_53
	v_readlane_b32 s1, v253, 33
	v_readlane_b32 s0, v253, 34
	v_lshlrev_b32_e32 v2, 3, v188
	v_lshlrev_b32_e32 v4, 11, v188
	s_and_b32 s69, s1, 0xffff
	s_mov_b32 s1, 0x18030
	s_lshl_b32 s0, s0, 14
	v_bitop3_b32 v81, v2, s1, v4 bitop3:0xc8
	v_readlane_b32 s1, v253, 32
	s_lshl_b32 s35, s34, 3
	s_addk_i32 s0, 0x100
	s_and_b32 s61, s33, 0xffff
	s_and_b32 s89, s1, 0xffff
	s_add_u32 s36, s96, 0x900000
	s_addc_u32 s37, s97, 0
	v_readlane_b32 s12, v253, 14
	v_lshlrev_b32_e32 v4, 1, v188
	v_readlane_b32 s20, v253, 22
	v_readlane_b32 s21, v253, 23
	s_cmp_lg_u64 s[82:83], 0
	v_and_b32_e32 v2, 60, v198
	v_and_b32_e32 v4, 0x60, v4
	v_and_b32_e32 v6, 7, v188
	s_cselect_b64 s[28:29], -1, 0
	s_cmp_lg_u64 s[20:21], 0
	v_add_u32_e32 v4, s0, v4
	v_mul_u32_u24_e32 v5, 0x90, v2
	v_lshl_add_u32 v6, v6, 4, s0
	s_cselect_b64 s[30:31], -1, 0
	s_lshl_b32 s0, s3, 13
	v_lshlrev_b32_e32 v74, 2, v2
	v_mbcnt_lo_u32_b32 v2, -1, 0
	v_mov_b32_e32 v67, 0
	v_lshrrev_b32_e32 v1, 3, v190
	v_and_b32_e32 v83, 48, v188
	v_lshlrev_b32_e32 v8, 3, v190
	s_add_i32 s42, s0, 0xfd500000
	s_lshl_b32 s0, s3, 2
	v_mbcnt_hi_u32_b32 v91, -1, v2
	v_and_b32_e32 v3, 1, v188
	s_mov_b32 s11, 0x20000
	s_brev_b32 s10, -2
	v_lshlrev_b32_e32 v7, 4, v188
	v_and_b32_e32 v8, 64, v8
	v_mul_u32_u24_e32 v9, 0x90, v1
	v_lshlrev_b32_e32 v66, 2, v83
	v_lshlrev_b32_e32 v70, 4, v190
	v_mov_b32_e32 v71, v67
	s_add_i32 s44, s0, 0xffffaa00
	s_lshl_b32 s0, s3, 12
	v_and_b32_e32 v2, 64, v91
	v_bfe_u32 v80, v190, 3, 1
	s_mov_b32 s70, s10
	s_mov_b32 s71, s11
	v_add_u32_e32 v82, 2, v190
	v_bfe_u32 v84, v188, 2, 1
	v_or_b32_e32 v85, 0x100, v81
	v_lshl_add_u64 v[68:69], s[20:21], 0, v[66:67]
	v_lshl_add_u64 v[72:73], s[82:83], 0, v[70:71]
	v_and_or_b32 v71, v7, 48, v8
	s_lshl_b32 s38, s3, 6
	s_lshl_b32 s39, s34, 9
	s_lshl_b32 s40, s3, 5
	s_lshl_b32 s41, s34, 8
	s_lshl_b32 s43, s34, 16
	s_lshl_b32 s45, s34, 5
	s_add_i32 s52, s0, 0xfea80000
	s_lshl_b32 s46, s34, 15
	s_movk_i32 s47, 0x2000
	s_movk_i32 s48, 0x3000
	v_cndmask_b32_e64 v86, 0, 1, s[28:29]
	v_mov_b32_e32 v87, 0x358637bd
	s_mov_b32 s49, 0xf800000
	v_mov_b32_e32 v88, 0x260
	v_add_u32_e32 v89, v4, v5
	v_add_u32_e32 v90, v6, v9
	v_lshlrev_b32_e32 v66, 4, v190
	v_add_u32_e32 v92, 64, v2
	v_xor_b32_e32 v93, 1, v91
	v_xor_b32_e32 v94, 2, v91
	v_xor_b32_e32 v95, 4, v91
	v_xor_b32_e32 v96, 8, v91
	v_xor_b32_e32 v97, 16, v91
	v_xor_b32_e32 v98, 32, v91
	s_mov_b32 s50, s3
	s_mov_b32 s55, 0
	v_cmp_eq_u32_e64 s[0:1], 0, v3
	v_cmp_gt_u32_e64 s[4:5], 2, v190
	s_mov_b64 s[56:57], 0x1000
	s_mov_b64 s[58:59], 0x2000
	s_mov_b64 s[64:65], 0x3000
	v_readlane_b32 s13, v253, 15
	v_readlane_b32 s14, v253, 16
	v_readlane_b32 s15, v253, 17
	v_readlane_b32 s16, v253, 18
	v_readlane_b32 s17, v253, 19
	v_readlane_b32 s18, v253, 20
	v_readlane_b32 s19, v253, 21
	v_readlane_b32 s22, v253, 24
	v_readlane_b32 s23, v253, 25
	v_readlane_b32 s24, v253, 26
	v_readlane_b32 s25, v253, 27
	v_readlane_b32 s26, v253, 28
	v_readlane_b32 s27, v253, 29
	s_branch .LBB0_16

.LBB0_267:
	s_mov_b32 s49, s35
	s_add_i32 s35, s35, 1
	s_cmp_lt_u32 s35, s15
	s_mov_b64 s[30:31], s[28:29]
	s_mov_b32 s28, s48
	s_cselect_b64 s[54:55], -1, 0
	s_add_i32 s48, s35, s4
	s_mov_b64 s[52:53], s[6:7]
	s_and_b64 s[6:7], s[54:55], exec
	s_cselect_b32 s6, s48, s28
	s_cselect_b32 s28, s58, s58
	s_ashr_i32 s29, s28, 31
	s_lshl_b64 s[28:29], s[28:29], 19
	s_add_u32 s28, s60, s28
	s_addc_u32 s29, s33, s29
	s_and_b64 s[50:51], s[54:55], exec
	s_cselect_b32 s50, s29, s31
	s_cselect_b32 s51, s28, s30
	s_ashr_i32 s7, s6, 31
	s_lshl_b64 s[6:7], s[6:7], 19
	s_add_u32 s6, s86, s6
	s_addc_u32 s7, s87, s7
	s_and_b64 s[54:55], s[54:55], exec
	s_cselect_b32 s54, s7, s53
	s_cselect_b32 s55, s6, s52
	s_add_u32 s61, s52, 0x10000
	s_addc_u32 s66, s53, 0
	s_mov_b32 s67, -2
	v_add_u32_e32 v160, s43, v1
	ds_read_b128 v[156:159], v160
	ds_read_b128 v[162:165], v160 offset:1024
	ds_read_b128 v[166:169], v160 offset:2048
	ds_read_b128 v[170:173], v160 offset:3072
	v_add_u32_e32 v160, s44, v1
	ds_read_b128 v[174:177], v160
	ds_read_b128 v[178:181], v160 offset:1024
	ds_read_b128 v[182:185], v160 offset:2048
	ds_read_b128 v[192:195], v160 offset:3072
	s_add_u32 s52, s30, 0x10000
	s_addc_u32 s53, s31, 0
	s_cmp_eq_u32 s67, 12
	s_cselect_b32 s64, s51, s52
	s_cselect_b32 s65, s50, s53
	s_cselect_b32 s62, s55, s61
	s_cselect_b32 s63, s54, s66
	s_add_u32 s56, s64, 0x8000
	s_addc_u32 s57, s65, 0
	s_add_i32 m0, s36, 0xc000
	ds_read_b128 v[200:203], v155
	ds_read_b128 v[204:207], v155 offset:1024
	ds_read_b128 v[208:211], v155 offset:2048
	ds_read_b128 v[212:215], v155 offset:3072
	ds_read_b128 v[216:219], v155 offset:4096
	ds_read_b128 v[220:223], v155 offset:5120
	ds_read_b128 v[224:227], v155 offset:6144
	ds_read_b128 v[228:231], v155 offset:7168
	global_load_lds_dwordx4 v146, s[30:31] sc1
	s_add_i32 m0, s36, 0xe000
	s_nop 0
	global_load_lds_dwordx4 v148, s[30:31] sc1
	s_waitcnt vmcnt(8)
	s_waitcnt lgkmcnt(0)
	s_barrier
	s_waitcnt lgkmcnt(0)
	v_mfma_f32_16x16x32_bf16 v[118:121], v[156:159], v[200:203], 0
	v_mfma_f32_16x16x32_bf16 v[110:113], v[166:169], v[200:203], 0
	v_mfma_f32_16x16x32_bf16 v[102:105], v[156:159], v[208:211], 0
	v_mfma_f32_16x16x32_bf16 v[94:97], v[166:169], v[208:211], 0
	v_mfma_f32_16x16x32_bf16 v[86:89], v[156:159], v[216:219], 0
	v_mfma_f32_16x16x32_bf16 v[78:81], v[166:169], v[216:219], 0
	v_mfma_f32_16x16x32_bf16 v[62:65], v[156:159], v[224:227], 0
	v_mfma_f32_16x16x32_bf16 v[54:57], v[166:169], v[224:227], 0
	v_mfma_f32_16x16x32_bf16 v[118:121], v[162:165], v[204:207], v[118:121]
	v_mfma_f32_16x16x32_bf16 v[110:113], v[170:173], v[204:207], v[110:113]
	v_mfma_f32_16x16x32_bf16 v[102:105], v[162:165], v[212:215], v[102:105]
	v_mfma_f32_16x16x32_bf16 v[94:97], v[170:173], v[212:215], v[94:97]
	v_mfma_f32_16x16x32_bf16 v[86:89], v[162:165], v[220:223], v[86:89]
	v_mfma_f32_16x16x32_bf16 v[78:81], v[170:173], v[220:223], v[78:81]
	v_mfma_f32_16x16x32_bf16 v[62:65], v[162:165], v[228:231], v[62:65]
	v_mfma_f32_16x16x32_bf16 v[54:57], v[170:173], v[228:231], v[54:57]
	v_mfma_f32_16x16x32_bf16 v[126:129], v[174:177], v[200:203], 0
	v_mfma_f32_16x16x32_bf16 v[122:125], v[182:185], v[200:203], 0
	v_mfma_f32_16x16x32_bf16 v[114:117], v[174:177], v[208:211], 0
	v_mfma_f32_16x16x32_bf16 v[106:109], v[182:185], v[208:211], 0
	v_mfma_f32_16x16x32_bf16 v[98:101], v[174:177], v[216:219], 0
	v_mfma_f32_16x16x32_bf16 v[90:93], v[182:185], v[216:219], 0
	v_mfma_f32_16x16x32_bf16 v[82:85], v[174:177], v[224:227], 0
	v_mfma_f32_16x16x32_bf16 v[70:73], v[182:185], v[224:227], 0
	v_mfma_f32_16x16x32_bf16 v[126:129], v[178:181], v[204:207], v[126:129]
	v_mfma_f32_16x16x32_bf16 v[122:125], v[192:195], v[204:207], v[122:125]
	v_mfma_f32_16x16x32_bf16 v[114:117], v[178:181], v[212:215], v[114:117]
	v_mfma_f32_16x16x32_bf16 v[106:109], v[192:195], v[212:215], v[106:109]
	v_mfma_f32_16x16x32_bf16 v[98:101], v[178:181], v[220:223], v[98:101]
	v_mfma_f32_16x16x32_bf16 v[90:93], v[192:195], v[220:223], v[90:93]
	v_mfma_f32_16x16x32_bf16 v[82:85], v[178:181], v[228:231], v[82:85]
	v_mfma_f32_16x16x32_bf16 v[70:73], v[192:195], v[228:231], v[70:73]
	s_barrier
	s_add_i32 s30, s43, s5
	s_mov_b32 m0, s30
	ds_read_b128 v[200:203], v155 offset:16384
	ds_read_b128 v[204:207], v155 offset:17408
	ds_read_b128 v[208:211], v155 offset:18432
	ds_read_b128 v[212:215], v155 offset:19456
	ds_read_b128 v[216:219], v155 offset:20480
	ds_read_b128 v[220:223], v155 offset:21504
	ds_read_b128 v[224:227], v155 offset:22528
	ds_read_b128 v[228:231], v155 offset:23552
	global_load_lds_dwordx4 v134, s[62:63] sc1
	s_add_i32 m0, s30, 0x2000
	s_add_u32 s30, s62, 0x4000
	s_addc_u32 s31, s63, 0
	s_add_i32 s69, s44, s5
	global_load_lds_dwordx4 v136, s[62:63] sc1
	s_mov_b32 m0, s69
	s_nop 0
	global_load_lds_dwordx4 v134, s[30:31] sc1
	s_add_i32 m0, s69, 0x2000
	s_nop 0
	global_load_lds_dwordx4 v136, s[30:31] sc1
	s_mov_b32 m0, s36
	s_nop 0
	global_load_lds_dwordx4 v132, s[64:65] sc1
	s_mov_b32 m0, s37
	s_nop 0
	global_load_lds_dwordx4 v130, s[64:65] sc1
	s_waitcnt vmcnt(8)
	s_waitcnt lgkmcnt(0)
	s_barrier
	s_waitcnt lgkmcnt(0)
	v_mfma_f32_16x16x32_bf16 v[58:61], v[156:159], v[200:203], 0
	v_mfma_f32_16x16x32_bf16 v[46:49], v[166:169], v[200:203], 0
	v_mfma_f32_16x16x32_bf16 v[38:41], v[156:159], v[208:211], 0
	v_mfma_f32_16x16x32_bf16 v[30:33], v[166:169], v[208:211], 0
	v_mfma_f32_16x16x32_bf16 v[22:25], v[156:159], v[216:219], 0
	v_mfma_f32_16x16x32_bf16 v[14:17], v[166:169], v[216:219], 0
	v_mfma_f32_16x16x32_bf16 v[6:9], v[156:159], v[224:227], 0
	v_mfma_f32_16x16x32_bf16 v[2:5], v[166:169], v[224:227], 0
	v_mfma_f32_16x16x32_bf16 v[58:61], v[162:165], v[204:207], v[58:61]
	v_mfma_f32_16x16x32_bf16 v[46:49], v[170:173], v[204:207], v[46:49]
	v_mfma_f32_16x16x32_bf16 v[38:41], v[162:165], v[212:215], v[38:41]
	v_mfma_f32_16x16x32_bf16 v[30:33], v[170:173], v[212:215], v[30:33]
	v_mfma_f32_16x16x32_bf16 v[22:25], v[162:165], v[220:223], v[22:25]
	v_mfma_f32_16x16x32_bf16 v[14:17], v[170:173], v[220:223], v[14:17]
	v_mfma_f32_16x16x32_bf16 v[6:9], v[162:165], v[228:231], v[6:9]
	v_mfma_f32_16x16x32_bf16 v[2:5], v[170:173], v[228:231], v[2:5]
	v_mfma_f32_16x16x32_bf16 v[74:77], v[174:177], v[200:203], 0
	v_mfma_f32_16x16x32_bf16 v[66:69], v[182:185], v[200:203], 0
	v_mfma_f32_16x16x32_bf16 v[50:53], v[174:177], v[208:211], 0
	v_mfma_f32_16x16x32_bf16 v[42:45], v[182:185], v[208:211], 0
	v_mfma_f32_16x16x32_bf16 v[34:37], v[174:177], v[216:219], 0
	v_mfma_f32_16x16x32_bf16 v[26:29], v[182:185], v[216:219], 0
	v_mfma_f32_16x16x32_bf16 v[18:21], v[174:177], v[224:227], 0
	v_mfma_f32_16x16x32_bf16 v[10:13], v[182:185], v[224:227], 0
	v_mfma_f32_16x16x32_bf16 v[74:77], v[178:181], v[204:207], v[74:77]
	v_mfma_f32_16x16x32_bf16 v[66:69], v[192:195], v[204:207], v[66:69]
	v_mfma_f32_16x16x32_bf16 v[50:53], v[178:181], v[212:215], v[50:53]
	v_mfma_f32_16x16x32_bf16 v[42:45], v[192:195], v[212:215], v[42:45]
	v_mfma_f32_16x16x32_bf16 v[34:37], v[178:181], v[220:223], v[34:37]
	v_mfma_f32_16x16x32_bf16 v[26:29], v[192:195], v[220:223], v[26:29]
	v_mfma_f32_16x16x32_bf16 v[18:21], v[178:181], v[228:231], v[18:21]
	v_mfma_f32_16x16x32_bf16 v[10:13], v[192:195], v[228:231], v[10:13]
	s_barrier
	v_add_u32_e32 v160, s45, v1
	ds_read_b128 v[156:159], v160
	ds_read_b128 v[162:165], v160 offset:1024
	ds_read_b128 v[166:169], v160 offset:2048
	ds_read_b128 v[170:173], v160 offset:3072
	v_add_u32_e32 v160, s46, v1
	ds_read_b128 v[174:177], v160
	ds_read_b128 v[178:181], v160 offset:1024
	ds_read_b128 v[182:185], v160 offset:2048
	ds_read_b128 v[192:195], v160 offset:3072
	s_add_u32 s30, s64, 0x4000
	s_addc_u32 s31, s65, 0
	s_mov_b32 m0, s38
	ds_read_b128 v[200:203], v155 offset:32768
	ds_read_b128 v[204:207], v155 offset:33792
	ds_read_b128 v[208:211], v155 offset:34816
	ds_read_b128 v[212:215], v155 offset:35840
	ds_read_b128 v[216:219], v155 offset:36864
	ds_read_b128 v[220:223], v155 offset:37888
	ds_read_b128 v[224:227], v155 offset:38912
	ds_read_b128 v[228:231], v155 offset:39936
	global_load_lds_dwordx4 v132, s[30:31] sc1
	s_mov_b32 m0, s39
	s_nop 0
	global_load_lds_dwordx4 v130, s[30:31] sc1
	s_waitcnt vmcnt(8)
	s_waitcnt lgkmcnt(0)
	s_barrier
	s_waitcnt lgkmcnt(0)
	v_mfma_f32_16x16x32_bf16 v[118:121], v[156:159], v[200:203], v[118:121]
	v_mfma_f32_16x16x32_bf16 v[110:113], v[166:169], v[200:203], v[110:113]
	v_mfma_f32_16x16x32_bf16 v[102:105], v[156:159], v[208:211], v[102:105]
	v_mfma_f32_16x16x32_bf16 v[94:97], v[166:169], v[208:211], v[94:97]
	v_mfma_f32_16x16x32_bf16 v[86:89], v[156:159], v[216:219], v[86:89]
	v_mfma_f32_16x16x32_bf16 v[78:81], v[166:169], v[216:219], v[78:81]
	v_mfma_f32_16x16x32_bf16 v[62:65], v[156:159], v[224:227], v[62:65]
	v_mfma_f32_16x16x32_bf16 v[54:57], v[166:169], v[224:227], v[54:57]
	v_mfma_f32_16x16x32_bf16 v[118:121], v[162:165], v[204:207], v[118:121]
	v_mfma_f32_16x16x32_bf16 v[110:113], v[170:173], v[204:207], v[110:113]
	v_mfma_f32_16x16x32_bf16 v[102:105], v[162:165], v[212:215], v[102:105]
	v_mfma_f32_16x16x32_bf16 v[94:97], v[170:173], v[212:215], v[94:97]
	v_mfma_f32_16x16x32_bf16 v[86:89], v[162:165], v[220:223], v[86:89]
	v_mfma_f32_16x16x32_bf16 v[78:81], v[170:173], v[220:223], v[78:81]
	v_mfma_f32_16x16x32_bf16 v[62:65], v[162:165], v[228:231], v[62:65]
	v_mfma_f32_16x16x32_bf16 v[54:57], v[170:173], v[228:231], v[54:57]
	v_mfma_f32_16x16x32_bf16 v[126:129], v[174:177], v[200:203], v[126:129]
	v_mfma_f32_16x16x32_bf16 v[122:125], v[182:185], v[200:203], v[122:125]
	v_mfma_f32_16x16x32_bf16 v[114:117], v[174:177], v[208:211], v[114:117]
	v_mfma_f32_16x16x32_bf16 v[106:109], v[182:185], v[208:211], v[106:109]
	v_mfma_f32_16x16x32_bf16 v[98:101], v[174:177], v[216:219], v[98:101]
	v_mfma_f32_16x16x32_bf16 v[90:93], v[182:185], v[216:219], v[90:93]
	v_mfma_f32_16x16x32_bf16 v[82:85], v[174:177], v[224:227], v[82:85]
	v_mfma_f32_16x16x32_bf16 v[70:73], v[182:185], v[224:227], v[70:73]
	v_mfma_f32_16x16x32_bf16 v[126:129], v[178:181], v[204:207], v[126:129]
	v_mfma_f32_16x16x32_bf16 v[122:125], v[192:195], v[204:207], v[122:125]
	v_mfma_f32_16x16x32_bf16 v[114:117], v[178:181], v[212:215], v[114:117]
	v_mfma_f32_16x16x32_bf16 v[106:109], v[192:195], v[212:215], v[106:109]
	v_mfma_f32_16x16x32_bf16 v[98:101], v[178:181], v[220:223], v[98:101]
	v_mfma_f32_16x16x32_bf16 v[90:93], v[192:195], v[220:223], v[90:93]
	v_mfma_f32_16x16x32_bf16 v[82:85], v[178:181], v[228:231], v[82:85]
	v_mfma_f32_16x16x32_bf16 v[70:73], v[192:195], v[228:231], v[70:73]
	s_barrier
	s_add_u32 s30, s62, 0x8000
	s_addc_u32 s31, s63, 0
	s_add_i32 s64, s45, s5
	s_mov_b32 m0, s64
	ds_read_b128 v[200:203], v155 offset:49152
	ds_read_b128 v[204:207], v155 offset:50176
	ds_read_b128 v[208:211], v155 offset:51200
	ds_read_b128 v[212:215], v155 offset:52224
	ds_read_b128 v[216:219], v155 offset:53248
	ds_read_b128 v[220:223], v155 offset:54272
	ds_read_b128 v[224:227], v155 offset:55296
	ds_read_b128 v[228:231], v155 offset:56320
	global_load_lds_dwordx4 v134, s[30:31] sc1
	s_add_i32 m0, s64, 0x2000
	s_nop 0
	global_load_lds_dwordx4 v136, s[30:31] sc1
	s_add_u32 s30, s62, 0xc000
	s_addc_u32 s31, s63, 0
	s_add_i32 s62, s46, s5
	s_mov_b32 m0, s62
	s_nop 0
	global_load_lds_dwordx4 v134, s[30:31] sc1
	s_add_i32 m0, s62, 0x2000
	s_nop 0
	global_load_lds_dwordx4 v136, s[30:31] sc1
	s_mov_b32 m0, s40
	s_nop 0
	global_load_lds_dwordx4 v132, s[56:57] sc1
	s_mov_b32 m0, s41
	s_nop 0
	global_load_lds_dwordx4 v130, s[56:57] sc1
	s_waitcnt vmcnt(8)
	s_waitcnt lgkmcnt(0)
	s_barrier
	s_waitcnt lgkmcnt(0)
	v_mfma_f32_16x16x32_bf16 v[58:61], v[156:159], v[200:203], v[58:61]
	v_mfma_f32_16x16x32_bf16 v[46:49], v[166:169], v[200:203], v[46:49]
	v_mfma_f32_16x16x32_bf16 v[38:41], v[156:159], v[208:211], v[38:41]
	v_mfma_f32_16x16x32_bf16 v[30:33], v[166:169], v[208:211], v[30:33]
	v_mfma_f32_16x16x32_bf16 v[22:25], v[156:159], v[216:219], v[22:25]
	v_mfma_f32_16x16x32_bf16 v[14:17], v[166:169], v[216:219], v[14:17]
	v_mfma_f32_16x16x32_bf16 v[6:9], v[156:159], v[224:227], v[6:9]
	v_mfma_f32_16x16x32_bf16 v[2:5], v[166:169], v[224:227], v[2:5]
	v_mfma_f32_16x16x32_bf16 v[58:61], v[162:165], v[204:207], v[58:61]
	v_mfma_f32_16x16x32_bf16 v[46:49], v[170:173], v[204:207], v[46:49]
	v_mfma_f32_16x16x32_bf16 v[38:41], v[162:165], v[212:215], v[38:41]
	v_mfma_f32_16x16x32_bf16 v[30:33], v[170:173], v[212:215], v[30:33]
	v_mfma_f32_16x16x32_bf16 v[22:25], v[162:165], v[220:223], v[22:25]
	v_mfma_f32_16x16x32_bf16 v[14:17], v[170:173], v[220:223], v[14:17]
	v_mfma_f32_16x16x32_bf16 v[6:9], v[162:165], v[228:231], v[6:9]
	v_mfma_f32_16x16x32_bf16 v[2:5], v[170:173], v[228:231], v[2:5]
	v_mfma_f32_16x16x32_bf16 v[74:77], v[174:177], v[200:203], v[74:77]
	v_mfma_f32_16x16x32_bf16 v[66:69], v[182:185], v[200:203], v[66:69]
	v_mfma_f32_16x16x32_bf16 v[50:53], v[174:177], v[208:211], v[50:53]
	v_mfma_f32_16x16x32_bf16 v[42:45], v[182:185], v[208:211], v[42:45]
	v_mfma_f32_16x16x32_bf16 v[34:37], v[174:177], v[216:219], v[34:37]
	v_mfma_f32_16x16x32_bf16 v[26:29], v[182:185], v[216:219], v[26:29]
	v_mfma_f32_16x16x32_bf16 v[18:21], v[174:177], v[224:227], v[18:21]
	v_mfma_f32_16x16x32_bf16 v[10:13], v[182:185], v[224:227], v[10:13]
	v_mfma_f32_16x16x32_bf16 v[74:77], v[178:181], v[204:207], v[74:77]
	v_mfma_f32_16x16x32_bf16 v[66:69], v[192:195], v[204:207], v[66:69]
	v_mfma_f32_16x16x32_bf16 v[50:53], v[178:181], v[212:215], v[50:53]
	v_mfma_f32_16x16x32_bf16 v[42:45], v[192:195], v[212:215], v[42:45]
	v_mfma_f32_16x16x32_bf16 v[34:37], v[178:181], v[220:223], v[34:37]
	v_mfma_f32_16x16x32_bf16 v[26:29], v[192:195], v[220:223], v[26:29]
	v_mfma_f32_16x16x32_bf16 v[18:21], v[178:181], v[228:231], v[18:21]
	v_mfma_f32_16x16x32_bf16 v[10:13], v[192:195], v[228:231], v[10:13]
	s_barrier
	s_add_i32 s67, s67, 2
	s_add_u32 s61, s61, 0x10000
	s_addc_u32 s66, s66, 0
	s_cmp_gt_u32 s67, 13
	s_mov_b64 s[30:31], s[52:53]
.LBB0_268:
	v_add_u32_e32 v160, s43, v1
	ds_read_b128 v[156:159], v160
	ds_read_b128 v[162:165], v160 offset:1024
	ds_read_b128 v[166:169], v160 offset:2048
	ds_read_b128 v[170:173], v160 offset:3072
	v_add_u32_e32 v160, s44, v1
	ds_read_b128 v[174:177], v160
	ds_read_b128 v[178:181], v160 offset:1024
	ds_read_b128 v[182:185], v160 offset:2048
	ds_read_b128 v[192:195], v160 offset:3072
	s_add_u32 s52, s30, 0x10000
	s_addc_u32 s53, s31, 0
	s_cmp_eq_u32 s67, 12
	s_cselect_b32 s64, s51, s52
	s_cselect_b32 s65, s50, s53
	s_cselect_b32 s62, s55, s61
	s_cselect_b32 s63, s54, s66
	s_add_u32 s56, s64, 0x8000
	s_addc_u32 s57, s65, 0
	s_add_i32 m0, s36, 0xc000
	ds_read_b128 v[200:203], v155
	ds_read_b128 v[204:207], v155 offset:1024
	ds_read_b128 v[208:211], v155 offset:2048
	ds_read_b128 v[212:215], v155 offset:3072
	ds_read_b128 v[216:219], v155 offset:4096
	ds_read_b128 v[220:223], v155 offset:5120
	ds_read_b128 v[224:227], v155 offset:6144
	ds_read_b128 v[228:231], v155 offset:7168
	global_load_lds_dwordx4 v146, s[30:31] sc1
	s_add_i32 m0, s36, 0xe000
	s_nop 0
	global_load_lds_dwordx4 v148, s[30:31] sc1
	s_waitcnt vmcnt(8)
	s_waitcnt lgkmcnt(0)
	s_barrier
	s_waitcnt lgkmcnt(0)
	v_mfma_f32_16x16x32_bf16 v[118:121], v[156:159], v[200:203], v[118:121]
	v_mfma_f32_16x16x32_bf16 v[110:113], v[166:169], v[200:203], v[110:113]
	v_mfma_f32_16x16x32_bf16 v[102:105], v[156:159], v[208:211], v[102:105]
	v_mfma_f32_16x16x32_bf16 v[94:97], v[166:169], v[208:211], v[94:97]
	v_mfma_f32_16x16x32_bf16 v[86:89], v[156:159], v[216:219], v[86:89]
	v_mfma_f32_16x16x32_bf16 v[78:81], v[166:169], v[216:219], v[78:81]
	v_mfma_f32_16x16x32_bf16 v[62:65], v[156:159], v[224:227], v[62:65]
	v_mfma_f32_16x16x32_bf16 v[54:57], v[166:169], v[224:227], v[54:57]
	v_mfma_f32_16x16x32_bf16 v[118:121], v[162:165], v[204:207], v[118:121]
	v_mfma_f32_16x16x32_bf16 v[110:113], v[170:173], v[204:207], v[110:113]
	v_mfma_f32_16x16x32_bf16 v[102:105], v[162:165], v[212:215], v[102:105]
	v_mfma_f32_16x16x32_bf16 v[94:97], v[170:173], v[212:215], v[94:97]
	v_mfma_f32_16x16x32_bf16 v[86:89], v[162:165], v[220:223], v[86:89]
	v_mfma_f32_16x16x32_bf16 v[78:81], v[170:173], v[220:223], v[78:81]
	v_mfma_f32_16x16x32_bf16 v[62:65], v[162:165], v[228:231], v[62:65]
	v_mfma_f32_16x16x32_bf16 v[54:57], v[170:173], v[228:231], v[54:57]
	v_mfma_f32_16x16x32_bf16 v[126:129], v[174:177], v[200:203], v[126:129]
	v_mfma_f32_16x16x32_bf16 v[122:125], v[182:185], v[200:203], v[122:125]
	v_mfma_f32_16x16x32_bf16 v[114:117], v[174:177], v[208:211], v[114:117]
	v_mfma_f32_16x16x32_bf16 v[106:109], v[182:185], v[208:211], v[106:109]
	v_mfma_f32_16x16x32_bf16 v[98:101], v[174:177], v[216:219], v[98:101]
	v_mfma_f32_16x16x32_bf16 v[90:93], v[182:185], v[216:219], v[90:93]
	v_mfma_f32_16x16x32_bf16 v[82:85], v[174:177], v[224:227], v[82:85]
	v_mfma_f32_16x16x32_bf16 v[70:73], v[182:185], v[224:227], v[70:73]
	v_mfma_f32_16x16x32_bf16 v[126:129], v[178:181], v[204:207], v[126:129]
	v_mfma_f32_16x16x32_bf16 v[122:125], v[192:195], v[204:207], v[122:125]
	v_mfma_f32_16x16x32_bf16 v[114:117], v[178:181], v[212:215], v[114:117]
	v_mfma_f32_16x16x32_bf16 v[106:109], v[192:195], v[212:215], v[106:109]
	v_mfma_f32_16x16x32_bf16 v[98:101], v[178:181], v[220:223], v[98:101]
	v_mfma_f32_16x16x32_bf16 v[90:93], v[192:195], v[220:223], v[90:93]
	v_mfma_f32_16x16x32_bf16 v[82:85], v[178:181], v[228:231], v[82:85]
	v_mfma_f32_16x16x32_bf16 v[70:73], v[192:195], v[228:231], v[70:73]
	s_barrier
	s_add_i32 s30, s43, s5
	s_mov_b32 m0, s30
	ds_read_b128 v[200:203], v155 offset:16384
	ds_read_b128 v[204:207], v155 offset:17408
	ds_read_b128 v[208:211], v155 offset:18432
	ds_read_b128 v[212:215], v155 offset:19456
	ds_read_b128 v[216:219], v155 offset:20480
	ds_read_b128 v[220:223], v155 offset:21504
	ds_read_b128 v[224:227], v155 offset:22528
	ds_read_b128 v[228:231], v155 offset:23552
	global_load_lds_dwordx4 v134, s[62:63] sc1
	s_add_i32 m0, s30, 0x2000
	s_add_u32 s30, s62, 0x4000
	s_addc_u32 s31, s63, 0
	s_add_i32 s69, s44, s5
	global_load_lds_dwordx4 v136, s[62:63] sc1
	s_mov_b32 m0, s69
	s_nop 0
	global_load_lds_dwordx4 v134, s[30:31] sc1
	s_add_i32 m0, s69, 0x2000
	s_nop 0
	global_load_lds_dwordx4 v136, s[30:31] sc1
	s_mov_b32 m0, s36
	s_nop 0
	global_load_lds_dwordx4 v132, s[64:65] sc1
	s_mov_b32 m0, s37
	s_nop 0
	global_load_lds_dwordx4 v130, s[64:65] sc1
	s_waitcnt vmcnt(8)
	s_waitcnt lgkmcnt(0)
	s_barrier
	s_waitcnt lgkmcnt(0)
	v_mfma_f32_16x16x32_bf16 v[58:61], v[156:159], v[200:203], v[58:61]
	v_mfma_f32_16x16x32_bf16 v[46:49], v[166:169], v[200:203], v[46:49]
	v_mfma_f32_16x16x32_bf16 v[38:41], v[156:159], v[208:211], v[38:41]
	v_mfma_f32_16x16x32_bf16 v[30:33], v[166:169], v[208:211], v[30:33]
	v_mfma_f32_16x16x32_bf16 v[22:25], v[156:159], v[216:219], v[22:25]
	v_mfma_f32_16x16x32_bf16 v[14:17], v[166:169], v[216:219], v[14:17]
	v_mfma_f32_16x16x32_bf16 v[6:9], v[156:159], v[224:227], v[6:9]
	v_mfma_f32_16x16x32_bf16 v[2:5], v[166:169], v[224:227], v[2:5]
	v_mfma_f32_16x16x32_bf16 v[58:61], v[162:165], v[204:207], v[58:61]
	v_mfma_f32_16x16x32_bf16 v[46:49], v[170:173], v[204:207], v[46:49]
	v_mfma_f32_16x16x32_bf16 v[38:41], v[162:165], v[212:215], v[38:41]
	v_mfma_f32_16x16x32_bf16 v[30:33], v[170:173], v[212:215], v[30:33]
	v_mfma_f32_16x16x32_bf16 v[22:25], v[162:165], v[220:223], v[22:25]
	v_mfma_f32_16x16x32_bf16 v[14:17], v[170:173], v[220:223], v[14:17]
	v_mfma_f32_16x16x32_bf16 v[6:9], v[162:165], v[228:231], v[6:9]
	v_mfma_f32_16x16x32_bf16 v[2:5], v[170:173], v[228:231], v[2:5]
	v_mfma_f32_16x16x32_bf16 v[74:77], v[174:177], v[200:203], v[74:77]
	v_mfma_f32_16x16x32_bf16 v[66:69], v[182:185], v[200:203], v[66:69]
	v_mfma_f32_16x16x32_bf16 v[50:53], v[174:177], v[208:211], v[50:53]
	v_mfma_f32_16x16x32_bf16 v[42:45], v[182:185], v[208:211], v[42:45]
	v_mfma_f32_16x16x32_bf16 v[34:37], v[174:177], v[216:219], v[34:37]
	v_mfma_f32_16x16x32_bf16 v[26:29], v[182:185], v[216:219], v[26:29]
	v_mfma_f32_16x16x32_bf16 v[18:21], v[174:177], v[224:227], v[18:21]
	v_mfma_f32_16x16x32_bf16 v[10:13], v[182:185], v[224:227], v[10:13]
	v_mfma_f32_16x16x32_bf16 v[74:77], v[178:181], v[204:207], v[74:77]
	v_mfma_f32_16x16x32_bf16 v[66:69], v[192:195], v[204:207], v[66:69]
	v_mfma_f32_16x16x32_bf16 v[50:53], v[178:181], v[212:215], v[50:53]
	v_mfma_f32_16x16x32_bf16 v[42:45], v[192:195], v[212:215], v[42:45]
	v_mfma_f32_16x16x32_bf16 v[34:37], v[178:181], v[220:223], v[34:37]
	v_mfma_f32_16x16x32_bf16 v[26:29], v[192:195], v[220:223], v[26:29]
	v_mfma_f32_16x16x32_bf16 v[18:21], v[178:181], v[228:231], v[18:21]
	v_mfma_f32_16x16x32_bf16 v[10:13], v[192:195], v[228:231], v[10:13]
	s_barrier
	v_add_u32_e32 v160, s45, v1
	ds_read_b128 v[156:159], v160
	ds_read_b128 v[162:165], v160 offset:1024
	ds_read_b128 v[166:169], v160 offset:2048
	ds_read_b128 v[170:173], v160 offset:3072
	v_add_u32_e32 v160, s46, v1
	ds_read_b128 v[174:177], v160
	ds_read_b128 v[178:181], v160 offset:1024
	ds_read_b128 v[182:185], v160 offset:2048
	ds_read_b128 v[192:195], v160 offset:3072
	s_add_u32 s30, s64, 0x4000
	s_addc_u32 s31, s65, 0
	s_mov_b32 m0, s38
	ds_read_b128 v[200:203], v155 offset:32768
	ds_read_b128 v[204:207], v155 offset:33792
	ds_read_b128 v[208:211], v155 offset:34816
	ds_read_b128 v[212:215], v155 offset:35840
	ds_read_b128 v[216:219], v155 offset:36864
	ds_read_b128 v[220:223], v155 offset:37888
	ds_read_b128 v[224:227], v155 offset:38912
	ds_read_b128 v[228:231], v155 offset:39936
	global_load_lds_dwordx4 v132, s[30:31] sc1
	s_mov_b32 m0, s39
	s_nop 0
	global_load_lds_dwordx4 v130, s[30:31] sc1
	s_waitcnt vmcnt(8)
	s_waitcnt lgkmcnt(0)
	s_barrier
	s_waitcnt lgkmcnt(0)
	v_mfma_f32_16x16x32_bf16 v[118:121], v[156:159], v[200:203], v[118:121]
	v_mfma_f32_16x16x32_bf16 v[110:113], v[166:169], v[200:203], v[110:113]
	v_mfma_f32_16x16x32_bf16 v[102:105], v[156:159], v[208:211], v[102:105]
	v_mfma_f32_16x16x32_bf16 v[94:97], v[166:169], v[208:211], v[94:97]
	v_mfma_f32_16x16x32_bf16 v[86:89], v[156:159], v[216:219], v[86:89]
	v_mfma_f32_16x16x32_bf16 v[78:81], v[166:169], v[216:219], v[78:81]
	v_mfma_f32_16x16x32_bf16 v[62:65], v[156:159], v[224:227], v[62:65]
	v_mfma_f32_16x16x32_bf16 v[54:57], v[166:169], v[224:227], v[54:57]
	v_mfma_f32_16x16x32_bf16 v[118:121], v[162:165], v[204:207], v[118:121]
	v_mfma_f32_16x16x32_bf16 v[110:113], v[170:173], v[204:207], v[110:113]
	v_mfma_f32_16x16x32_bf16 v[102:105], v[162:165], v[212:215], v[102:105]
	v_mfma_f32_16x16x32_bf16 v[94:97], v[170:173], v[212:215], v[94:97]
	v_mfma_f32_16x16x32_bf16 v[86:89], v[162:165], v[220:223], v[86:89]
	v_mfma_f32_16x16x32_bf16 v[78:81], v[170:173], v[220:223], v[78:81]
	v_mfma_f32_16x16x32_bf16 v[62:65], v[162:165], v[228:231], v[62:65]
	v_mfma_f32_16x16x32_bf16 v[54:57], v[170:173], v[228:231], v[54:57]
	v_mfma_f32_16x16x32_bf16 v[126:129], v[174:177], v[200:203], v[126:129]
	v_mfma_f32_16x16x32_bf16 v[122:125], v[182:185], v[200:203], v[122:125]
	v_mfma_f32_16x16x32_bf16 v[114:117], v[174:177], v[208:211], v[114:117]
	v_mfma_f32_16x16x32_bf16 v[106:109], v[182:185], v[208:211], v[106:109]
	v_mfma_f32_16x16x32_bf16 v[98:101], v[174:177], v[216:219], v[98:101]
	v_mfma_f32_16x16x32_bf16 v[90:93], v[182:185], v[216:219], v[90:93]
	v_mfma_f32_16x16x32_bf16 v[82:85], v[174:177], v[224:227], v[82:85]
	v_mfma_f32_16x16x32_bf16 v[70:73], v[182:185], v[224:227], v[70:73]
	v_mfma_f32_16x16x32_bf16 v[126:129], v[178:181], v[204:207], v[126:129]
	v_mfma_f32_16x16x32_bf16 v[122:125], v[192:195], v[204:207], v[122:125]
	v_mfma_f32_16x16x32_bf16 v[114:117], v[178:181], v[212:215], v[114:117]
	v_mfma_f32_16x16x32_bf16 v[106:109], v[192:195], v[212:215], v[106:109]
	v_mfma_f32_16x16x32_bf16 v[98:101], v[178:181], v[220:223], v[98:101]
	v_mfma_f32_16x16x32_bf16 v[90:93], v[192:195], v[220:223], v[90:93]
	v_mfma_f32_16x16x32_bf16 v[82:85], v[178:181], v[228:231], v[82:85]
	v_mfma_f32_16x16x32_bf16 v[70:73], v[192:195], v[228:231], v[70:73]
	s_barrier
	s_add_u32 s30, s62, 0x8000
	s_addc_u32 s31, s63, 0
	s_add_i32 s64, s45, s5
	s_mov_b32 m0, s64
	ds_read_b128 v[200:203], v155 offset:49152
	ds_read_b128 v[204:207], v155 offset:50176
	ds_read_b128 v[208:211], v155 offset:51200
	ds_read_b128 v[212:215], v155 offset:52224
	ds_read_b128 v[216:219], v155 offset:53248
	ds_read_b128 v[220:223], v155 offset:54272
	ds_read_b128 v[224:227], v155 offset:55296
	ds_read_b128 v[228:231], v155 offset:56320
	global_load_lds_dwordx4 v134, s[30:31] sc1
	s_add_i32 m0, s64, 0x2000
	s_nop 0
	global_load_lds_dwordx4 v136, s[30:31] sc1
	s_add_u32 s30, s62, 0xc000
	s_addc_u32 s31, s63, 0
	s_add_i32 s62, s46, s5
	s_mov_b32 m0, s62
	s_nop 0
	global_load_lds_dwordx4 v134, s[30:31] sc1
	s_add_i32 m0, s62, 0x2000
	s_nop 0
	global_load_lds_dwordx4 v136, s[30:31] sc1
	s_mov_b32 m0, s40
	s_nop 0
	global_load_lds_dwordx4 v132, s[56:57] sc1
	s_mov_b32 m0, s41
	s_nop 0
	global_load_lds_dwordx4 v130, s[56:57] sc1
	s_waitcnt vmcnt(8)
	s_waitcnt lgkmcnt(0)
	s_barrier
	s_waitcnt lgkmcnt(0)
	v_mfma_f32_16x16x32_bf16 v[58:61], v[156:159], v[200:203], v[58:61]
	v_mfma_f32_16x16x32_bf16 v[46:49], v[166:169], v[200:203], v[46:49]
	v_mfma_f32_16x16x32_bf16 v[38:41], v[156:159], v[208:211], v[38:41]
	v_mfma_f32_16x16x32_bf16 v[30:33], v[166:169], v[208:211], v[30:33]
	v_mfma_f32_16x16x32_bf16 v[22:25], v[156:159], v[216:219], v[22:25]
	v_mfma_f32_16x16x32_bf16 v[14:17], v[166:169], v[216:219], v[14:17]
	v_mfma_f32_16x16x32_bf16 v[6:9], v[156:159], v[224:227], v[6:9]
	v_mfma_f32_16x16x32_bf16 v[2:5], v[166:169], v[224:227], v[2:5]
	v_mfma_f32_16x16x32_bf16 v[58:61], v[162:165], v[204:207], v[58:61]
	v_mfma_f32_16x16x32_bf16 v[46:49], v[170:173], v[204:207], v[46:49]
	v_mfma_f32_16x16x32_bf16 v[38:41], v[162:165], v[212:215], v[38:41]
	v_mfma_f32_16x16x32_bf16 v[30:33], v[170:173], v[212:215], v[30:33]
	v_mfma_f32_16x16x32_bf16 v[22:25], v[162:165], v[220:223], v[22:25]
	v_mfma_f32_16x16x32_bf16 v[14:17], v[170:173], v[220:223], v[14:17]
	v_mfma_f32_16x16x32_bf16 v[6:9], v[162:165], v[228:231], v[6:9]
	v_mfma_f32_16x16x32_bf16 v[2:5], v[170:173], v[228:231], v[2:5]
	v_mfma_f32_16x16x32_bf16 v[74:77], v[174:177], v[200:203], v[74:77]
	v_mfma_f32_16x16x32_bf16 v[66:69], v[182:185], v[200:203], v[66:69]
	v_mfma_f32_16x16x32_bf16 v[50:53], v[174:177], v[208:211], v[50:53]
	v_mfma_f32_16x16x32_bf16 v[42:45], v[182:185], v[208:211], v[42:45]
	v_mfma_f32_16x16x32_bf16 v[34:37], v[174:177], v[216:219], v[34:37]
	v_mfma_f32_16x16x32_bf16 v[26:29], v[182:185], v[216:219], v[26:29]
	v_mfma_f32_16x16x32_bf16 v[18:21], v[174:177], v[224:227], v[18:21]
	v_mfma_f32_16x16x32_bf16 v[10:13], v[182:185], v[224:227], v[10:13]
	v_mfma_f32_16x16x32_bf16 v[74:77], v[178:181], v[204:207], v[74:77]
	v_mfma_f32_16x16x32_bf16 v[66:69], v[192:195], v[204:207], v[66:69]
	v_mfma_f32_16x16x32_bf16 v[50:53], v[178:181], v[212:215], v[50:53]
	v_mfma_f32_16x16x32_bf16 v[42:45], v[192:195], v[212:215], v[42:45]
	v_mfma_f32_16x16x32_bf16 v[34:37], v[178:181], v[220:223], v[34:37]
	v_mfma_f32_16x16x32_bf16 v[26:29], v[192:195], v[220:223], v[26:29]
	v_mfma_f32_16x16x32_bf16 v[18:21], v[178:181], v[228:231], v[18:21]
	v_mfma_f32_16x16x32_bf16 v[10:13], v[192:195], v[228:231], v[10:13]
	s_barrier
	s_add_i32 s67, s67, 2
	s_add_u32 s61, s61, 0x10000
	s_addc_u32 s66, s66, 0
	s_cmp_gt_u32 s67, 13
	s_mov_b64 s[30:31], s[52:53]
	s_cbranch_scc0 .LBB0_268
	s_and_b64 vcc, exec, s[10:11]
	s_cbranch_vccz .LBB0_271
	s_barrier

.LBB0_403:
	s_add_u32 s61, s62, 0x10000
	s_addc_u32 s69, s63, 0
	s_lshl_b32 s62, s10, 2
	s_ashr_i32 s29, s28, 31
	s_ashr_i32 s63, s62, 31
	s_lshl_b64 s[64:65], s[28:29], 19
	s_lshl_b64 s[62:63], s[62:63], 15
	s_add_u32 s29, s60, s62
	s_addc_u32 s55, s33, s63
	s_add_u32 s29, s29, s64
	s_addc_u32 s55, s55, s65
	s_add_u32 s62, s29, 0x10000
	s_addc_u32 s63, s55, 0
	s_and_b64 s[8:9], s[8:9], exec
	s_cselect_b32 s70, s57, s63
	s_cselect_b32 s71, s56, s62
	s_cselect_b32 s78, s53, s55
	s_cselect_b32 s79, s52, s29
	v_lshl_add_u64 v[146:147], s[30:31], 0, v[138:139]
	v_lshl_add_u64 v[148:149], s[30:31], 0, v[140:141]
	s_mov_b32 s80, -2
	s_mov_b64 s[8:9], 0
	s_add_u32 s29, s30, s8
	v_add_u32_e32 v157, s45, v153
	s_addc_u32 s55, s31, s9
	ds_read_b128 v[162:165], v157
	ds_read_b128 v[166:169], v157 offset:1024
	ds_read_b128 v[170:173], v157 offset:2048
	ds_read_b128 v[174:177], v157 offset:3072
	v_add_u32_e32 v157, s47, v153
	s_add_u32 s29, s29, 0x10000
	ds_read_b128 v[178:181], v157
	ds_read_b128 v[182:185], v157 offset:1024
	ds_read_b128 v[192:195], v157 offset:2048
	ds_read_b128 v[200:203], v157 offset:3072
	s_addc_u32 s55, s55, 0
	s_add_u32 s62, s61, s8
	s_addc_u32 s63, s69, s9
	s_cmp_eq_u32 s8, 0x150000
	s_cselect_b32 s66, s71, s29
	s_cselect_b32 s67, s70, s55
	s_cselect_b32 s64, s79, s62
	s_cselect_b32 s65, s78, s63
	s_add_u32 s62, s66, 0x8000
	s_addc_u32 s63, s67, 0
	s_add_i32 s29, s37, 0xc000
	v_lshl_add_u64 v[158:159], v[146:147], 0, s[8:9]
	s_mov_b32 m0, s29
	s_add_i32 s55, s37, 0xe000
	ds_read_b128 v[204:207], v155
	ds_read_b128 v[208:211], v155 offset:1024
	ds_read_b128 v[212:215], v155 offset:2048
	ds_read_b128 v[216:219], v155 offset:3072
	ds_read_b128 v[220:223], v155 offset:4096
	ds_read_b128 v[224:227], v155 offset:5120
	ds_read_b128 v[228:231], v155 offset:6144
	ds_read_b128 v[232:235], v155 offset:7168
	global_load_lds_dwordx4 v[158:159], off sc1
	v_lshl_add_u64 v[158:159], v[148:149], 0, s[8:9]
	s_mov_b32 m0, s55
	s_nop 0
	global_load_lds_dwordx4 v[158:159], off sc1
	s_waitcnt vmcnt(8)
	s_waitcnt lgkmcnt(0)
	s_barrier
	s_waitcnt lgkmcnt(0)
	v_mfma_f32_16x16x32_bf16 v[114:117], v[162:165], v[204:207], 0
	v_mfma_f32_16x16x32_bf16 v[118:121], v[170:173], v[204:207], 0
	v_mfma_f32_16x16x32_bf16 v[98:101], v[162:165], v[212:215], 0
	v_mfma_f32_16x16x32_bf16 v[102:105], v[170:173], v[212:215], 0
	v_mfma_f32_16x16x32_bf16 v[82:85], v[162:165], v[220:223], 0
	v_mfma_f32_16x16x32_bf16 v[86:89], v[170:173], v[220:223], 0
	v_mfma_f32_16x16x32_bf16 v[66:69], v[162:165], v[228:231], 0
	v_mfma_f32_16x16x32_bf16 v[70:73], v[170:173], v[228:231], 0
	v_mfma_f32_16x16x32_bf16 v[114:117], v[166:169], v[208:211], v[114:117]
	v_mfma_f32_16x16x32_bf16 v[118:121], v[174:177], v[208:211], v[118:121]
	v_mfma_f32_16x16x32_bf16 v[98:101], v[166:169], v[216:219], v[98:101]
	v_mfma_f32_16x16x32_bf16 v[102:105], v[174:177], v[216:219], v[102:105]
	v_mfma_f32_16x16x32_bf16 v[82:85], v[166:169], v[224:227], v[82:85]
	v_mfma_f32_16x16x32_bf16 v[86:89], v[174:177], v[224:227], v[86:89]
	v_mfma_f32_16x16x32_bf16 v[66:69], v[166:169], v[232:235], v[66:69]
	v_mfma_f32_16x16x32_bf16 v[70:73], v[174:177], v[232:235], v[70:73]
	v_mfma_f32_16x16x32_bf16 v[122:125], v[178:181], v[204:207], 0
	v_mfma_f32_16x16x32_bf16 v[126:129], v[192:195], v[204:207], 0
	v_mfma_f32_16x16x32_bf16 v[106:109], v[178:181], v[212:215], 0
	v_mfma_f32_16x16x32_bf16 v[110:113], v[192:195], v[212:215], 0
	v_mfma_f32_16x16x32_bf16 v[90:93], v[178:181], v[220:223], 0
	v_mfma_f32_16x16x32_bf16 v[94:97], v[192:195], v[220:223], 0
	v_mfma_f32_16x16x32_bf16 v[74:77], v[178:181], v[228:231], 0
	v_mfma_f32_16x16x32_bf16 v[78:81], v[192:195], v[228:231], 0
	v_mfma_f32_16x16x32_bf16 v[122:125], v[182:185], v[208:211], v[122:125]
	v_mfma_f32_16x16x32_bf16 v[126:129], v[200:203], v[208:211], v[126:129]
	v_mfma_f32_16x16x32_bf16 v[106:109], v[182:185], v[216:219], v[106:109]
	v_mfma_f32_16x16x32_bf16 v[110:113], v[200:203], v[216:219], v[110:113]
	v_mfma_f32_16x16x32_bf16 v[90:93], v[182:185], v[224:227], v[90:93]
	v_mfma_f32_16x16x32_bf16 v[94:97], v[200:203], v[224:227], v[94:97]
	v_mfma_f32_16x16x32_bf16 v[74:77], v[182:185], v[232:235], v[74:77]
	v_mfma_f32_16x16x32_bf16 v[78:81], v[200:203], v[232:235], v[78:81]
	s_barrier
	s_add_i32 s81, s45, s35
	s_mov_b32 m0, s81
	ds_read_b128 v[204:207], v155 offset:16384
	ds_read_b128 v[208:211], v155 offset:17408
	ds_read_b128 v[212:215], v155 offset:18432
	ds_read_b128 v[216:219], v155 offset:19456
	ds_read_b128 v[220:223], v155 offset:20480
	ds_read_b128 v[224:227], v155 offset:21504
	ds_read_b128 v[228:231], v155 offset:22528
	ds_read_b128 v[232:235], v155 offset:23552
	global_load_lds_dwordx4 v132, s[64:65] sc1
	s_add_i32 m0, s81, 0x2000
	s_add_u32 s82, s64, 0x4000
	s_addc_u32 s83, s65, 0
	s_add_i32 s81, s47, s35
	global_load_lds_dwordx4 v136, s[64:65] sc1
	s_mov_b32 m0, s81
	s_nop 0
	global_load_lds_dwordx4 v132, s[82:83] sc1
	s_add_i32 m0, s81, 0x2000
	s_nop 0
	global_load_lds_dwordx4 v136, s[82:83] sc1
	s_mov_b32 m0, s37
	s_nop 0
	global_load_lds_dwordx4 v130, s[66:67] sc1
	s_mov_b32 m0, s39
	s_nop 0
	global_load_lds_dwordx4 v134, s[66:67] sc1
	s_waitcnt vmcnt(8)
	s_waitcnt lgkmcnt(0)
	s_barrier
	s_waitcnt lgkmcnt(0)
	v_mfma_f32_16x16x32_bf16 v[50:53], v[162:165], v[204:207], 0
	v_mfma_f32_16x16x32_bf16 v[54:57], v[170:173], v[204:207], 0
	v_mfma_f32_16x16x32_bf16 v[34:37], v[162:165], v[212:215], 0
	v_mfma_f32_16x16x32_bf16 v[38:41], v[170:173], v[212:215], 0
	v_mfma_f32_16x16x32_bf16 v[18:21], v[162:165], v[220:223], 0
	v_mfma_f32_16x16x32_bf16 v[22:25], v[170:173], v[220:223], 0
	v_mfma_f32_16x16x32_bf16 v[2:5], v[162:165], v[228:231], 0
	v_mfma_f32_16x16x32_bf16 v[6:9], v[170:173], v[228:231], 0
	v_mfma_f32_16x16x32_bf16 v[50:53], v[166:169], v[208:211], v[50:53]
	v_mfma_f32_16x16x32_bf16 v[54:57], v[174:177], v[208:211], v[54:57]
	v_mfma_f32_16x16x32_bf16 v[34:37], v[166:169], v[216:219], v[34:37]
	v_mfma_f32_16x16x32_bf16 v[38:41], v[174:177], v[216:219], v[38:41]
	v_mfma_f32_16x16x32_bf16 v[18:21], v[166:169], v[224:227], v[18:21]
	v_mfma_f32_16x16x32_bf16 v[22:25], v[174:177], v[224:227], v[22:25]
	v_mfma_f32_16x16x32_bf16 v[2:5], v[166:169], v[232:235], v[2:5]
	v_mfma_f32_16x16x32_bf16 v[6:9], v[174:177], v[232:235], v[6:9]
	v_mfma_f32_16x16x32_bf16 v[58:61], v[178:181], v[204:207], 0
	v_mfma_f32_16x16x32_bf16 v[62:65], v[192:195], v[204:207], 0
	v_mfma_f32_16x16x32_bf16 v[42:45], v[178:181], v[212:215], 0
	v_mfma_f32_16x16x32_bf16 v[46:49], v[192:195], v[212:215], 0
	v_mfma_f32_16x16x32_bf16 v[26:29], v[178:181], v[220:223], 0
	v_mfma_f32_16x16x32_bf16 v[30:33], v[192:195], v[220:223], 0
	v_mfma_f32_16x16x32_bf16 v[10:13], v[178:181], v[228:231], 0
	v_mfma_f32_16x16x32_bf16 v[14:17], v[192:195], v[228:231], 0
	v_mfma_f32_16x16x32_bf16 v[58:61], v[182:185], v[208:211], v[58:61]
	v_mfma_f32_16x16x32_bf16 v[62:65], v[200:203], v[208:211], v[62:65]
	v_mfma_f32_16x16x32_bf16 v[42:45], v[182:185], v[216:219], v[42:45]
	v_mfma_f32_16x16x32_bf16 v[46:49], v[200:203], v[216:219], v[46:49]
	v_mfma_f32_16x16x32_bf16 v[26:29], v[182:185], v[224:227], v[26:29]
	v_mfma_f32_16x16x32_bf16 v[30:33], v[200:203], v[224:227], v[30:33]
	v_mfma_f32_16x16x32_bf16 v[10:13], v[182:185], v[232:235], v[10:13]
	v_mfma_f32_16x16x32_bf16 v[14:17], v[200:203], v[232:235], v[14:17]
	s_barrier
	v_add_u32_e32 v157, s48, v153
	ds_read_b128 v[162:165], v157
	ds_read_b128 v[166:169], v157 offset:1024
	ds_read_b128 v[170:173], v157 offset:2048
	ds_read_b128 v[174:177], v157 offset:3072
	v_add_u32_e32 v157, s49, v153
	ds_read_b128 v[178:181], v157
	ds_read_b128 v[182:185], v157 offset:1024
	ds_read_b128 v[192:195], v157 offset:2048
	ds_read_b128 v[200:203], v157 offset:3072
	s_add_u32 s66, s66, 0x4000
	s_addc_u32 s67, s67, 0
	s_mov_b32 m0, s40
	ds_read_b128 v[204:207], v155 offset:32768
	ds_read_b128 v[208:211], v155 offset:33792
	ds_read_b128 v[212:215], v155 offset:34816
	ds_read_b128 v[216:219], v155 offset:35840
	ds_read_b128 v[220:223], v155 offset:36864
	ds_read_b128 v[224:227], v155 offset:37888
	ds_read_b128 v[228:231], v155 offset:38912
	ds_read_b128 v[232:235], v155 offset:39936
	global_load_lds_dwordx4 v130, s[66:67] sc1
	s_mov_b32 m0, s41
	s_nop 0
	global_load_lds_dwordx4 v134, s[66:67] sc1
	s_waitcnt vmcnt(8)
	s_waitcnt lgkmcnt(0)
	s_barrier
	s_waitcnt lgkmcnt(0)
	v_mfma_f32_16x16x32_bf16 v[114:117], v[162:165], v[204:207], v[114:117]
	v_mfma_f32_16x16x32_bf16 v[118:121], v[170:173], v[204:207], v[118:121]
	v_mfma_f32_16x16x32_bf16 v[98:101], v[162:165], v[212:215], v[98:101]
	v_mfma_f32_16x16x32_bf16 v[102:105], v[170:173], v[212:215], v[102:105]
	v_mfma_f32_16x16x32_bf16 v[82:85], v[162:165], v[220:223], v[82:85]
	v_mfma_f32_16x16x32_bf16 v[86:89], v[170:173], v[220:223], v[86:89]
	v_mfma_f32_16x16x32_bf16 v[66:69], v[162:165], v[228:231], v[66:69]
	v_mfma_f32_16x16x32_bf16 v[70:73], v[170:173], v[228:231], v[70:73]
	v_mfma_f32_16x16x32_bf16 v[114:117], v[166:169], v[208:211], v[114:117]
	v_mfma_f32_16x16x32_bf16 v[118:121], v[174:177], v[208:211], v[118:121]
	v_mfma_f32_16x16x32_bf16 v[98:101], v[166:169], v[216:219], v[98:101]
	v_mfma_f32_16x16x32_bf16 v[102:105], v[174:177], v[216:219], v[102:105]
	v_mfma_f32_16x16x32_bf16 v[82:85], v[166:169], v[224:227], v[82:85]
	v_mfma_f32_16x16x32_bf16 v[86:89], v[174:177], v[224:227], v[86:89]
	v_mfma_f32_16x16x32_bf16 v[66:69], v[166:169], v[232:235], v[66:69]
	v_mfma_f32_16x16x32_bf16 v[70:73], v[174:177], v[232:235], v[70:73]
	v_mfma_f32_16x16x32_bf16 v[122:125], v[178:181], v[204:207], v[122:125]
	v_mfma_f32_16x16x32_bf16 v[126:129], v[192:195], v[204:207], v[126:129]
	v_mfma_f32_16x16x32_bf16 v[106:109], v[178:181], v[212:215], v[106:109]
	v_mfma_f32_16x16x32_bf16 v[110:113], v[192:195], v[212:215], v[110:113]
	v_mfma_f32_16x16x32_bf16 v[90:93], v[178:181], v[220:223], v[90:93]
	v_mfma_f32_16x16x32_bf16 v[94:97], v[192:195], v[220:223], v[94:97]
	v_mfma_f32_16x16x32_bf16 v[74:77], v[178:181], v[228:231], v[74:77]
	v_mfma_f32_16x16x32_bf16 v[78:81], v[192:195], v[228:231], v[78:81]
	v_mfma_f32_16x16x32_bf16 v[122:125], v[182:185], v[208:211], v[122:125]
	v_mfma_f32_16x16x32_bf16 v[126:129], v[200:203], v[208:211], v[126:129]
	v_mfma_f32_16x16x32_bf16 v[106:109], v[182:185], v[216:219], v[106:109]
	v_mfma_f32_16x16x32_bf16 v[110:113], v[200:203], v[216:219], v[110:113]
	v_mfma_f32_16x16x32_bf16 v[90:93], v[182:185], v[224:227], v[90:93]
	v_mfma_f32_16x16x32_bf16 v[94:97], v[200:203], v[224:227], v[94:97]
	v_mfma_f32_16x16x32_bf16 v[74:77], v[182:185], v[232:235], v[74:77]
	v_mfma_f32_16x16x32_bf16 v[78:81], v[200:203], v[232:235], v[78:81]
	s_barrier
	s_add_u32 s66, s64, 0x8000
	s_addc_u32 s67, s65, 0
	s_add_i32 s81, s48, s35
	s_mov_b32 m0, s81
	ds_read_b128 v[204:207], v155 offset:49152
	ds_read_b128 v[208:211], v155 offset:50176
	ds_read_b128 v[212:215], v155 offset:51200
	ds_read_b128 v[216:219], v155 offset:52224
	ds_read_b128 v[220:223], v155 offset:53248
	ds_read_b128 v[224:227], v155 offset:54272
	ds_read_b128 v[228:231], v155 offset:55296
	ds_read_b128 v[232:235], v155 offset:56320
	global_load_lds_dwordx4 v132, s[66:67] sc1
	s_add_i32 m0, s81, 0x2000
	s_add_u32 s64, s64, 0xc000
	global_load_lds_dwordx4 v136, s[66:67] sc1
	s_addc_u32 s65, s65, 0
	s_add_i32 s66, s49, s35
	s_mov_b32 m0, s66
	s_nop 0
	global_load_lds_dwordx4 v132, s[64:65] sc1
	s_add_i32 m0, s66, 0x2000
	s_nop 0
	global_load_lds_dwordx4 v136, s[64:65] sc1
	s_mov_b32 m0, s43
	s_nop 0
	global_load_lds_dwordx4 v130, s[62:63] sc1
	s_mov_b32 m0, s44
	s_nop 0
	global_load_lds_dwordx4 v134, s[62:63] sc1
	s_waitcnt vmcnt(8)
	s_waitcnt lgkmcnt(0)
	s_barrier
	s_waitcnt lgkmcnt(0)
	v_mfma_f32_16x16x32_bf16 v[50:53], v[162:165], v[204:207], v[50:53]
	v_mfma_f32_16x16x32_bf16 v[54:57], v[170:173], v[204:207], v[54:57]
	v_mfma_f32_16x16x32_bf16 v[34:37], v[162:165], v[212:215], v[34:37]
	v_mfma_f32_16x16x32_bf16 v[38:41], v[170:173], v[212:215], v[38:41]
	v_mfma_f32_16x16x32_bf16 v[18:21], v[162:165], v[220:223], v[18:21]
	v_mfma_f32_16x16x32_bf16 v[22:25], v[170:173], v[220:223], v[22:25]
	v_mfma_f32_16x16x32_bf16 v[2:5], v[162:165], v[228:231], v[2:5]
	v_mfma_f32_16x16x32_bf16 v[6:9], v[170:173], v[228:231], v[6:9]
	v_mfma_f32_16x16x32_bf16 v[50:53], v[166:169], v[208:211], v[50:53]
	v_mfma_f32_16x16x32_bf16 v[54:57], v[174:177], v[208:211], v[54:57]
	v_mfma_f32_16x16x32_bf16 v[34:37], v[166:169], v[216:219], v[34:37]
	v_mfma_f32_16x16x32_bf16 v[38:41], v[174:177], v[216:219], v[38:41]
	v_mfma_f32_16x16x32_bf16 v[18:21], v[166:169], v[224:227], v[18:21]
	v_mfma_f32_16x16x32_bf16 v[22:25], v[174:177], v[224:227], v[22:25]
	v_mfma_f32_16x16x32_bf16 v[2:5], v[166:169], v[232:235], v[2:5]
	v_mfma_f32_16x16x32_bf16 v[6:9], v[174:177], v[232:235], v[6:9]
	v_mfma_f32_16x16x32_bf16 v[58:61], v[178:181], v[204:207], v[58:61]
	v_mfma_f32_16x16x32_bf16 v[62:65], v[192:195], v[204:207], v[62:65]
	v_mfma_f32_16x16x32_bf16 v[42:45], v[178:181], v[212:215], v[42:45]
	v_mfma_f32_16x16x32_bf16 v[46:49], v[192:195], v[212:215], v[46:49]
	v_mfma_f32_16x16x32_bf16 v[26:29], v[178:181], v[220:223], v[26:29]
	v_mfma_f32_16x16x32_bf16 v[30:33], v[192:195], v[220:223], v[30:33]
	v_mfma_f32_16x16x32_bf16 v[10:13], v[178:181], v[228:231], v[10:13]
	v_mfma_f32_16x16x32_bf16 v[14:17], v[192:195], v[228:231], v[14:17]
	v_mfma_f32_16x16x32_bf16 v[58:61], v[182:185], v[208:211], v[58:61]
	v_mfma_f32_16x16x32_bf16 v[62:65], v[200:203], v[208:211], v[62:65]
	v_mfma_f32_16x16x32_bf16 v[42:45], v[182:185], v[216:219], v[42:45]
	v_mfma_f32_16x16x32_bf16 v[46:49], v[200:203], v[216:219], v[46:49]
	v_mfma_f32_16x16x32_bf16 v[26:29], v[182:185], v[224:227], v[26:29]
	v_mfma_f32_16x16x32_bf16 v[30:33], v[200:203], v[224:227], v[30:33]
	v_mfma_f32_16x16x32_bf16 v[10:13], v[182:185], v[232:235], v[10:13]
	v_mfma_f32_16x16x32_bf16 v[14:17], v[200:203], v[232:235], v[14:17]
	s_barrier
	s_add_i32 s80, s80, 2
	s_add_u32 s8, s8, 0x10000
	s_addc_u32 s9, s9, 0
	s_cmp_gt_u32 s80, 41
.LBB0_404:
	s_add_u32 s29, s30, s8
	v_add_u32_e32 v157, s45, v153
	s_addc_u32 s55, s31, s9
	ds_read_b128 v[162:165], v157
	ds_read_b128 v[166:169], v157 offset:1024
	ds_read_b128 v[170:173], v157 offset:2048
	ds_read_b128 v[174:177], v157 offset:3072
	v_add_u32_e32 v157, s47, v153
	s_add_u32 s29, s29, 0x10000
	ds_read_b128 v[178:181], v157
	ds_read_b128 v[182:185], v157 offset:1024
	ds_read_b128 v[192:195], v157 offset:2048
	ds_read_b128 v[200:203], v157 offset:3072
	s_addc_u32 s55, s55, 0
	s_add_u32 s62, s61, s8
	s_addc_u32 s63, s69, s9
	s_cmp_eq_u32 s8, 0x150000
	s_cselect_b32 s66, s71, s29
	s_cselect_b32 s67, s70, s55
	s_cselect_b32 s64, s79, s62
	s_cselect_b32 s65, s78, s63
	s_add_u32 s62, s66, 0x8000
	s_addc_u32 s63, s67, 0
	s_add_i32 s29, s37, 0xc000
	v_lshl_add_u64 v[158:159], v[146:147], 0, s[8:9]
	s_mov_b32 m0, s29
	s_add_i32 s55, s37, 0xe000
	ds_read_b128 v[204:207], v155
	ds_read_b128 v[208:211], v155 offset:1024
	ds_read_b128 v[212:215], v155 offset:2048
	ds_read_b128 v[216:219], v155 offset:3072
	ds_read_b128 v[220:223], v155 offset:4096
	ds_read_b128 v[224:227], v155 offset:5120
	ds_read_b128 v[228:231], v155 offset:6144
	ds_read_b128 v[232:235], v155 offset:7168
	global_load_lds_dwordx4 v[158:159], off sc1
	v_lshl_add_u64 v[158:159], v[148:149], 0, s[8:9]
	s_mov_b32 m0, s55
	s_nop 0
	global_load_lds_dwordx4 v[158:159], off sc1
	s_waitcnt vmcnt(8)
	s_waitcnt lgkmcnt(0)
	s_barrier
	s_waitcnt lgkmcnt(0)
	v_mfma_f32_16x16x32_bf16 v[114:117], v[162:165], v[204:207], v[114:117]
	v_mfma_f32_16x16x32_bf16 v[118:121], v[170:173], v[204:207], v[118:121]
	v_mfma_f32_16x16x32_bf16 v[98:101], v[162:165], v[212:215], v[98:101]
	v_mfma_f32_16x16x32_bf16 v[102:105], v[170:173], v[212:215], v[102:105]
	v_mfma_f32_16x16x32_bf16 v[82:85], v[162:165], v[220:223], v[82:85]
	v_mfma_f32_16x16x32_bf16 v[86:89], v[170:173], v[220:223], v[86:89]
	v_mfma_f32_16x16x32_bf16 v[66:69], v[162:165], v[228:231], v[66:69]
	v_mfma_f32_16x16x32_bf16 v[70:73], v[170:173], v[228:231], v[70:73]
	v_mfma_f32_16x16x32_bf16 v[114:117], v[166:169], v[208:211], v[114:117]
	v_mfma_f32_16x16x32_bf16 v[118:121], v[174:177], v[208:211], v[118:121]
	v_mfma_f32_16x16x32_bf16 v[98:101], v[166:169], v[216:219], v[98:101]
	v_mfma_f32_16x16x32_bf16 v[102:105], v[174:177], v[216:219], v[102:105]
	v_mfma_f32_16x16x32_bf16 v[82:85], v[166:169], v[224:227], v[82:85]
	v_mfma_f32_16x16x32_bf16 v[86:89], v[174:177], v[224:227], v[86:89]
	v_mfma_f32_16x16x32_bf16 v[66:69], v[166:169], v[232:235], v[66:69]
	v_mfma_f32_16x16x32_bf16 v[70:73], v[174:177], v[232:235], v[70:73]
	v_mfma_f32_16x16x32_bf16 v[122:125], v[178:181], v[204:207], v[122:125]
	v_mfma_f32_16x16x32_bf16 v[126:129], v[192:195], v[204:207], v[126:129]
	v_mfma_f32_16x16x32_bf16 v[106:109], v[178:181], v[212:215], v[106:109]
	v_mfma_f32_16x16x32_bf16 v[110:113], v[192:195], v[212:215], v[110:113]
	v_mfma_f32_16x16x32_bf16 v[90:93], v[178:181], v[220:223], v[90:93]
	v_mfma_f32_16x16x32_bf16 v[94:97], v[192:195], v[220:223], v[94:97]
	v_mfma_f32_16x16x32_bf16 v[74:77], v[178:181], v[228:231], v[74:77]
	v_mfma_f32_16x16x32_bf16 v[78:81], v[192:195], v[228:231], v[78:81]
	v_mfma_f32_16x16x32_bf16 v[122:125], v[182:185], v[208:211], v[122:125]
	v_mfma_f32_16x16x32_bf16 v[126:129], v[200:203], v[208:211], v[126:129]
	v_mfma_f32_16x16x32_bf16 v[106:109], v[182:185], v[216:219], v[106:109]
	v_mfma_f32_16x16x32_bf16 v[110:113], v[200:203], v[216:219], v[110:113]
	v_mfma_f32_16x16x32_bf16 v[90:93], v[182:185], v[224:227], v[90:93]
	v_mfma_f32_16x16x32_bf16 v[94:97], v[200:203], v[224:227], v[94:97]
	v_mfma_f32_16x16x32_bf16 v[74:77], v[182:185], v[232:235], v[74:77]
	v_mfma_f32_16x16x32_bf16 v[78:81], v[200:203], v[232:235], v[78:81]
	s_barrier
	s_add_i32 s81, s45, s35
	s_mov_b32 m0, s81
	ds_read_b128 v[204:207], v155 offset:16384
	ds_read_b128 v[208:211], v155 offset:17408
	ds_read_b128 v[212:215], v155 offset:18432
	ds_read_b128 v[216:219], v155 offset:19456
	ds_read_b128 v[220:223], v155 offset:20480
	ds_read_b128 v[224:227], v155 offset:21504
	ds_read_b128 v[228:231], v155 offset:22528
	ds_read_b128 v[232:235], v155 offset:23552
	global_load_lds_dwordx4 v132, s[64:65] sc1
	s_add_i32 m0, s81, 0x2000
	s_add_u32 s82, s64, 0x4000
	s_addc_u32 s83, s65, 0
	s_add_i32 s81, s47, s35
	global_load_lds_dwordx4 v136, s[64:65] sc1
	s_mov_b32 m0, s81
	s_nop 0
	global_load_lds_dwordx4 v132, s[82:83] sc1
	s_add_i32 m0, s81, 0x2000
	s_nop 0
	global_load_lds_dwordx4 v136, s[82:83] sc1
	s_mov_b32 m0, s37
	s_nop 0
	global_load_lds_dwordx4 v130, s[66:67] sc1
	s_mov_b32 m0, s39
	s_nop 0
	global_load_lds_dwordx4 v134, s[66:67] sc1
	s_waitcnt vmcnt(8)
	s_waitcnt lgkmcnt(0)
	s_barrier
	s_waitcnt lgkmcnt(0)
	v_mfma_f32_16x16x32_bf16 v[50:53], v[162:165], v[204:207], v[50:53]
	v_mfma_f32_16x16x32_bf16 v[54:57], v[170:173], v[204:207], v[54:57]
	v_mfma_f32_16x16x32_bf16 v[34:37], v[162:165], v[212:215], v[34:37]
	v_mfma_f32_16x16x32_bf16 v[38:41], v[170:173], v[212:215], v[38:41]
	v_mfma_f32_16x16x32_bf16 v[18:21], v[162:165], v[220:223], v[18:21]
	v_mfma_f32_16x16x32_bf16 v[22:25], v[170:173], v[220:223], v[22:25]
	v_mfma_f32_16x16x32_bf16 v[2:5], v[162:165], v[228:231], v[2:5]
	v_mfma_f32_16x16x32_bf16 v[6:9], v[170:173], v[228:231], v[6:9]
	v_mfma_f32_16x16x32_bf16 v[50:53], v[166:169], v[208:211], v[50:53]
	v_mfma_f32_16x16x32_bf16 v[54:57], v[174:177], v[208:211], v[54:57]
	v_mfma_f32_16x16x32_bf16 v[34:37], v[166:169], v[216:219], v[34:37]
	v_mfma_f32_16x16x32_bf16 v[38:41], v[174:177], v[216:219], v[38:41]
	v_mfma_f32_16x16x32_bf16 v[18:21], v[166:169], v[224:227], v[18:21]
	v_mfma_f32_16x16x32_bf16 v[22:25], v[174:177], v[224:227], v[22:25]
	v_mfma_f32_16x16x32_bf16 v[2:5], v[166:169], v[232:235], v[2:5]
	v_mfma_f32_16x16x32_bf16 v[6:9], v[174:177], v[232:235], v[6:9]
	v_mfma_f32_16x16x32_bf16 v[58:61], v[178:181], v[204:207], v[58:61]
	v_mfma_f32_16x16x32_bf16 v[62:65], v[192:195], v[204:207], v[62:65]
	v_mfma_f32_16x16x32_bf16 v[42:45], v[178:181], v[212:215], v[42:45]
	v_mfma_f32_16x16x32_bf16 v[46:49], v[192:195], v[212:215], v[46:49]
	v_mfma_f32_16x16x32_bf16 v[26:29], v[178:181], v[220:223], v[26:29]
	v_mfma_f32_16x16x32_bf16 v[30:33], v[192:195], v[220:223], v[30:33]
	v_mfma_f32_16x16x32_bf16 v[10:13], v[178:181], v[228:231], v[10:13]
	v_mfma_f32_16x16x32_bf16 v[14:17], v[192:195], v[228:231], v[14:17]
	v_mfma_f32_16x16x32_bf16 v[58:61], v[182:185], v[208:211], v[58:61]
	v_mfma_f32_16x16x32_bf16 v[62:65], v[200:203], v[208:211], v[62:65]
	v_mfma_f32_16x16x32_bf16 v[42:45], v[182:185], v[216:219], v[42:45]
	v_mfma_f32_16x16x32_bf16 v[46:49], v[200:203], v[216:219], v[46:49]
	v_mfma_f32_16x16x32_bf16 v[26:29], v[182:185], v[224:227], v[26:29]
	v_mfma_f32_16x16x32_bf16 v[30:33], v[200:203], v[224:227], v[30:33]
	v_mfma_f32_16x16x32_bf16 v[10:13], v[182:185], v[232:235], v[10:13]
	v_mfma_f32_16x16x32_bf16 v[14:17], v[200:203], v[232:235], v[14:17]
	s_barrier
	v_add_u32_e32 v157, s48, v153
	ds_read_b128 v[162:165], v157
	ds_read_b128 v[166:169], v157 offset:1024
	ds_read_b128 v[170:173], v157 offset:2048
	ds_read_b128 v[174:177], v157 offset:3072
	v_add_u32_e32 v157, s49, v153
	ds_read_b128 v[178:181], v157
	ds_read_b128 v[182:185], v157 offset:1024
	ds_read_b128 v[192:195], v157 offset:2048
	ds_read_b128 v[200:203], v157 offset:3072
	s_add_u32 s66, s66, 0x4000
	s_addc_u32 s67, s67, 0
	s_mov_b32 m0, s40
	ds_read_b128 v[204:207], v155 offset:32768
	ds_read_b128 v[208:211], v155 offset:33792
	ds_read_b128 v[212:215], v155 offset:34816
	ds_read_b128 v[216:219], v155 offset:35840
	ds_read_b128 v[220:223], v155 offset:36864
	ds_read_b128 v[224:227], v155 offset:37888
	ds_read_b128 v[228:231], v155 offset:38912
	ds_read_b128 v[232:235], v155 offset:39936
	global_load_lds_dwordx4 v130, s[66:67] sc1
	s_mov_b32 m0, s41
	s_nop 0
	global_load_lds_dwordx4 v134, s[66:67] sc1
	s_waitcnt vmcnt(8)
	s_waitcnt lgkmcnt(0)
	s_barrier
	s_waitcnt lgkmcnt(0)
	v_mfma_f32_16x16x32_bf16 v[114:117], v[162:165], v[204:207], v[114:117]
	v_mfma_f32_16x16x32_bf16 v[118:121], v[170:173], v[204:207], v[118:121]
	v_mfma_f32_16x16x32_bf16 v[98:101], v[162:165], v[212:215], v[98:101]
	v_mfma_f32_16x16x32_bf16 v[102:105], v[170:173], v[212:215], v[102:105]
	v_mfma_f32_16x16x32_bf16 v[82:85], v[162:165], v[220:223], v[82:85]
	v_mfma_f32_16x16x32_bf16 v[86:89], v[170:173], v[220:223], v[86:89]
	v_mfma_f32_16x16x32_bf16 v[66:69], v[162:165], v[228:231], v[66:69]
	v_mfma_f32_16x16x32_bf16 v[70:73], v[170:173], v[228:231], v[70:73]
	v_mfma_f32_16x16x32_bf16 v[114:117], v[166:169], v[208:211], v[114:117]
	v_mfma_f32_16x16x32_bf16 v[118:121], v[174:177], v[208:211], v[118:121]
	v_mfma_f32_16x16x32_bf16 v[98:101], v[166:169], v[216:219], v[98:101]
	v_mfma_f32_16x16x32_bf16 v[102:105], v[174:177], v[216:219], v[102:105]
	v_mfma_f32_16x16x32_bf16 v[82:85], v[166:169], v[224:227], v[82:85]
	v_mfma_f32_16x16x32_bf16 v[86:89], v[174:177], v[224:227], v[86:89]
	v_mfma_f32_16x16x32_bf16 v[66:69], v[166:169], v[232:235], v[66:69]
	v_mfma_f32_16x16x32_bf16 v[70:73], v[174:177], v[232:235], v[70:73]
	v_mfma_f32_16x16x32_bf16 v[122:125], v[178:181], v[204:207], v[122:125]
	v_mfma_f32_16x16x32_bf16 v[126:129], v[192:195], v[204:207], v[126:129]
	v_mfma_f32_16x16x32_bf16 v[106:109], v[178:181], v[212:215], v[106:109]
	v_mfma_f32_16x16x32_bf16 v[110:113], v[192:195], v[212:215], v[110:113]
	v_mfma_f32_16x16x32_bf16 v[90:93], v[178:181], v[220:223], v[90:93]
	v_mfma_f32_16x16x32_bf16 v[94:97], v[192:195], v[220:223], v[94:97]
	v_mfma_f32_16x16x32_bf16 v[74:77], v[178:181], v[228:231], v[74:77]
	v_mfma_f32_16x16x32_bf16 v[78:81], v[192:195], v[228:231], v[78:81]
	v_mfma_f32_16x16x32_bf16 v[122:125], v[182:185], v[208:211], v[122:125]
	v_mfma_f32_16x16x32_bf16 v[126:129], v[200:203], v[208:211], v[126:129]
	v_mfma_f32_16x16x32_bf16 v[106:109], v[182:185], v[216:219], v[106:109]
	v_mfma_f32_16x16x32_bf16 v[110:113], v[200:203], v[216:219], v[110:113]
	v_mfma_f32_16x16x32_bf16 v[90:93], v[182:185], v[224:227], v[90:93]
	v_mfma_f32_16x16x32_bf16 v[94:97], v[200:203], v[224:227], v[94:97]
	v_mfma_f32_16x16x32_bf16 v[74:77], v[182:185], v[232:235], v[74:77]
	v_mfma_f32_16x16x32_bf16 v[78:81], v[200:203], v[232:235], v[78:81]
	s_barrier
	s_add_u32 s66, s64, 0x8000
	s_addc_u32 s67, s65, 0
	s_add_i32 s81, s48, s35
	s_mov_b32 m0, s81
	ds_read_b128 v[204:207], v155 offset:49152
	ds_read_b128 v[208:211], v155 offset:50176
	ds_read_b128 v[212:215], v155 offset:51200
	ds_read_b128 v[216:219], v155 offset:52224
	ds_read_b128 v[220:223], v155 offset:53248
	ds_read_b128 v[224:227], v155 offset:54272
	ds_read_b128 v[228:231], v155 offset:55296
	ds_read_b128 v[232:235], v155 offset:56320
	global_load_lds_dwordx4 v132, s[66:67] sc1
	s_add_i32 m0, s81, 0x2000
	s_add_u32 s64, s64, 0xc000
	global_load_lds_dwordx4 v136, s[66:67] sc1
	s_addc_u32 s65, s65, 0
	s_add_i32 s66, s49, s35
	s_mov_b32 m0, s66
	s_nop 0
	global_load_lds_dwordx4 v132, s[64:65] sc1
	s_add_i32 m0, s66, 0x2000
	s_nop 0
	global_load_lds_dwordx4 v136, s[64:65] sc1
	s_mov_b32 m0, s43
	s_nop 0
	global_load_lds_dwordx4 v130, s[62:63] sc1
	s_mov_b32 m0, s44
	s_nop 0
	global_load_lds_dwordx4 v134, s[62:63] sc1
	s_waitcnt vmcnt(8)
	s_waitcnt lgkmcnt(0)
	s_barrier
	s_waitcnt lgkmcnt(0)
	v_mfma_f32_16x16x32_bf16 v[50:53], v[162:165], v[204:207], v[50:53]
	v_mfma_f32_16x16x32_bf16 v[54:57], v[170:173], v[204:207], v[54:57]
	v_mfma_f32_16x16x32_bf16 v[34:37], v[162:165], v[212:215], v[34:37]
	v_mfma_f32_16x16x32_bf16 v[38:41], v[170:173], v[212:215], v[38:41]
	v_mfma_f32_16x16x32_bf16 v[18:21], v[162:165], v[220:223], v[18:21]
	v_mfma_f32_16x16x32_bf16 v[22:25], v[170:173], v[220:223], v[22:25]
	v_mfma_f32_16x16x32_bf16 v[2:5], v[162:165], v[228:231], v[2:5]
	v_mfma_f32_16x16x32_bf16 v[6:9], v[170:173], v[228:231], v[6:9]
	v_mfma_f32_16x16x32_bf16 v[50:53], v[166:169], v[208:211], v[50:53]
	v_mfma_f32_16x16x32_bf16 v[54:57], v[174:177], v[208:211], v[54:57]
	v_mfma_f32_16x16x32_bf16 v[34:37], v[166:169], v[216:219], v[34:37]
	v_mfma_f32_16x16x32_bf16 v[38:41], v[174:177], v[216:219], v[38:41]
	v_mfma_f32_16x16x32_bf16 v[18:21], v[166:169], v[224:227], v[18:21]
	v_mfma_f32_16x16x32_bf16 v[22:25], v[174:177], v[224:227], v[22:25]
	v_mfma_f32_16x16x32_bf16 v[2:5], v[166:169], v[232:235], v[2:5]
	v_mfma_f32_16x16x32_bf16 v[6:9], v[174:177], v[232:235], v[6:9]
	v_mfma_f32_16x16x32_bf16 v[58:61], v[178:181], v[204:207], v[58:61]
	v_mfma_f32_16x16x32_bf16 v[62:65], v[192:195], v[204:207], v[62:65]
	v_mfma_f32_16x16x32_bf16 v[42:45], v[178:181], v[212:215], v[42:45]
	v_mfma_f32_16x16x32_bf16 v[46:49], v[192:195], v[212:215], v[46:49]
	v_mfma_f32_16x16x32_bf16 v[26:29], v[178:181], v[220:223], v[26:29]
	v_mfma_f32_16x16x32_bf16 v[30:33], v[192:195], v[220:223], v[30:33]
	v_mfma_f32_16x16x32_bf16 v[10:13], v[178:181], v[228:231], v[10:13]
	v_mfma_f32_16x16x32_bf16 v[14:17], v[192:195], v[228:231], v[14:17]
	v_mfma_f32_16x16x32_bf16 v[58:61], v[182:185], v[208:211], v[58:61]
	v_mfma_f32_16x16x32_bf16 v[62:65], v[200:203], v[208:211], v[62:65]
	v_mfma_f32_16x16x32_bf16 v[42:45], v[182:185], v[216:219], v[42:45]
	v_mfma_f32_16x16x32_bf16 v[46:49], v[200:203], v[216:219], v[46:49]
	v_mfma_f32_16x16x32_bf16 v[26:29], v[182:185], v[224:227], v[26:29]
	v_mfma_f32_16x16x32_bf16 v[30:33], v[200:203], v[224:227], v[30:33]
	v_mfma_f32_16x16x32_bf16 v[10:13], v[182:185], v[232:235], v[10:13]
	v_mfma_f32_16x16x32_bf16 v[14:17], v[200:203], v[232:235], v[14:17]
	s_barrier
	s_add_i32 s80, s80, 2
	s_add_u32 s8, s8, 0x10000
	s_addc_u32 s9, s9, 0
	s_cmp_gt_u32 s80, 41
	s_cbranch_scc0 .LBB0_404
	s_add_u32 s8, s61, 0xffff0000
	s_addc_u32 s9, s69, -1
	s_and_b64 vcc, exec, s[6:7]
	s_cbranch_vccnz .LBB0_391
	s_mov_b32 s10, s50
	s_mov_b32 s28, s51
	s_mov_b64 s[30:31], s[56:57]
	s_mov_b32 s46, s54
	s_andn2_b64 vcc, exec, s[4:5]
	s_cbranch_vccnz .LBB0_392

.LBB0_459:
	s_mov_b32 s40, s38
	s_add_i32 s38, s38, 1
	s_cmp_lt_u32 s38, s7
	s_mov_b32 s35, s39
	s_cselect_b64 s[42:43], -1, 0
	s_add_i32 s39, s38, s6
	s_sub_i32 s98, s39, 11
	s_cmp_lt_u32 s98, 3
	s_cselect_b32 s99, 7, 0
	s_sub_i32 s98, s39, 18
	s_cmp_lt_u32 s98, 3
	s_cselect_b32 s98, 0xfffffff9, 0
	s_add_i32 s99, s99, s98
	s_cmp_eq_u32 s39, 6
	s_cselect_b32 s98, 11, 0
	s_add_i32 s99, s99, s98
	s_cmp_eq_u32 s39, 17
	s_cselect_b32 s98, 0xfffffff5, 0
	s_add_i32 s99, s99, s98
	s_add_i32 s39, s39, s99
	s_and_b64 s[44:45], s[42:43], exec
	s_cselect_b32 s46, s58, s58
	s_cselect_b32 s44, s39, s35
	s_ashr_i32 s47, s46, 31
	s_lshl_b64 s[46:47], s[46:47], 19
	s_mov_b64 s[4:5], s[82:83]
	s_add_u32 s82, s60, s46
	s_addc_u32 s83, s33, s47
	s_and_b64 s[46:47], s[42:43], exec
	s_cselect_b32 s35, s83, s5
	s_cselect_b32 s41, s82, s4
	s_ashr_i32 s45, s44, 31
	s_lshl_b64 s[44:45], s[44:45], 19
	v_readlane_b32 s12, v253, 61
	s_mov_b64 s[8:9], s[62:63]
	v_readlane_b32 s13, v253, 62
	s_add_u32 s62, s12, s44
	s_addc_u32 s63, s13, s45
	s_and_b64 s[42:43], s[42:43], exec
	s_cselect_b32 s42, s63, s9
	s_cselect_b32 s43, s62, s8
	s_add_u32 s44, s8, 0x10000
	s_addc_u32 s45, s9, 0
	s_mov_b32 s46, -2
	v_add_u32_e32 v134, s95, v1
	ds_read_b128 v[130:133], v134
	ds_read_b128 v[136:139], v134 offset:1024
	ds_read_b128 v[140:143], v134 offset:2048
	ds_read_b128 v[144:147], v134 offset:3072
	v_add_u32_e32 v134, s93, v1
	ds_read_b128 v[170:173], v134
	ds_read_b128 v[200:203], v134 offset:1024
	ds_read_b128 v[204:207], v134 offset:2048
	ds_read_b128 v[208:211], v134 offset:3072
	s_add_u32 s8, s4, 0x10000
	s_addc_u32 s9, s5, 0
	s_cmp_eq_u32 s46, 12
	s_cselect_b32 s84, s41, s8
	s_cselect_b32 s85, s35, s9
	s_cselect_b32 s64, s43, s44
	s_cselect_b32 s65, s42, s45
	s_add_u32 s56, s84, 0x8000
	s_addc_u32 s57, s85, 0
	s_add_i32 m0, s69, 0xc000
	ds_read_b128 v[212:215], v194
	ds_read_b128 v[216:219], v194 offset:1024
	ds_read_b128 v[220:223], v194 offset:2048
	ds_read_b128 v[224:227], v194 offset:3072
	ds_read_b128 v[228:231], v194 offset:4096
	ds_read_b128 v[232:235], v194 offset:5120
	ds_read_b128 v[236:239], v194 offset:6144
	ds_read_b128 v[240:243], v194 offset:7168
	global_load_lds_dwordx4 v166, s[4:5] sc1
	s_add_i32 m0, s69, 0xe000
	s_nop 0
	global_load_lds_dwordx4 v168, s[4:5] sc1
	s_waitcnt vmcnt(8)
	s_waitcnt lgkmcnt(0)
	s_barrier
	s_waitcnt lgkmcnt(0)
	v_mfma_f32_16x16x32_bf16 v[122:125], v[130:133], v[212:215], 0
	v_mfma_f32_16x16x32_bf16 v[126:129], v[140:143], v[212:215], 0
	v_mfma_f32_16x16x32_bf16 v[106:109], v[130:133], v[220:223], 0
	v_mfma_f32_16x16x32_bf16 v[110:113], v[140:143], v[220:223], 0
	v_mfma_f32_16x16x32_bf16 v[90:93], v[130:133], v[228:231], 0
	v_mfma_f32_16x16x32_bf16 v[94:97], v[140:143], v[228:231], 0
	v_mfma_f32_16x16x32_bf16 v[74:77], v[130:133], v[236:239], 0
	v_mfma_f32_16x16x32_bf16 v[78:81], v[140:143], v[236:239], 0
	v_mfma_f32_16x16x32_bf16 v[122:125], v[136:139], v[216:219], v[122:125]
	v_mfma_f32_16x16x32_bf16 v[126:129], v[144:147], v[216:219], v[126:129]
	v_mfma_f32_16x16x32_bf16 v[106:109], v[136:139], v[224:227], v[106:109]
	v_mfma_f32_16x16x32_bf16 v[110:113], v[144:147], v[224:227], v[110:113]
	v_mfma_f32_16x16x32_bf16 v[90:93], v[136:139], v[232:235], v[90:93]
	v_mfma_f32_16x16x32_bf16 v[94:97], v[144:147], v[232:235], v[94:97]
	v_mfma_f32_16x16x32_bf16 v[74:77], v[136:139], v[240:243], v[74:77]
	v_mfma_f32_16x16x32_bf16 v[78:81], v[144:147], v[240:243], v[78:81]
	v_mfma_f32_16x16x32_bf16 v[114:117], v[170:173], v[212:215], 0
	v_mfma_f32_16x16x32_bf16 v[118:121], v[204:207], v[212:215], 0
	v_mfma_f32_16x16x32_bf16 v[98:101], v[170:173], v[220:223], 0
	v_mfma_f32_16x16x32_bf16 v[102:105], v[204:207], v[220:223], 0
	v_mfma_f32_16x16x32_bf16 v[82:85], v[170:173], v[228:231], 0
	v_mfma_f32_16x16x32_bf16 v[86:89], v[204:207], v[228:231], 0
	v_mfma_f32_16x16x32_bf16 v[66:69], v[170:173], v[236:239], 0
	v_mfma_f32_16x16x32_bf16 v[70:73], v[204:207], v[236:239], 0
	v_mfma_f32_16x16x32_bf16 v[114:117], v[200:203], v[216:219], v[114:117]
	v_mfma_f32_16x16x32_bf16 v[118:121], v[208:211], v[216:219], v[118:121]
	v_mfma_f32_16x16x32_bf16 v[98:101], v[200:203], v[224:227], v[98:101]
	v_mfma_f32_16x16x32_bf16 v[102:105], v[208:211], v[224:227], v[102:105]
	v_mfma_f32_16x16x32_bf16 v[82:85], v[200:203], v[232:235], v[82:85]
	v_mfma_f32_16x16x32_bf16 v[86:89], v[208:211], v[232:235], v[86:89]
	v_mfma_f32_16x16x32_bf16 v[66:69], v[200:203], v[240:243], v[66:69]
	v_mfma_f32_16x16x32_bf16 v[70:73], v[208:211], v[240:243], v[70:73]
	s_barrier
	s_add_i32 s4, s95, s61
	s_mov_b32 m0, s4
	ds_read_b128 v[212:215], v194 offset:16384
	ds_read_b128 v[216:219], v194 offset:17408
	ds_read_b128 v[220:223], v194 offset:18432
	ds_read_b128 v[224:227], v194 offset:19456
	ds_read_b128 v[228:231], v194 offset:20480
	ds_read_b128 v[232:235], v194 offset:21504
	ds_read_b128 v[236:239], v194 offset:22528
	ds_read_b128 v[240:243], v194 offset:23552
	global_load_lds_dwordx4 v152, s[64:65] sc1
	s_add_i32 m0, s4, 0x2000
	s_add_u32 s4, s64, 0x4000
	s_addc_u32 s5, s65, 0
	s_add_i32 s47, s93, s61
	global_load_lds_dwordx4 v154, s[64:65] sc1
	s_mov_b32 m0, s47
	s_nop 0
	global_load_lds_dwordx4 v152, s[4:5] sc1
	s_add_i32 m0, s47, 0x2000
	s_nop 0
	global_load_lds_dwordx4 v154, s[4:5] sc1
	s_mov_b32 m0, s69
	s_nop 0
	global_load_lds_dwordx4 v150, s[84:85] sc1
	s_mov_b32 m0, s77
	s_nop 0
	global_load_lds_dwordx4 v148, s[84:85] sc1
	s_waitcnt vmcnt(8)
	s_waitcnt lgkmcnt(0)
	s_barrier
	s_waitcnt lgkmcnt(0)
	v_mfma_f32_16x16x32_bf16 v[58:61], v[130:133], v[212:215], 0
	v_mfma_f32_16x16x32_bf16 v[62:65], v[140:143], v[212:215], 0
	v_mfma_f32_16x16x32_bf16 v[42:45], v[130:133], v[220:223], 0
	v_mfma_f32_16x16x32_bf16 v[46:49], v[140:143], v[220:223], 0
	v_mfma_f32_16x16x32_bf16 v[26:29], v[130:133], v[228:231], 0
	v_mfma_f32_16x16x32_bf16 v[30:33], v[140:143], v[228:231], 0
	v_mfma_f32_16x16x32_bf16 v[10:13], v[130:133], v[236:239], 0
	v_mfma_f32_16x16x32_bf16 v[14:17], v[140:143], v[236:239], 0
	v_mfma_f32_16x16x32_bf16 v[58:61], v[136:139], v[216:219], v[58:61]
	v_mfma_f32_16x16x32_bf16 v[62:65], v[144:147], v[216:219], v[62:65]
	v_mfma_f32_16x16x32_bf16 v[42:45], v[136:139], v[224:227], v[42:45]
	v_mfma_f32_16x16x32_bf16 v[46:49], v[144:147], v[224:227], v[46:49]
	v_mfma_f32_16x16x32_bf16 v[26:29], v[136:139], v[232:235], v[26:29]
	v_mfma_f32_16x16x32_bf16 v[30:33], v[144:147], v[232:235], v[30:33]
	v_mfma_f32_16x16x32_bf16 v[10:13], v[136:139], v[240:243], v[10:13]
	v_mfma_f32_16x16x32_bf16 v[14:17], v[144:147], v[240:243], v[14:17]
	v_mfma_f32_16x16x32_bf16 v[50:53], v[170:173], v[212:215], 0
	v_mfma_f32_16x16x32_bf16 v[54:57], v[204:207], v[212:215], 0
	v_mfma_f32_16x16x32_bf16 v[34:37], v[170:173], v[220:223], 0
	v_mfma_f32_16x16x32_bf16 v[38:41], v[204:207], v[220:223], 0
	v_mfma_f32_16x16x32_bf16 v[18:21], v[170:173], v[228:231], 0
	v_mfma_f32_16x16x32_bf16 v[22:25], v[204:207], v[228:231], 0
	v_mfma_f32_16x16x32_bf16 v[2:5], v[170:173], v[236:239], 0
	v_mfma_f32_16x16x32_bf16 v[6:9], v[204:207], v[236:239], 0
	v_mfma_f32_16x16x32_bf16 v[50:53], v[200:203], v[216:219], v[50:53]
	v_mfma_f32_16x16x32_bf16 v[54:57], v[208:211], v[216:219], v[54:57]
	v_mfma_f32_16x16x32_bf16 v[34:37], v[200:203], v[224:227], v[34:37]
	v_mfma_f32_16x16x32_bf16 v[38:41], v[208:211], v[224:227], v[38:41]
	v_mfma_f32_16x16x32_bf16 v[18:21], v[200:203], v[232:235], v[18:21]
	v_mfma_f32_16x16x32_bf16 v[22:25], v[208:211], v[232:235], v[22:25]
	v_mfma_f32_16x16x32_bf16 v[2:5], v[200:203], v[240:243], v[2:5]
	v_mfma_f32_16x16x32_bf16 v[6:9], v[208:211], v[240:243], v[6:9]
	s_barrier
	v_add_u32_e32 v134, s36, v1
	ds_read_b128 v[130:133], v134
	ds_read_b128 v[136:139], v134 offset:1024
	ds_read_b128 v[140:143], v134 offset:2048
	ds_read_b128 v[144:147], v134 offset:3072
	v_add_u32_e32 v134, s37, v1
	ds_read_b128 v[170:173], v134
	ds_read_b128 v[200:203], v134 offset:1024
	ds_read_b128 v[204:207], v134 offset:2048
	ds_read_b128 v[208:211], v134 offset:3072
	s_add_u32 s4, s84, 0x4000
	s_addc_u32 s5, s85, 0
	s_mov_b32 m0, s86
	ds_read_b128 v[212:215], v194 offset:32768
	ds_read_b128 v[216:219], v194 offset:33792
	ds_read_b128 v[220:223], v194 offset:34816
	ds_read_b128 v[224:227], v194 offset:35840
	ds_read_b128 v[228:231], v194 offset:36864
	ds_read_b128 v[232:235], v194 offset:37888
	ds_read_b128 v[236:239], v194 offset:38912
	ds_read_b128 v[240:243], v194 offset:39936
	global_load_lds_dwordx4 v150, s[4:5] sc1
	s_mov_b32 m0, s87
	s_nop 0
	global_load_lds_dwordx4 v148, s[4:5] sc1
	s_waitcnt vmcnt(8)
	s_waitcnt lgkmcnt(0)
	s_barrier
	s_waitcnt lgkmcnt(0)
	v_mfma_f32_16x16x32_bf16 v[122:125], v[130:133], v[212:215], v[122:125]
	v_mfma_f32_16x16x32_bf16 v[126:129], v[140:143], v[212:215], v[126:129]
	v_mfma_f32_16x16x32_bf16 v[106:109], v[130:133], v[220:223], v[106:109]
	v_mfma_f32_16x16x32_bf16 v[110:113], v[140:143], v[220:223], v[110:113]
	v_mfma_f32_16x16x32_bf16 v[90:93], v[130:133], v[228:231], v[90:93]
	v_mfma_f32_16x16x32_bf16 v[94:97], v[140:143], v[228:231], v[94:97]
	v_mfma_f32_16x16x32_bf16 v[74:77], v[130:133], v[236:239], v[74:77]
	v_mfma_f32_16x16x32_bf16 v[78:81], v[140:143], v[236:239], v[78:81]
	v_mfma_f32_16x16x32_bf16 v[122:125], v[136:139], v[216:219], v[122:125]
	v_mfma_f32_16x16x32_bf16 v[126:129], v[144:147], v[216:219], v[126:129]
	v_mfma_f32_16x16x32_bf16 v[106:109], v[136:139], v[224:227], v[106:109]
	v_mfma_f32_16x16x32_bf16 v[110:113], v[144:147], v[224:227], v[110:113]
	v_mfma_f32_16x16x32_bf16 v[90:93], v[136:139], v[232:235], v[90:93]
	v_mfma_f32_16x16x32_bf16 v[94:97], v[144:147], v[232:235], v[94:97]
	v_mfma_f32_16x16x32_bf16 v[74:77], v[136:139], v[240:243], v[74:77]
	v_mfma_f32_16x16x32_bf16 v[78:81], v[144:147], v[240:243], v[78:81]
	v_mfma_f32_16x16x32_bf16 v[114:117], v[170:173], v[212:215], v[114:117]
	v_mfma_f32_16x16x32_bf16 v[118:121], v[204:207], v[212:215], v[118:121]
	v_mfma_f32_16x16x32_bf16 v[98:101], v[170:173], v[220:223], v[98:101]
	v_mfma_f32_16x16x32_bf16 v[102:105], v[204:207], v[220:223], v[102:105]
	v_mfma_f32_16x16x32_bf16 v[82:85], v[170:173], v[228:231], v[82:85]
	v_mfma_f32_16x16x32_bf16 v[86:89], v[204:207], v[228:231], v[86:89]
	v_mfma_f32_16x16x32_bf16 v[66:69], v[170:173], v[236:239], v[66:69]
	v_mfma_f32_16x16x32_bf16 v[70:73], v[204:207], v[236:239], v[70:73]
	v_mfma_f32_16x16x32_bf16 v[114:117], v[200:203], v[216:219], v[114:117]
	v_mfma_f32_16x16x32_bf16 v[118:121], v[208:211], v[216:219], v[118:121]
	v_mfma_f32_16x16x32_bf16 v[98:101], v[200:203], v[224:227], v[98:101]
	v_mfma_f32_16x16x32_bf16 v[102:105], v[208:211], v[224:227], v[102:105]
	v_mfma_f32_16x16x32_bf16 v[82:85], v[200:203], v[232:235], v[82:85]
	v_mfma_f32_16x16x32_bf16 v[86:89], v[208:211], v[232:235], v[86:89]
	v_mfma_f32_16x16x32_bf16 v[66:69], v[200:203], v[240:243], v[66:69]
	v_mfma_f32_16x16x32_bf16 v[70:73], v[208:211], v[240:243], v[70:73]
	s_barrier
	s_add_u32 s4, s64, 0x8000
	s_addc_u32 s5, s65, 0
	s_add_i32 s47, s36, s61
	s_mov_b32 m0, s47
	ds_read_b128 v[212:215], v194 offset:49152
	ds_read_b128 v[216:219], v194 offset:50176
	ds_read_b128 v[220:223], v194 offset:51200
	ds_read_b128 v[224:227], v194 offset:52224
	ds_read_b128 v[228:231], v194 offset:53248
	ds_read_b128 v[232:235], v194 offset:54272
	ds_read_b128 v[236:239], v194 offset:55296
	ds_read_b128 v[240:243], v194 offset:56320
	global_load_lds_dwordx4 v152, s[4:5] sc1
	s_add_i32 m0, s47, 0x2000
	s_nop 0
	global_load_lds_dwordx4 v154, s[4:5] sc1
	s_add_u32 s4, s64, 0xc000
	s_addc_u32 s5, s65, 0
	s_add_i32 s47, s37, s61
	s_mov_b32 m0, s47
	s_nop 0
	global_load_lds_dwordx4 v152, s[4:5] sc1
	s_add_i32 m0, s47, 0x2000
	s_nop 0
	global_load_lds_dwordx4 v154, s[4:5] sc1
	s_mov_b32 m0, s91
	s_nop 0
	global_load_lds_dwordx4 v150, s[56:57] sc1
	s_mov_b32 m0, s92
	s_nop 0
	global_load_lds_dwordx4 v148, s[56:57] sc1
	s_waitcnt vmcnt(8)
	s_waitcnt lgkmcnt(0)
	s_barrier
	s_waitcnt lgkmcnt(0)
	v_mfma_f32_16x16x32_bf16 v[58:61], v[130:133], v[212:215], v[58:61]
	v_mfma_f32_16x16x32_bf16 v[62:65], v[140:143], v[212:215], v[62:65]
	v_mfma_f32_16x16x32_bf16 v[42:45], v[130:133], v[220:223], v[42:45]
	v_mfma_f32_16x16x32_bf16 v[46:49], v[140:143], v[220:223], v[46:49]
	v_mfma_f32_16x16x32_bf16 v[26:29], v[130:133], v[228:231], v[26:29]
	v_mfma_f32_16x16x32_bf16 v[30:33], v[140:143], v[228:231], v[30:33]
	v_mfma_f32_16x16x32_bf16 v[10:13], v[130:133], v[236:239], v[10:13]
	v_mfma_f32_16x16x32_bf16 v[14:17], v[140:143], v[236:239], v[14:17]
	v_mfma_f32_16x16x32_bf16 v[58:61], v[136:139], v[216:219], v[58:61]
	v_mfma_f32_16x16x32_bf16 v[62:65], v[144:147], v[216:219], v[62:65]
	v_mfma_f32_16x16x32_bf16 v[42:45], v[136:139], v[224:227], v[42:45]
	v_mfma_f32_16x16x32_bf16 v[46:49], v[144:147], v[224:227], v[46:49]
	v_mfma_f32_16x16x32_bf16 v[26:29], v[136:139], v[232:235], v[26:29]
	v_mfma_f32_16x16x32_bf16 v[30:33], v[144:147], v[232:235], v[30:33]
	v_mfma_f32_16x16x32_bf16 v[10:13], v[136:139], v[240:243], v[10:13]
	v_mfma_f32_16x16x32_bf16 v[14:17], v[144:147], v[240:243], v[14:17]
	v_mfma_f32_16x16x32_bf16 v[50:53], v[170:173], v[212:215], v[50:53]
	v_mfma_f32_16x16x32_bf16 v[54:57], v[204:207], v[212:215], v[54:57]
	v_mfma_f32_16x16x32_bf16 v[34:37], v[170:173], v[220:223], v[34:37]
	v_mfma_f32_16x16x32_bf16 v[38:41], v[204:207], v[220:223], v[38:41]
	v_mfma_f32_16x16x32_bf16 v[18:21], v[170:173], v[228:231], v[18:21]
	v_mfma_f32_16x16x32_bf16 v[22:25], v[204:207], v[228:231], v[22:25]
	v_mfma_f32_16x16x32_bf16 v[2:5], v[170:173], v[236:239], v[2:5]
	v_mfma_f32_16x16x32_bf16 v[6:9], v[204:207], v[236:239], v[6:9]
	v_mfma_f32_16x16x32_bf16 v[50:53], v[200:203], v[216:219], v[50:53]
	v_mfma_f32_16x16x32_bf16 v[54:57], v[208:211], v[216:219], v[54:57]
	v_mfma_f32_16x16x32_bf16 v[34:37], v[200:203], v[224:227], v[34:37]
	v_mfma_f32_16x16x32_bf16 v[38:41], v[208:211], v[224:227], v[38:41]
	v_mfma_f32_16x16x32_bf16 v[18:21], v[200:203], v[232:235], v[18:21]
	v_mfma_f32_16x16x32_bf16 v[22:25], v[208:211], v[232:235], v[22:25]
	v_mfma_f32_16x16x32_bf16 v[2:5], v[200:203], v[240:243], v[2:5]
	v_mfma_f32_16x16x32_bf16 v[6:9], v[208:211], v[240:243], v[6:9]
	s_barrier
	s_add_i32 s46, s46, 2
	s_add_u32 s44, s44, 0x10000
	s_addc_u32 s45, s45, 0
	s_cmp_gt_u32 s46, 13
	s_mov_b64 s[4:5], s[8:9]
.LBB0_460:
	v_add_u32_e32 v134, s95, v1
	ds_read_b128 v[130:133], v134
	ds_read_b128 v[136:139], v134 offset:1024
	ds_read_b128 v[140:143], v134 offset:2048
	ds_read_b128 v[144:147], v134 offset:3072
	v_add_u32_e32 v134, s93, v1
	ds_read_b128 v[170:173], v134
	ds_read_b128 v[200:203], v134 offset:1024
	ds_read_b128 v[204:207], v134 offset:2048
	ds_read_b128 v[208:211], v134 offset:3072
	s_add_u32 s8, s4, 0x10000
	s_addc_u32 s9, s5, 0
	s_cmp_eq_u32 s46, 12
	s_cselect_b32 s84, s41, s8
	s_cselect_b32 s85, s35, s9
	s_cselect_b32 s64, s43, s44
	s_cselect_b32 s65, s42, s45
	s_add_u32 s56, s84, 0x8000
	s_addc_u32 s57, s85, 0
	s_add_i32 m0, s69, 0xc000
	ds_read_b128 v[212:215], v194
	ds_read_b128 v[216:219], v194 offset:1024
	ds_read_b128 v[220:223], v194 offset:2048
	ds_read_b128 v[224:227], v194 offset:3072
	ds_read_b128 v[228:231], v194 offset:4096
	ds_read_b128 v[232:235], v194 offset:5120
	ds_read_b128 v[236:239], v194 offset:6144
	ds_read_b128 v[240:243], v194 offset:7168
	global_load_lds_dwordx4 v166, s[4:5] sc1
	s_add_i32 m0, s69, 0xe000
	s_nop 0
	global_load_lds_dwordx4 v168, s[4:5] sc1
	s_waitcnt vmcnt(8)
	s_waitcnt lgkmcnt(0)
	s_barrier
	s_waitcnt lgkmcnt(0)
	v_mfma_f32_16x16x32_bf16 v[122:125], v[130:133], v[212:215], v[122:125]
	v_mfma_f32_16x16x32_bf16 v[126:129], v[140:143], v[212:215], v[126:129]
	v_mfma_f32_16x16x32_bf16 v[106:109], v[130:133], v[220:223], v[106:109]
	v_mfma_f32_16x16x32_bf16 v[110:113], v[140:143], v[220:223], v[110:113]
	v_mfma_f32_16x16x32_bf16 v[90:93], v[130:133], v[228:231], v[90:93]
	v_mfma_f32_16x16x32_bf16 v[94:97], v[140:143], v[228:231], v[94:97]
	v_mfma_f32_16x16x32_bf16 v[74:77], v[130:133], v[236:239], v[74:77]
	v_mfma_f32_16x16x32_bf16 v[78:81], v[140:143], v[236:239], v[78:81]
	v_mfma_f32_16x16x32_bf16 v[122:125], v[136:139], v[216:219], v[122:125]
	v_mfma_f32_16x16x32_bf16 v[126:129], v[144:147], v[216:219], v[126:129]
	v_mfma_f32_16x16x32_bf16 v[106:109], v[136:139], v[224:227], v[106:109]
	v_mfma_f32_16x16x32_bf16 v[110:113], v[144:147], v[224:227], v[110:113]
	v_mfma_f32_16x16x32_bf16 v[90:93], v[136:139], v[232:235], v[90:93]
	v_mfma_f32_16x16x32_bf16 v[94:97], v[144:147], v[232:235], v[94:97]
	v_mfma_f32_16x16x32_bf16 v[74:77], v[136:139], v[240:243], v[74:77]
	v_mfma_f32_16x16x32_bf16 v[78:81], v[144:147], v[240:243], v[78:81]
	v_mfma_f32_16x16x32_bf16 v[114:117], v[170:173], v[212:215], v[114:117]
	v_mfma_f32_16x16x32_bf16 v[118:121], v[204:207], v[212:215], v[118:121]
	v_mfma_f32_16x16x32_bf16 v[98:101], v[170:173], v[220:223], v[98:101]
	v_mfma_f32_16x16x32_bf16 v[102:105], v[204:207], v[220:223], v[102:105]
	v_mfma_f32_16x16x32_bf16 v[82:85], v[170:173], v[228:231], v[82:85]
	v_mfma_f32_16x16x32_bf16 v[86:89], v[204:207], v[228:231], v[86:89]
	v_mfma_f32_16x16x32_bf16 v[66:69], v[170:173], v[236:239], v[66:69]
	v_mfma_f32_16x16x32_bf16 v[70:73], v[204:207], v[236:239], v[70:73]
	v_mfma_f32_16x16x32_bf16 v[114:117], v[200:203], v[216:219], v[114:117]
	v_mfma_f32_16x16x32_bf16 v[118:121], v[208:211], v[216:219], v[118:121]
	v_mfma_f32_16x16x32_bf16 v[98:101], v[200:203], v[224:227], v[98:101]
	v_mfma_f32_16x16x32_bf16 v[102:105], v[208:211], v[224:227], v[102:105]
	v_mfma_f32_16x16x32_bf16 v[82:85], v[200:203], v[232:235], v[82:85]
	v_mfma_f32_16x16x32_bf16 v[86:89], v[208:211], v[232:235], v[86:89]
	v_mfma_f32_16x16x32_bf16 v[66:69], v[200:203], v[240:243], v[66:69]
	v_mfma_f32_16x16x32_bf16 v[70:73], v[208:211], v[240:243], v[70:73]
	s_barrier
	s_add_i32 s4, s95, s61
	s_mov_b32 m0, s4
	ds_read_b128 v[212:215], v194 offset:16384
	ds_read_b128 v[216:219], v194 offset:17408
	ds_read_b128 v[220:223], v194 offset:18432
	ds_read_b128 v[224:227], v194 offset:19456
	ds_read_b128 v[228:231], v194 offset:20480
	ds_read_b128 v[232:235], v194 offset:21504
	ds_read_b128 v[236:239], v194 offset:22528
	ds_read_b128 v[240:243], v194 offset:23552
	global_load_lds_dwordx4 v152, s[64:65] sc1
	s_add_i32 m0, s4, 0x2000
	s_add_u32 s4, s64, 0x4000
	s_addc_u32 s5, s65, 0
	s_add_i32 s47, s93, s61
	global_load_lds_dwordx4 v154, s[64:65] sc1
	s_mov_b32 m0, s47
	s_nop 0
	global_load_lds_dwordx4 v152, s[4:5] sc1
	s_add_i32 m0, s47, 0x2000
	s_nop 0
	global_load_lds_dwordx4 v154, s[4:5] sc1
	s_mov_b32 m0, s69
	s_nop 0
	global_load_lds_dwordx4 v150, s[84:85] sc1
	s_mov_b32 m0, s77
	s_nop 0
	global_load_lds_dwordx4 v148, s[84:85] sc1
	s_waitcnt vmcnt(8)
	s_waitcnt lgkmcnt(0)
	s_barrier
	s_waitcnt lgkmcnt(0)
	v_mfma_f32_16x16x32_bf16 v[58:61], v[130:133], v[212:215], v[58:61]
	v_mfma_f32_16x16x32_bf16 v[62:65], v[140:143], v[212:215], v[62:65]
	v_mfma_f32_16x16x32_bf16 v[42:45], v[130:133], v[220:223], v[42:45]
	v_mfma_f32_16x16x32_bf16 v[46:49], v[140:143], v[220:223], v[46:49]
	v_mfma_f32_16x16x32_bf16 v[26:29], v[130:133], v[228:231], v[26:29]
	v_mfma_f32_16x16x32_bf16 v[30:33], v[140:143], v[228:231], v[30:33]
	v_mfma_f32_16x16x32_bf16 v[10:13], v[130:133], v[236:239], v[10:13]
	v_mfma_f32_16x16x32_bf16 v[14:17], v[140:143], v[236:239], v[14:17]
	v_mfma_f32_16x16x32_bf16 v[58:61], v[136:139], v[216:219], v[58:61]
	v_mfma_f32_16x16x32_bf16 v[62:65], v[144:147], v[216:219], v[62:65]
	v_mfma_f32_16x16x32_bf16 v[42:45], v[136:139], v[224:227], v[42:45]
	v_mfma_f32_16x16x32_bf16 v[46:49], v[144:147], v[224:227], v[46:49]
	v_mfma_f32_16x16x32_bf16 v[26:29], v[136:139], v[232:235], v[26:29]
	v_mfma_f32_16x16x32_bf16 v[30:33], v[144:147], v[232:235], v[30:33]
	v_mfma_f32_16x16x32_bf16 v[10:13], v[136:139], v[240:243], v[10:13]
	v_mfma_f32_16x16x32_bf16 v[14:17], v[144:147], v[240:243], v[14:17]
	v_mfma_f32_16x16x32_bf16 v[50:53], v[170:173], v[212:215], v[50:53]
	v_mfma_f32_16x16x32_bf16 v[54:57], v[204:207], v[212:215], v[54:57]
	v_mfma_f32_16x16x32_bf16 v[34:37], v[170:173], v[220:223], v[34:37]
	v_mfma_f32_16x16x32_bf16 v[38:41], v[204:207], v[220:223], v[38:41]
	v_mfma_f32_16x16x32_bf16 v[18:21], v[170:173], v[228:231], v[18:21]
	v_mfma_f32_16x16x32_bf16 v[22:25], v[204:207], v[228:231], v[22:25]
	v_mfma_f32_16x16x32_bf16 v[2:5], v[170:173], v[236:239], v[2:5]
	v_mfma_f32_16x16x32_bf16 v[6:9], v[204:207], v[236:239], v[6:9]
	v_mfma_f32_16x16x32_bf16 v[50:53], v[200:203], v[216:219], v[50:53]
	v_mfma_f32_16x16x32_bf16 v[54:57], v[208:211], v[216:219], v[54:57]
	v_mfma_f32_16x16x32_bf16 v[34:37], v[200:203], v[224:227], v[34:37]
	v_mfma_f32_16x16x32_bf16 v[38:41], v[208:211], v[224:227], v[38:41]
	v_mfma_f32_16x16x32_bf16 v[18:21], v[200:203], v[232:235], v[18:21]
	v_mfma_f32_16x16x32_bf16 v[22:25], v[208:211], v[232:235], v[22:25]
	v_mfma_f32_16x16x32_bf16 v[2:5], v[200:203], v[240:243], v[2:5]
	v_mfma_f32_16x16x32_bf16 v[6:9], v[208:211], v[240:243], v[6:9]
	s_barrier
	v_add_u32_e32 v134, s36, v1
	ds_read_b128 v[130:133], v134
	ds_read_b128 v[136:139], v134 offset:1024
	ds_read_b128 v[140:143], v134 offset:2048
	ds_read_b128 v[144:147], v134 offset:3072
	v_add_u32_e32 v134, s37, v1
	ds_read_b128 v[170:173], v134
	ds_read_b128 v[200:203], v134 offset:1024
	ds_read_b128 v[204:207], v134 offset:2048
	ds_read_b128 v[208:211], v134 offset:3072
	s_add_u32 s4, s84, 0x4000
	s_addc_u32 s5, s85, 0
	s_mov_b32 m0, s86
	ds_read_b128 v[212:215], v194 offset:32768
	ds_read_b128 v[216:219], v194 offset:33792
	ds_read_b128 v[220:223], v194 offset:34816
	ds_read_b128 v[224:227], v194 offset:35840
	ds_read_b128 v[228:231], v194 offset:36864
	ds_read_b128 v[232:235], v194 offset:37888
	ds_read_b128 v[236:239], v194 offset:38912
	ds_read_b128 v[240:243], v194 offset:39936
	global_load_lds_dwordx4 v150, s[4:5] sc1
	s_mov_b32 m0, s87
	s_nop 0
	global_load_lds_dwordx4 v148, s[4:5] sc1
	s_waitcnt vmcnt(8)
	s_waitcnt lgkmcnt(0)
	s_barrier
	s_waitcnt lgkmcnt(0)
	v_mfma_f32_16x16x32_bf16 v[122:125], v[130:133], v[212:215], v[122:125]
	v_mfma_f32_16x16x32_bf16 v[126:129], v[140:143], v[212:215], v[126:129]
	v_mfma_f32_16x16x32_bf16 v[106:109], v[130:133], v[220:223], v[106:109]
	v_mfma_f32_16x16x32_bf16 v[110:113], v[140:143], v[220:223], v[110:113]
	v_mfma_f32_16x16x32_bf16 v[90:93], v[130:133], v[228:231], v[90:93]
	v_mfma_f32_16x16x32_bf16 v[94:97], v[140:143], v[228:231], v[94:97]
	v_mfma_f32_16x16x32_bf16 v[74:77], v[130:133], v[236:239], v[74:77]
	v_mfma_f32_16x16x32_bf16 v[78:81], v[140:143], v[236:239], v[78:81]
	v_mfma_f32_16x16x32_bf16 v[122:125], v[136:139], v[216:219], v[122:125]
	v_mfma_f32_16x16x32_bf16 v[126:129], v[144:147], v[216:219], v[126:129]
	v_mfma_f32_16x16x32_bf16 v[106:109], v[136:139], v[224:227], v[106:109]
	v_mfma_f32_16x16x32_bf16 v[110:113], v[144:147], v[224:227], v[110:113]
	v_mfma_f32_16x16x32_bf16 v[90:93], v[136:139], v[232:235], v[90:93]
	v_mfma_f32_16x16x32_bf16 v[94:97], v[144:147], v[232:235], v[94:97]
	v_mfma_f32_16x16x32_bf16 v[74:77], v[136:139], v[240:243], v[74:77]
	v_mfma_f32_16x16x32_bf16 v[78:81], v[144:147], v[240:243], v[78:81]
	v_mfma_f32_16x16x32_bf16 v[114:117], v[170:173], v[212:215], v[114:117]
	v_mfma_f32_16x16x32_bf16 v[118:121], v[204:207], v[212:215], v[118:121]
	v_mfma_f32_16x16x32_bf16 v[98:101], v[170:173], v[220:223], v[98:101]
	v_mfma_f32_16x16x32_bf16 v[102:105], v[204:207], v[220:223], v[102:105]
	v_mfma_f32_16x16x32_bf16 v[82:85], v[170:173], v[228:231], v[82:85]
	v_mfma_f32_16x16x32_bf16 v[86:89], v[204:207], v[228:231], v[86:89]
	v_mfma_f32_16x16x32_bf16 v[66:69], v[170:173], v[236:239], v[66:69]
	v_mfma_f32_16x16x32_bf16 v[70:73], v[204:207], v[236:239], v[70:73]
	v_mfma_f32_16x16x32_bf16 v[114:117], v[200:203], v[216:219], v[114:117]
	v_mfma_f32_16x16x32_bf16 v[118:121], v[208:211], v[216:219], v[118:121]
	v_mfma_f32_16x16x32_bf16 v[98:101], v[200:203], v[224:227], v[98:101]
	v_mfma_f32_16x16x32_bf16 v[102:105], v[208:211], v[224:227], v[102:105]
	v_mfma_f32_16x16x32_bf16 v[82:85], v[200:203], v[232:235], v[82:85]
	v_mfma_f32_16x16x32_bf16 v[86:89], v[208:211], v[232:235], v[86:89]
	v_mfma_f32_16x16x32_bf16 v[66:69], v[200:203], v[240:243], v[66:69]
	v_mfma_f32_16x16x32_bf16 v[70:73], v[208:211], v[240:243], v[70:73]
	s_barrier
	s_add_u32 s4, s64, 0x8000
	s_addc_u32 s5, s65, 0
	s_add_i32 s47, s36, s61
	s_mov_b32 m0, s47
	ds_read_b128 v[212:215], v194 offset:49152
	ds_read_b128 v[216:219], v194 offset:50176
	ds_read_b128 v[220:223], v194 offset:51200
	ds_read_b128 v[224:227], v194 offset:52224
	ds_read_b128 v[228:231], v194 offset:53248
	ds_read_b128 v[232:235], v194 offset:54272
	ds_read_b128 v[236:239], v194 offset:55296
	ds_read_b128 v[240:243], v194 offset:56320
	global_load_lds_dwordx4 v152, s[4:5] sc1
	s_add_i32 m0, s47, 0x2000
	s_nop 0
	global_load_lds_dwordx4 v154, s[4:5] sc1
	s_add_u32 s4, s64, 0xc000
	s_addc_u32 s5, s65, 0
	s_add_i32 s47, s37, s61
	s_mov_b32 m0, s47
	s_nop 0
	global_load_lds_dwordx4 v152, s[4:5] sc1
	s_add_i32 m0, s47, 0x2000
	s_nop 0
	global_load_lds_dwordx4 v154, s[4:5] sc1
	s_mov_b32 m0, s91
	s_nop 0
	global_load_lds_dwordx4 v150, s[56:57] sc1
	s_mov_b32 m0, s92
	s_nop 0
	global_load_lds_dwordx4 v148, s[56:57] sc1
	s_waitcnt vmcnt(8)
	s_waitcnt lgkmcnt(0)
	s_barrier
	s_waitcnt lgkmcnt(0)
	v_mfma_f32_16x16x32_bf16 v[58:61], v[130:133], v[212:215], v[58:61]
	v_mfma_f32_16x16x32_bf16 v[62:65], v[140:143], v[212:215], v[62:65]
	v_mfma_f32_16x16x32_bf16 v[42:45], v[130:133], v[220:223], v[42:45]
	v_mfma_f32_16x16x32_bf16 v[46:49], v[140:143], v[220:223], v[46:49]
	v_mfma_f32_16x16x32_bf16 v[26:29], v[130:133], v[228:231], v[26:29]
	v_mfma_f32_16x16x32_bf16 v[30:33], v[140:143], v[228:231], v[30:33]
	v_mfma_f32_16x16x32_bf16 v[10:13], v[130:133], v[236:239], v[10:13]
	v_mfma_f32_16x16x32_bf16 v[14:17], v[140:143], v[236:239], v[14:17]
	v_mfma_f32_16x16x32_bf16 v[58:61], v[136:139], v[216:219], v[58:61]
	v_mfma_f32_16x16x32_bf16 v[62:65], v[144:147], v[216:219], v[62:65]
	v_mfma_f32_16x16x32_bf16 v[42:45], v[136:139], v[224:227], v[42:45]
	v_mfma_f32_16x16x32_bf16 v[46:49], v[144:147], v[224:227], v[46:49]
	v_mfma_f32_16x16x32_bf16 v[26:29], v[136:139], v[232:235], v[26:29]
	v_mfma_f32_16x16x32_bf16 v[30:33], v[144:147], v[232:235], v[30:33]
	v_mfma_f32_16x16x32_bf16 v[10:13], v[136:139], v[240:243], v[10:13]
	v_mfma_f32_16x16x32_bf16 v[14:17], v[144:147], v[240:243], v[14:17]
	v_mfma_f32_16x16x32_bf16 v[50:53], v[170:173], v[212:215], v[50:53]
	v_mfma_f32_16x16x32_bf16 v[54:57], v[204:207], v[212:215], v[54:57]
	v_mfma_f32_16x16x32_bf16 v[34:37], v[170:173], v[220:223], v[34:37]
	v_mfma_f32_16x16x32_bf16 v[38:41], v[204:207], v[220:223], v[38:41]
	v_mfma_f32_16x16x32_bf16 v[18:21], v[170:173], v[228:231], v[18:21]
	v_mfma_f32_16x16x32_bf16 v[22:25], v[204:207], v[228:231], v[22:25]
	v_mfma_f32_16x16x32_bf16 v[2:5], v[170:173], v[236:239], v[2:5]
	v_mfma_f32_16x16x32_bf16 v[6:9], v[204:207], v[236:239], v[6:9]
	v_mfma_f32_16x16x32_bf16 v[50:53], v[200:203], v[216:219], v[50:53]
	v_mfma_f32_16x16x32_bf16 v[54:57], v[208:211], v[216:219], v[54:57]
	v_mfma_f32_16x16x32_bf16 v[34:37], v[200:203], v[224:227], v[34:37]
	v_mfma_f32_16x16x32_bf16 v[38:41], v[208:211], v[224:227], v[38:41]
	v_mfma_f32_16x16x32_bf16 v[18:21], v[200:203], v[232:235], v[18:21]
	v_mfma_f32_16x16x32_bf16 v[22:25], v[208:211], v[232:235], v[22:25]
	v_mfma_f32_16x16x32_bf16 v[2:5], v[200:203], v[240:243], v[2:5]
	v_mfma_f32_16x16x32_bf16 v[6:9], v[208:211], v[240:243], v[6:9]
	s_barrier
	s_add_i32 s46, s46, 2
	s_add_u32 s44, s44, 0x10000
	s_addc_u32 s45, s45, 0
	s_cmp_gt_u32 s46, 13
	s_mov_b64 s[4:5], s[8:9]
	s_cbranch_scc0 .LBB0_460
	s_and_b64 vcc, exec, s[70:71]
	s_cbranch_vccz .LBB0_463
	s_barrier

.LBB0_622:
	s_ashr_i32 s57, s56, 31
	s_lshl_b64 s[62:63], s[56:57], 19
	s_add_u32 s62, s68, s62
	v_readlane_b32 s11, v253, 33
	s_addc_u32 s63, s11, s63
	s_and_b64 s[64:65], s[66:67], exec
	s_cselect_b32 s55, s63, s71
	s_cselect_b32 s57, s62, s70
	s_ashr_i32 s11, s10, 31
	s_lshl_b64 s[64:65], s[10:11], 19
	s_add_u32 s64, s37, s64
	s_addc_u32 s65, s38, s65
	s_and_b64 s[82:83], s[66:67], exec
	s_cselect_b32 s11, s65, s79
	s_cselect_b32 s61, s64, s78
	s_add_u32 s69, s78, 0x10000
	s_addc_u32 s77, s79, 0
	s_mov_b32 s94, -2
	v_add_u32_e32 v160, s47, v142
	ds_read_b128 v[152:155], v160
	ds_read_b128 v[156:159], v160 offset:1024
	ds_read_b128 v[162:165], v160 offset:2048
	ds_read_b128 v[166:169], v160 offset:3072
	v_add_u32_e32 v160, s48, v142
	ds_read_b128 v[170:173], v160
	ds_read_b128 v[174:177], v160 offset:1024
	ds_read_b128 v[178:181], v160 offset:2048
	ds_read_b128 v[182:185], v160 offset:3072
	s_add_u32 s78, s70, 0x10000
	s_addc_u32 s79, s71, 0
	s_cmp_eq_u32 s94, 12
	s_cselect_b32 s92, s57, s78
	s_cselect_b32 s93, s55, s79
	s_cselect_b32 s90, s61, s69
	s_cselect_b32 s91, s11, s77
	s_add_u32 s82, s92, 0x8000
	s_addc_u32 s83, s93, 0
	s_add_i32 m0, s39, 0xc000
	ds_read_b128 v[192:195], v150
	ds_read_b128 v[200:203], v150 offset:1024
	ds_read_b128 v[204:207], v150 offset:2048
	ds_read_b128 v[208:211], v150 offset:3072
	ds_read_b128 v[212:215], v150 offset:4096
	ds_read_b128 v[216:219], v150 offset:5120
	ds_read_b128 v[220:223], v150 offset:6144
	ds_read_b128 v[224:227], v150 offset:7168
	global_load_lds_dwordx4 v138, s[70:71] sc1
	s_add_i32 m0, s39, 0xe000
	s_nop 0
	global_load_lds_dwordx4 v140, s[70:71] sc1
	s_waitcnt vmcnt(8)
	s_waitcnt lgkmcnt(0)
	s_barrier
	s_waitcnt lgkmcnt(0)
	v_mfma_f32_16x16x32_bf16 v[98:101], v[152:155], v[192:195], 0
	v_mfma_f32_16x16x32_bf16 v[102:105], v[162:165], v[192:195], 0
	v_mfma_f32_16x16x32_bf16 v[62:65], v[152:155], v[204:207], 0
	v_mfma_f32_16x16x32_bf16 v[78:81], v[162:165], v[204:207], 0
	v_mfma_f32_16x16x32_bf16 v[34:37], v[152:155], v[212:215], 0
	v_mfma_f32_16x16x32_bf16 v[46:49], v[162:165], v[212:215], 0
	v_mfma_f32_16x16x32_bf16 v[14:17], v[152:155], v[220:223], 0
	v_mfma_f32_16x16x32_bf16 v[22:25], v[162:165], v[220:223], 0
	v_mfma_f32_16x16x32_bf16 v[98:101], v[156:159], v[200:203], v[98:101]
	v_mfma_f32_16x16x32_bf16 v[102:105], v[166:169], v[200:203], v[102:105]
	v_mfma_f32_16x16x32_bf16 v[62:65], v[156:159], v[208:211], v[62:65]
	v_mfma_f32_16x16x32_bf16 v[78:81], v[166:169], v[208:211], v[78:81]
	v_mfma_f32_16x16x32_bf16 v[34:37], v[156:159], v[216:219], v[34:37]
	v_mfma_f32_16x16x32_bf16 v[46:49], v[166:169], v[216:219], v[46:49]
	v_mfma_f32_16x16x32_bf16 v[14:17], v[156:159], v[224:227], v[14:17]
	v_mfma_f32_16x16x32_bf16 v[22:25], v[166:169], v[224:227], v[22:25]
	v_mfma_f32_16x16x32_bf16 v[122:125], v[170:173], v[192:195], 0
	v_mfma_f32_16x16x32_bf16 v[126:129], v[178:181], v[192:195], 0
	v_mfma_f32_16x16x32_bf16 v[110:113], v[170:173], v[204:207], 0
	v_mfma_f32_16x16x32_bf16 v[118:121], v[178:181], v[204:207], 0
	v_mfma_f32_16x16x32_bf16 v[86:89], v[170:173], v[212:215], 0
	v_mfma_f32_16x16x32_bf16 v[94:97], v[178:181], v[212:215], 0
	v_mfma_f32_16x16x32_bf16 v[54:57], v[170:173], v[220:223], 0
	v_mfma_f32_16x16x32_bf16 v[70:73], v[178:181], v[220:223], 0
	v_mfma_f32_16x16x32_bf16 v[122:125], v[174:177], v[200:203], v[122:125]
	v_mfma_f32_16x16x32_bf16 v[126:129], v[182:185], v[200:203], v[126:129]
	v_mfma_f32_16x16x32_bf16 v[110:113], v[174:177], v[208:211], v[110:113]
	v_mfma_f32_16x16x32_bf16 v[118:121], v[182:185], v[208:211], v[118:121]
	v_mfma_f32_16x16x32_bf16 v[86:89], v[174:177], v[216:219], v[86:89]
	v_mfma_f32_16x16x32_bf16 v[94:97], v[182:185], v[216:219], v[94:97]
	v_mfma_f32_16x16x32_bf16 v[54:57], v[174:177], v[224:227], v[54:57]
	v_mfma_f32_16x16x32_bf16 v[70:73], v[182:185], v[224:227], v[70:73]
	s_barrier
	s_add_i32 s70, s47, s35
	s_mov_b32 m0, s70
	ds_read_b128 v[192:195], v150 offset:16384
	ds_read_b128 v[200:203], v150 offset:17408
	ds_read_b128 v[204:207], v150 offset:18432
	ds_read_b128 v[208:211], v150 offset:19456
	ds_read_b128 v[212:215], v150 offset:20480
	ds_read_b128 v[216:219], v150 offset:21504
	ds_read_b128 v[220:223], v150 offset:22528
	ds_read_b128 v[224:227], v150 offset:23552
	global_load_lds_dwordx4 v132, s[90:91] sc1
	s_add_i32 m0, s70, 0x2000
	s_add_u32 s70, s90, 0x4000
	s_addc_u32 s71, s91, 0
	s_add_i32 s95, s48, s35
	global_load_lds_dwordx4 v136, s[90:91] sc1
	s_mov_b32 m0, s95
	s_nop 0
	global_load_lds_dwordx4 v132, s[70:71] sc1
	s_add_i32 m0, s95, 0x2000
	s_nop 0
	global_load_lds_dwordx4 v136, s[70:71] sc1
	s_mov_b32 m0, s39
	s_nop 0
	global_load_lds_dwordx4 v130, s[92:93] sc1
	s_mov_b32 m0, s40
	s_nop 0
	global_load_lds_dwordx4 v134, s[92:93] sc1
	s_waitcnt vmcnt(8)
	s_waitcnt lgkmcnt(0)
	s_barrier
	s_waitcnt lgkmcnt(0)
	v_mfma_f32_16x16x32_bf16 v[58:61], v[152:155], v[192:195], 0
	v_mfma_f32_16x16x32_bf16 v[74:77], v[162:165], v[192:195], 0
	v_mfma_f32_16x16x32_bf16 v[30:33], v[152:155], v[204:207], 0
	v_mfma_f32_16x16x32_bf16 v[42:45], v[162:165], v[204:207], 0
	v_mfma_f32_16x16x32_bf16 v[10:13], v[152:155], v[212:215], 0
	v_mfma_f32_16x16x32_bf16 v[18:21], v[162:165], v[212:215], 0
	v_mfma_f32_16x16x32_bf16 v[2:5], v[152:155], v[220:223], 0
	v_mfma_f32_16x16x32_bf16 v[6:9], v[162:165], v[220:223], 0
	v_mfma_f32_16x16x32_bf16 v[58:61], v[156:159], v[200:203], v[58:61]
	v_mfma_f32_16x16x32_bf16 v[74:77], v[166:169], v[200:203], v[74:77]
	v_mfma_f32_16x16x32_bf16 v[30:33], v[156:159], v[208:211], v[30:33]
	v_mfma_f32_16x16x32_bf16 v[42:45], v[166:169], v[208:211], v[42:45]
	v_mfma_f32_16x16x32_bf16 v[10:13], v[156:159], v[216:219], v[10:13]
	v_mfma_f32_16x16x32_bf16 v[18:21], v[166:169], v[216:219], v[18:21]
	v_mfma_f32_16x16x32_bf16 v[2:5], v[156:159], v[224:227], v[2:5]
	v_mfma_f32_16x16x32_bf16 v[6:9], v[166:169], v[224:227], v[6:9]
	v_mfma_f32_16x16x32_bf16 v[106:109], v[170:173], v[192:195], 0
	v_mfma_f32_16x16x32_bf16 v[114:117], v[178:181], v[192:195], 0
	v_mfma_f32_16x16x32_bf16 v[82:85], v[170:173], v[204:207], 0
	v_mfma_f32_16x16x32_bf16 v[90:93], v[178:181], v[204:207], 0
	v_mfma_f32_16x16x32_bf16 v[50:53], v[170:173], v[212:215], 0
	v_mfma_f32_16x16x32_bf16 v[66:69], v[178:181], v[212:215], 0
	v_mfma_f32_16x16x32_bf16 v[26:29], v[170:173], v[220:223], 0
	v_mfma_f32_16x16x32_bf16 v[38:41], v[178:181], v[220:223], 0
	v_mfma_f32_16x16x32_bf16 v[106:109], v[174:177], v[200:203], v[106:109]
	v_mfma_f32_16x16x32_bf16 v[114:117], v[182:185], v[200:203], v[114:117]
	v_mfma_f32_16x16x32_bf16 v[82:85], v[174:177], v[208:211], v[82:85]
	v_mfma_f32_16x16x32_bf16 v[90:93], v[182:185], v[208:211], v[90:93]
	v_mfma_f32_16x16x32_bf16 v[50:53], v[174:177], v[216:219], v[50:53]
	v_mfma_f32_16x16x32_bf16 v[66:69], v[182:185], v[216:219], v[66:69]
	v_mfma_f32_16x16x32_bf16 v[26:29], v[174:177], v[224:227], v[26:29]
	v_mfma_f32_16x16x32_bf16 v[38:41], v[182:185], v[224:227], v[38:41]
	s_barrier
	v_add_u32_e32 v160, s49, v142
	ds_read_b128 v[152:155], v160
	ds_read_b128 v[156:159], v160 offset:1024
	ds_read_b128 v[162:165], v160 offset:2048
	ds_read_b128 v[166:169], v160 offset:3072
	v_add_u32_e32 v160, s50, v142
	ds_read_b128 v[170:173], v160
	ds_read_b128 v[174:177], v160 offset:1024
	ds_read_b128 v[178:181], v160 offset:2048
	ds_read_b128 v[182:185], v160 offset:3072
	s_add_u32 s70, s92, 0x4000
	s_addc_u32 s71, s93, 0
	s_mov_b32 m0, s41
	ds_read_b128 v[192:195], v150 offset:32768
	ds_read_b128 v[200:203], v150 offset:33792
	ds_read_b128 v[204:207], v150 offset:34816
	ds_read_b128 v[208:211], v150 offset:35840
	ds_read_b128 v[212:215], v150 offset:36864
	ds_read_b128 v[216:219], v150 offset:37888
	ds_read_b128 v[220:223], v150 offset:38912
	ds_read_b128 v[224:227], v150 offset:39936
	global_load_lds_dwordx4 v130, s[70:71] sc1
	s_mov_b32 m0, s42
	s_nop 0
	global_load_lds_dwordx4 v134, s[70:71] sc1
	s_waitcnt vmcnt(8)
	s_waitcnt lgkmcnt(0)
	s_barrier
	s_waitcnt lgkmcnt(0)
	v_mfma_f32_16x16x32_bf16 v[98:101], v[152:155], v[192:195], v[98:101]
	v_mfma_f32_16x16x32_bf16 v[102:105], v[162:165], v[192:195], v[102:105]
	v_mfma_f32_16x16x32_bf16 v[62:65], v[152:155], v[204:207], v[62:65]
	v_mfma_f32_16x16x32_bf16 v[78:81], v[162:165], v[204:207], v[78:81]
	v_mfma_f32_16x16x32_bf16 v[34:37], v[152:155], v[212:215], v[34:37]
	v_mfma_f32_16x16x32_bf16 v[46:49], v[162:165], v[212:215], v[46:49]
	v_mfma_f32_16x16x32_bf16 v[14:17], v[152:155], v[220:223], v[14:17]
	v_mfma_f32_16x16x32_bf16 v[22:25], v[162:165], v[220:223], v[22:25]
	v_mfma_f32_16x16x32_bf16 v[98:101], v[156:159], v[200:203], v[98:101]
	v_mfma_f32_16x16x32_bf16 v[102:105], v[166:169], v[200:203], v[102:105]
	v_mfma_f32_16x16x32_bf16 v[62:65], v[156:159], v[208:211], v[62:65]
	v_mfma_f32_16x16x32_bf16 v[78:81], v[166:169], v[208:211], v[78:81]
	v_mfma_f32_16x16x32_bf16 v[34:37], v[156:159], v[216:219], v[34:37]
	v_mfma_f32_16x16x32_bf16 v[46:49], v[166:169], v[216:219], v[46:49]
	v_mfma_f32_16x16x32_bf16 v[14:17], v[156:159], v[224:227], v[14:17]
	v_mfma_f32_16x16x32_bf16 v[22:25], v[166:169], v[224:227], v[22:25]
	v_mfma_f32_16x16x32_bf16 v[122:125], v[170:173], v[192:195], v[122:125]
	v_mfma_f32_16x16x32_bf16 v[126:129], v[178:181], v[192:195], v[126:129]
	v_mfma_f32_16x16x32_bf16 v[110:113], v[170:173], v[204:207], v[110:113]
	v_mfma_f32_16x16x32_bf16 v[118:121], v[178:181], v[204:207], v[118:121]
	v_mfma_f32_16x16x32_bf16 v[86:89], v[170:173], v[212:215], v[86:89]
	v_mfma_f32_16x16x32_bf16 v[94:97], v[178:181], v[212:215], v[94:97]
	v_mfma_f32_16x16x32_bf16 v[54:57], v[170:173], v[220:223], v[54:57]
	v_mfma_f32_16x16x32_bf16 v[70:73], v[178:181], v[220:223], v[70:73]
	v_mfma_f32_16x16x32_bf16 v[122:125], v[174:177], v[200:203], v[122:125]
	v_mfma_f32_16x16x32_bf16 v[126:129], v[182:185], v[200:203], v[126:129]
	v_mfma_f32_16x16x32_bf16 v[110:113], v[174:177], v[208:211], v[110:113]
	v_mfma_f32_16x16x32_bf16 v[118:121], v[182:185], v[208:211], v[118:121]
	v_mfma_f32_16x16x32_bf16 v[86:89], v[174:177], v[216:219], v[86:89]
	v_mfma_f32_16x16x32_bf16 v[94:97], v[182:185], v[216:219], v[94:97]
	v_mfma_f32_16x16x32_bf16 v[54:57], v[174:177], v[224:227], v[54:57]
	v_mfma_f32_16x16x32_bf16 v[70:73], v[182:185], v[224:227], v[70:73]
	s_barrier
	s_add_u32 s70, s90, 0x8000
	s_addc_u32 s71, s91, 0
	s_add_i32 s92, s49, s35
	s_mov_b32 m0, s92
	ds_read_b128 v[192:195], v150 offset:49152
	ds_read_b128 v[200:203], v150 offset:50176
	ds_read_b128 v[204:207], v150 offset:51200
	ds_read_b128 v[208:211], v150 offset:52224
	ds_read_b128 v[212:215], v150 offset:53248
	ds_read_b128 v[216:219], v150 offset:54272
	ds_read_b128 v[220:223], v150 offset:55296
	ds_read_b128 v[224:227], v150 offset:56320
	global_load_lds_dwordx4 v132, s[70:71] sc1
	s_add_i32 m0, s92, 0x2000
	s_nop 0
	global_load_lds_dwordx4 v136, s[70:71] sc1
	s_add_u32 s70, s90, 0xc000
	s_addc_u32 s71, s91, 0
	s_add_i32 s90, s50, s35
	s_mov_b32 m0, s90
	s_nop 0
	global_load_lds_dwordx4 v132, s[70:71] sc1
	s_add_i32 m0, s90, 0x2000
	s_nop 0
	global_load_lds_dwordx4 v136, s[70:71] sc1
	s_mov_b32 m0, s44
	s_nop 0
	global_load_lds_dwordx4 v130, s[82:83] sc1
	s_mov_b32 m0, s45
	s_nop 0
	global_load_lds_dwordx4 v134, s[82:83] sc1
	s_waitcnt vmcnt(8)
	s_waitcnt lgkmcnt(0)
	s_barrier
	s_waitcnt lgkmcnt(0)
	v_mfma_f32_16x16x32_bf16 v[58:61], v[152:155], v[192:195], v[58:61]
	v_mfma_f32_16x16x32_bf16 v[74:77], v[162:165], v[192:195], v[74:77]
	v_mfma_f32_16x16x32_bf16 v[30:33], v[152:155], v[204:207], v[30:33]
	v_mfma_f32_16x16x32_bf16 v[42:45], v[162:165], v[204:207], v[42:45]
	v_mfma_f32_16x16x32_bf16 v[10:13], v[152:155], v[212:215], v[10:13]
	v_mfma_f32_16x16x32_bf16 v[18:21], v[162:165], v[212:215], v[18:21]
	v_mfma_f32_16x16x32_bf16 v[2:5], v[152:155], v[220:223], v[2:5]
	v_mfma_f32_16x16x32_bf16 v[6:9], v[162:165], v[220:223], v[6:9]
	v_mfma_f32_16x16x32_bf16 v[58:61], v[156:159], v[200:203], v[58:61]
	v_mfma_f32_16x16x32_bf16 v[74:77], v[166:169], v[200:203], v[74:77]
	v_mfma_f32_16x16x32_bf16 v[30:33], v[156:159], v[208:211], v[30:33]
	v_mfma_f32_16x16x32_bf16 v[42:45], v[166:169], v[208:211], v[42:45]
	v_mfma_f32_16x16x32_bf16 v[10:13], v[156:159], v[216:219], v[10:13]
	v_mfma_f32_16x16x32_bf16 v[18:21], v[166:169], v[216:219], v[18:21]
	v_mfma_f32_16x16x32_bf16 v[2:5], v[156:159], v[224:227], v[2:5]
	v_mfma_f32_16x16x32_bf16 v[6:9], v[166:169], v[224:227], v[6:9]
	v_mfma_f32_16x16x32_bf16 v[106:109], v[170:173], v[192:195], v[106:109]
	v_mfma_f32_16x16x32_bf16 v[114:117], v[178:181], v[192:195], v[114:117]
	v_mfma_f32_16x16x32_bf16 v[82:85], v[170:173], v[204:207], v[82:85]
	v_mfma_f32_16x16x32_bf16 v[90:93], v[178:181], v[204:207], v[90:93]
	v_mfma_f32_16x16x32_bf16 v[50:53], v[170:173], v[212:215], v[50:53]
	v_mfma_f32_16x16x32_bf16 v[66:69], v[178:181], v[212:215], v[66:69]
	v_mfma_f32_16x16x32_bf16 v[26:29], v[170:173], v[220:223], v[26:29]
	v_mfma_f32_16x16x32_bf16 v[38:41], v[178:181], v[220:223], v[38:41]
	v_mfma_f32_16x16x32_bf16 v[106:109], v[174:177], v[200:203], v[106:109]
	v_mfma_f32_16x16x32_bf16 v[114:117], v[182:185], v[200:203], v[114:117]
	v_mfma_f32_16x16x32_bf16 v[82:85], v[174:177], v[208:211], v[82:85]
	v_mfma_f32_16x16x32_bf16 v[90:93], v[182:185], v[208:211], v[90:93]
	v_mfma_f32_16x16x32_bf16 v[50:53], v[174:177], v[216:219], v[50:53]
	v_mfma_f32_16x16x32_bf16 v[66:69], v[182:185], v[216:219], v[66:69]
	v_mfma_f32_16x16x32_bf16 v[26:29], v[174:177], v[224:227], v[26:29]
	v_mfma_f32_16x16x32_bf16 v[38:41], v[182:185], v[224:227], v[38:41]
	s_barrier
	s_add_i32 s94, s94, 2
	s_add_u32 s69, s69, 0x10000
	s_addc_u32 s77, s77, 0
	s_cmp_gt_u32 s94, 13
	s_mov_b64 s[70:71], s[78:79]
.LBB0_623:
	v_add_u32_e32 v160, s47, v142
	ds_read_b128 v[152:155], v160
	ds_read_b128 v[156:159], v160 offset:1024
	ds_read_b128 v[162:165], v160 offset:2048
	ds_read_b128 v[166:169], v160 offset:3072
	v_add_u32_e32 v160, s48, v142
	ds_read_b128 v[170:173], v160
	ds_read_b128 v[174:177], v160 offset:1024
	ds_read_b128 v[178:181], v160 offset:2048
	ds_read_b128 v[182:185], v160 offset:3072
	s_add_u32 s78, s70, 0x10000
	s_addc_u32 s79, s71, 0
	s_cmp_eq_u32 s94, 12
	s_cselect_b32 s92, s57, s78
	s_cselect_b32 s93, s55, s79
	s_cselect_b32 s90, s61, s69
	s_cselect_b32 s91, s11, s77
	s_add_u32 s82, s92, 0x8000
	s_addc_u32 s83, s93, 0
	s_add_i32 m0, s39, 0xc000
	ds_read_b128 v[192:195], v150
	ds_read_b128 v[200:203], v150 offset:1024
	ds_read_b128 v[204:207], v150 offset:2048
	ds_read_b128 v[208:211], v150 offset:3072
	ds_read_b128 v[212:215], v150 offset:4096
	ds_read_b128 v[216:219], v150 offset:5120
	ds_read_b128 v[220:223], v150 offset:6144
	ds_read_b128 v[224:227], v150 offset:7168
	global_load_lds_dwordx4 v138, s[70:71] sc1
	s_add_i32 m0, s39, 0xe000
	s_nop 0
	global_load_lds_dwordx4 v140, s[70:71] sc1
	s_waitcnt vmcnt(8)
	s_waitcnt lgkmcnt(0)
	s_barrier
	s_waitcnt lgkmcnt(0)
	v_mfma_f32_16x16x32_bf16 v[98:101], v[152:155], v[192:195], v[98:101]
	v_mfma_f32_16x16x32_bf16 v[102:105], v[162:165], v[192:195], v[102:105]
	v_mfma_f32_16x16x32_bf16 v[62:65], v[152:155], v[204:207], v[62:65]
	v_mfma_f32_16x16x32_bf16 v[78:81], v[162:165], v[204:207], v[78:81]
	v_mfma_f32_16x16x32_bf16 v[34:37], v[152:155], v[212:215], v[34:37]
	v_mfma_f32_16x16x32_bf16 v[46:49], v[162:165], v[212:215], v[46:49]
	v_mfma_f32_16x16x32_bf16 v[14:17], v[152:155], v[220:223], v[14:17]
	v_mfma_f32_16x16x32_bf16 v[22:25], v[162:165], v[220:223], v[22:25]
	v_mfma_f32_16x16x32_bf16 v[98:101], v[156:159], v[200:203], v[98:101]
	v_mfma_f32_16x16x32_bf16 v[102:105], v[166:169], v[200:203], v[102:105]
	v_mfma_f32_16x16x32_bf16 v[62:65], v[156:159], v[208:211], v[62:65]
	v_mfma_f32_16x16x32_bf16 v[78:81], v[166:169], v[208:211], v[78:81]
	v_mfma_f32_16x16x32_bf16 v[34:37], v[156:159], v[216:219], v[34:37]
	v_mfma_f32_16x16x32_bf16 v[46:49], v[166:169], v[216:219], v[46:49]
	v_mfma_f32_16x16x32_bf16 v[14:17], v[156:159], v[224:227], v[14:17]
	v_mfma_f32_16x16x32_bf16 v[22:25], v[166:169], v[224:227], v[22:25]
	v_mfma_f32_16x16x32_bf16 v[122:125], v[170:173], v[192:195], v[122:125]
	v_mfma_f32_16x16x32_bf16 v[126:129], v[178:181], v[192:195], v[126:129]
	v_mfma_f32_16x16x32_bf16 v[110:113], v[170:173], v[204:207], v[110:113]
	v_mfma_f32_16x16x32_bf16 v[118:121], v[178:181], v[204:207], v[118:121]
	v_mfma_f32_16x16x32_bf16 v[86:89], v[170:173], v[212:215], v[86:89]
	v_mfma_f32_16x16x32_bf16 v[94:97], v[178:181], v[212:215], v[94:97]
	v_mfma_f32_16x16x32_bf16 v[54:57], v[170:173], v[220:223], v[54:57]
	v_mfma_f32_16x16x32_bf16 v[70:73], v[178:181], v[220:223], v[70:73]
	v_mfma_f32_16x16x32_bf16 v[122:125], v[174:177], v[200:203], v[122:125]
	v_mfma_f32_16x16x32_bf16 v[126:129], v[182:185], v[200:203], v[126:129]
	v_mfma_f32_16x16x32_bf16 v[110:113], v[174:177], v[208:211], v[110:113]
	v_mfma_f32_16x16x32_bf16 v[118:121], v[182:185], v[208:211], v[118:121]
	v_mfma_f32_16x16x32_bf16 v[86:89], v[174:177], v[216:219], v[86:89]
	v_mfma_f32_16x16x32_bf16 v[94:97], v[182:185], v[216:219], v[94:97]
	v_mfma_f32_16x16x32_bf16 v[54:57], v[174:177], v[224:227], v[54:57]
	v_mfma_f32_16x16x32_bf16 v[70:73], v[182:185], v[224:227], v[70:73]
	s_barrier
	s_add_i32 s70, s47, s35
	s_mov_b32 m0, s70
	ds_read_b128 v[192:195], v150 offset:16384
	ds_read_b128 v[200:203], v150 offset:17408
	ds_read_b128 v[204:207], v150 offset:18432
	ds_read_b128 v[208:211], v150 offset:19456
	ds_read_b128 v[212:215], v150 offset:20480
	ds_read_b128 v[216:219], v150 offset:21504
	ds_read_b128 v[220:223], v150 offset:22528
	ds_read_b128 v[224:227], v150 offset:23552
	global_load_lds_dwordx4 v132, s[90:91] sc1
	s_add_i32 m0, s70, 0x2000
	s_add_u32 s70, s90, 0x4000
	s_addc_u32 s71, s91, 0
	s_add_i32 s95, s48, s35
	global_load_lds_dwordx4 v136, s[90:91] sc1
	s_mov_b32 m0, s95
	s_nop 0
	global_load_lds_dwordx4 v132, s[70:71] sc1
	s_add_i32 m0, s95, 0x2000
	s_nop 0
	global_load_lds_dwordx4 v136, s[70:71] sc1
	s_mov_b32 m0, s39
	s_nop 0
	global_load_lds_dwordx4 v130, s[92:93] sc1
	s_mov_b32 m0, s40
	s_nop 0
	global_load_lds_dwordx4 v134, s[92:93] sc1
	s_waitcnt vmcnt(8)
	s_waitcnt lgkmcnt(0)
	s_barrier
	s_waitcnt lgkmcnt(0)
	v_mfma_f32_16x16x32_bf16 v[58:61], v[152:155], v[192:195], v[58:61]
	v_mfma_f32_16x16x32_bf16 v[74:77], v[162:165], v[192:195], v[74:77]
	v_mfma_f32_16x16x32_bf16 v[30:33], v[152:155], v[204:207], v[30:33]
	v_mfma_f32_16x16x32_bf16 v[42:45], v[162:165], v[204:207], v[42:45]
	v_mfma_f32_16x16x32_bf16 v[10:13], v[152:155], v[212:215], v[10:13]
	v_mfma_f32_16x16x32_bf16 v[18:21], v[162:165], v[212:215], v[18:21]
	v_mfma_f32_16x16x32_bf16 v[2:5], v[152:155], v[220:223], v[2:5]
	v_mfma_f32_16x16x32_bf16 v[6:9], v[162:165], v[220:223], v[6:9]
	v_mfma_f32_16x16x32_bf16 v[58:61], v[156:159], v[200:203], v[58:61]
	v_mfma_f32_16x16x32_bf16 v[74:77], v[166:169], v[200:203], v[74:77]
	v_mfma_f32_16x16x32_bf16 v[30:33], v[156:159], v[208:211], v[30:33]
	v_mfma_f32_16x16x32_bf16 v[42:45], v[166:169], v[208:211], v[42:45]
	v_mfma_f32_16x16x32_bf16 v[10:13], v[156:159], v[216:219], v[10:13]
	v_mfma_f32_16x16x32_bf16 v[18:21], v[166:169], v[216:219], v[18:21]
	v_mfma_f32_16x16x32_bf16 v[2:5], v[156:159], v[224:227], v[2:5]
	v_mfma_f32_16x16x32_bf16 v[6:9], v[166:169], v[224:227], v[6:9]
	v_mfma_f32_16x16x32_bf16 v[106:109], v[170:173], v[192:195], v[106:109]
	v_mfma_f32_16x16x32_bf16 v[114:117], v[178:181], v[192:195], v[114:117]
	v_mfma_f32_16x16x32_bf16 v[82:85], v[170:173], v[204:207], v[82:85]
	v_mfma_f32_16x16x32_bf16 v[90:93], v[178:181], v[204:207], v[90:93]
	v_mfma_f32_16x16x32_bf16 v[50:53], v[170:173], v[212:215], v[50:53]
	v_mfma_f32_16x16x32_bf16 v[66:69], v[178:181], v[212:215], v[66:69]
	v_mfma_f32_16x16x32_bf16 v[26:29], v[170:173], v[220:223], v[26:29]
	v_mfma_f32_16x16x32_bf16 v[38:41], v[178:181], v[220:223], v[38:41]
	v_mfma_f32_16x16x32_bf16 v[106:109], v[174:177], v[200:203], v[106:109]
	v_mfma_f32_16x16x32_bf16 v[114:117], v[182:185], v[200:203], v[114:117]
	v_mfma_f32_16x16x32_bf16 v[82:85], v[174:177], v[208:211], v[82:85]
	v_mfma_f32_16x16x32_bf16 v[90:93], v[182:185], v[208:211], v[90:93]
	v_mfma_f32_16x16x32_bf16 v[50:53], v[174:177], v[216:219], v[50:53]
	v_mfma_f32_16x16x32_bf16 v[66:69], v[182:185], v[216:219], v[66:69]
	v_mfma_f32_16x16x32_bf16 v[26:29], v[174:177], v[224:227], v[26:29]
	v_mfma_f32_16x16x32_bf16 v[38:41], v[182:185], v[224:227], v[38:41]
	s_barrier
	v_add_u32_e32 v160, s49, v142
	ds_read_b128 v[152:155], v160
	ds_read_b128 v[156:159], v160 offset:1024
	ds_read_b128 v[162:165], v160 offset:2048
	ds_read_b128 v[166:169], v160 offset:3072
	v_add_u32_e32 v160, s50, v142
	ds_read_b128 v[170:173], v160
	ds_read_b128 v[174:177], v160 offset:1024
	ds_read_b128 v[178:181], v160 offset:2048
	ds_read_b128 v[182:185], v160 offset:3072
	s_add_u32 s70, s92, 0x4000
	s_addc_u32 s71, s93, 0
	s_mov_b32 m0, s41
	ds_read_b128 v[192:195], v150 offset:32768
	ds_read_b128 v[200:203], v150 offset:33792
	ds_read_b128 v[204:207], v150 offset:34816
	ds_read_b128 v[208:211], v150 offset:35840
	ds_read_b128 v[212:215], v150 offset:36864
	ds_read_b128 v[216:219], v150 offset:37888
	ds_read_b128 v[220:223], v150 offset:38912
	ds_read_b128 v[224:227], v150 offset:39936
	global_load_lds_dwordx4 v130, s[70:71] sc1
	s_mov_b32 m0, s42
	s_nop 0
	global_load_lds_dwordx4 v134, s[70:71] sc1
	s_waitcnt vmcnt(8)
	s_waitcnt lgkmcnt(0)
	s_barrier
	s_waitcnt lgkmcnt(0)
	v_mfma_f32_16x16x32_bf16 v[98:101], v[152:155], v[192:195], v[98:101]
	v_mfma_f32_16x16x32_bf16 v[102:105], v[162:165], v[192:195], v[102:105]
	v_mfma_f32_16x16x32_bf16 v[62:65], v[152:155], v[204:207], v[62:65]
	v_mfma_f32_16x16x32_bf16 v[78:81], v[162:165], v[204:207], v[78:81]
	v_mfma_f32_16x16x32_bf16 v[34:37], v[152:155], v[212:215], v[34:37]
	v_mfma_f32_16x16x32_bf16 v[46:49], v[162:165], v[212:215], v[46:49]
	v_mfma_f32_16x16x32_bf16 v[14:17], v[152:155], v[220:223], v[14:17]
	v_mfma_f32_16x16x32_bf16 v[22:25], v[162:165], v[220:223], v[22:25]
	v_mfma_f32_16x16x32_bf16 v[98:101], v[156:159], v[200:203], v[98:101]
	v_mfma_f32_16x16x32_bf16 v[102:105], v[166:169], v[200:203], v[102:105]
	v_mfma_f32_16x16x32_bf16 v[62:65], v[156:159], v[208:211], v[62:65]
	v_mfma_f32_16x16x32_bf16 v[78:81], v[166:169], v[208:211], v[78:81]
	v_mfma_f32_16x16x32_bf16 v[34:37], v[156:159], v[216:219], v[34:37]
	v_mfma_f32_16x16x32_bf16 v[46:49], v[166:169], v[216:219], v[46:49]
	v_mfma_f32_16x16x32_bf16 v[14:17], v[156:159], v[224:227], v[14:17]
	v_mfma_f32_16x16x32_bf16 v[22:25], v[166:169], v[224:227], v[22:25]
	v_mfma_f32_16x16x32_bf16 v[122:125], v[170:173], v[192:195], v[122:125]
	v_mfma_f32_16x16x32_bf16 v[126:129], v[178:181], v[192:195], v[126:129]
	v_mfma_f32_16x16x32_bf16 v[110:113], v[170:173], v[204:207], v[110:113]
	v_mfma_f32_16x16x32_bf16 v[118:121], v[178:181], v[204:207], v[118:121]
	v_mfma_f32_16x16x32_bf16 v[86:89], v[170:173], v[212:215], v[86:89]
	v_mfma_f32_16x16x32_bf16 v[94:97], v[178:181], v[212:215], v[94:97]
	v_mfma_f32_16x16x32_bf16 v[54:57], v[170:173], v[220:223], v[54:57]
	v_mfma_f32_16x16x32_bf16 v[70:73], v[178:181], v[220:223], v[70:73]
	v_mfma_f32_16x16x32_bf16 v[122:125], v[174:177], v[200:203], v[122:125]
	v_mfma_f32_16x16x32_bf16 v[126:129], v[182:185], v[200:203], v[126:129]
	v_mfma_f32_16x16x32_bf16 v[110:113], v[174:177], v[208:211], v[110:113]
	v_mfma_f32_16x16x32_bf16 v[118:121], v[182:185], v[208:211], v[118:121]
	v_mfma_f32_16x16x32_bf16 v[86:89], v[174:177], v[216:219], v[86:89]
	v_mfma_f32_16x16x32_bf16 v[94:97], v[182:185], v[216:219], v[94:97]
	v_mfma_f32_16x16x32_bf16 v[54:57], v[174:177], v[224:227], v[54:57]
	v_mfma_f32_16x16x32_bf16 v[70:73], v[182:185], v[224:227], v[70:73]
	s_barrier
	s_add_u32 s70, s90, 0x8000
	s_addc_u32 s71, s91, 0
	s_add_i32 s92, s49, s35
	s_mov_b32 m0, s92
	ds_read_b128 v[192:195], v150 offset:49152
	ds_read_b128 v[200:203], v150 offset:50176
	ds_read_b128 v[204:207], v150 offset:51200
	ds_read_b128 v[208:211], v150 offset:52224
	ds_read_b128 v[212:215], v150 offset:53248
	ds_read_b128 v[216:219], v150 offset:54272
	ds_read_b128 v[220:223], v150 offset:55296
	ds_read_b128 v[224:227], v150 offset:56320
	global_load_lds_dwordx4 v132, s[70:71] sc1
	s_add_i32 m0, s92, 0x2000
	s_nop 0
	global_load_lds_dwordx4 v136, s[70:71] sc1
	s_add_u32 s70, s90, 0xc000
	s_addc_u32 s71, s91, 0
	s_add_i32 s90, s50, s35
	s_mov_b32 m0, s90
	s_nop 0
	global_load_lds_dwordx4 v132, s[70:71] sc1
	s_add_i32 m0, s90, 0x2000
	s_nop 0
	global_load_lds_dwordx4 v136, s[70:71] sc1
	s_mov_b32 m0, s44
	s_nop 0
	global_load_lds_dwordx4 v130, s[82:83] sc1
	s_mov_b32 m0, s45
	s_nop 0
	global_load_lds_dwordx4 v134, s[82:83] sc1
	s_waitcnt vmcnt(8)
	s_waitcnt lgkmcnt(0)
	s_barrier
	s_waitcnt lgkmcnt(0)
	v_mfma_f32_16x16x32_bf16 v[58:61], v[152:155], v[192:195], v[58:61]
	v_mfma_f32_16x16x32_bf16 v[74:77], v[162:165], v[192:195], v[74:77]
	v_mfma_f32_16x16x32_bf16 v[30:33], v[152:155], v[204:207], v[30:33]
	v_mfma_f32_16x16x32_bf16 v[42:45], v[162:165], v[204:207], v[42:45]
	v_mfma_f32_16x16x32_bf16 v[10:13], v[152:155], v[212:215], v[10:13]
	v_mfma_f32_16x16x32_bf16 v[18:21], v[162:165], v[212:215], v[18:21]
	v_mfma_f32_16x16x32_bf16 v[2:5], v[152:155], v[220:223], v[2:5]
	v_mfma_f32_16x16x32_bf16 v[6:9], v[162:165], v[220:223], v[6:9]
	v_mfma_f32_16x16x32_bf16 v[58:61], v[156:159], v[200:203], v[58:61]
	v_mfma_f32_16x16x32_bf16 v[74:77], v[166:169], v[200:203], v[74:77]
	v_mfma_f32_16x16x32_bf16 v[30:33], v[156:159], v[208:211], v[30:33]
	v_mfma_f32_16x16x32_bf16 v[42:45], v[166:169], v[208:211], v[42:45]
	v_mfma_f32_16x16x32_bf16 v[10:13], v[156:159], v[216:219], v[10:13]
	v_mfma_f32_16x16x32_bf16 v[18:21], v[166:169], v[216:219], v[18:21]
	v_mfma_f32_16x16x32_bf16 v[2:5], v[156:159], v[224:227], v[2:5]
	v_mfma_f32_16x16x32_bf16 v[6:9], v[166:169], v[224:227], v[6:9]
	v_mfma_f32_16x16x32_bf16 v[106:109], v[170:173], v[192:195], v[106:109]
	v_mfma_f32_16x16x32_bf16 v[114:117], v[178:181], v[192:195], v[114:117]
	v_mfma_f32_16x16x32_bf16 v[82:85], v[170:173], v[204:207], v[82:85]
	v_mfma_f32_16x16x32_bf16 v[90:93], v[178:181], v[204:207], v[90:93]
	v_mfma_f32_16x16x32_bf16 v[50:53], v[170:173], v[212:215], v[50:53]
	v_mfma_f32_16x16x32_bf16 v[66:69], v[178:181], v[212:215], v[66:69]
	v_mfma_f32_16x16x32_bf16 v[26:29], v[170:173], v[220:223], v[26:29]
	v_mfma_f32_16x16x32_bf16 v[38:41], v[178:181], v[220:223], v[38:41]
	v_mfma_f32_16x16x32_bf16 v[106:109], v[174:177], v[200:203], v[106:109]
	v_mfma_f32_16x16x32_bf16 v[114:117], v[182:185], v[200:203], v[114:117]
	v_mfma_f32_16x16x32_bf16 v[82:85], v[174:177], v[208:211], v[82:85]
	v_mfma_f32_16x16x32_bf16 v[90:93], v[182:185], v[208:211], v[90:93]
	v_mfma_f32_16x16x32_bf16 v[50:53], v[174:177], v[216:219], v[50:53]
	v_mfma_f32_16x16x32_bf16 v[66:69], v[182:185], v[216:219], v[66:69]
	v_mfma_f32_16x16x32_bf16 v[26:29], v[174:177], v[224:227], v[26:29]
	v_mfma_f32_16x16x32_bf16 v[38:41], v[182:185], v[224:227], v[38:41]
	s_barrier
	s_add_i32 s94, s94, 2
	s_add_u32 s69, s69, 0x10000
	s_addc_u32 s77, s77, 0
	s_cmp_gt_u32 s94, 13
	s_mov_b64 s[70:71], s[78:79]
	s_cbranch_scc0 .LBB0_623
	s_and_b64 vcc, exec, s[8:9]
	s_cbranch_vccz .LBB0_626
	s_barrier

.LBB0_883:
	s_add_u32 s69, s30, 0x10000
	s_addc_u32 s80, s31, 0
	s_ashr_i32 s57, s56, 31
	v_readlane_b32 s64, v253, 0
	s_lshl_b64 s[30:31], s[56:57], 20
	v_readlane_b32 s66, v253, 2
	v_readlane_b32 s67, v253, 3
	s_add_u32 s62, s66, s30
	s_addc_u32 s63, s67, s31
	s_ashr_i32 s41, s40, 31
	s_lshl_b64 s[30:31], s[40:41], 19
	s_add_u32 s30, s28, s30
	v_readlane_b32 s65, v253, 1
	s_addc_u32 s31, s29, s31
	s_lshl_b32 s64, s10, 2
	s_ashr_i32 s19, s18, 31
	s_ashr_i32 s65, s64, 31
	s_lshl_b64 s[66:67], s[18:19], 19
	s_lshl_b64 s[64:65], s[64:65], 15
	s_add_u32 s19, s60, s64
	s_addc_u32 s41, s33, s65
	s_add_u32 s19, s19, s66
	s_addc_u32 s41, s41, s67
	s_add_u32 s66, s19, 0x10000
	s_addc_u32 s57, s41, 0
	s_and_b64 s[64:65], s[8:9], exec
	s_cselect_b32 s57, s63, s57
	s_cselect_b32 s81, s62, s66
	s_cselect_b32 s85, s31, s41
	s_cselect_b32 s86, s30, s19
	v_lshl_add_u64 v[144:145], s[38:39], 0, v[136:137]
	v_lshl_add_u64 v[146:147], s[38:39], 0, v[138:139]
	s_mov_b32 s87, -2
	s_mov_b64 s[64:65], 0
	s_add_u32 s19, s38, s64
	s_addc_u32 s41, s39, s65
	v_add_u32_e32 v168, s49, v151
	v_add_u32_e32 v184, s51, v151
	s_add_u32 s19, s19, 0x10000
	ds_read_b128 v[156:159], v168
	ds_read_b128 v[160:163], v168 offset:1024
	ds_read_b128 v[164:167], v168 offset:2048
	ds_read_b128 v[168:171], v168 offset:3072
	ds_read_b128 v[172:175], v184
	ds_read_b128 v[176:179], v184 offset:1024
	ds_read_b128 v[180:183], v184 offset:2048
	ds_read_b128 v[184:187], v184 offset:3072
	s_addc_u32 s41, s41, 0
	s_add_u32 s66, s69, s64
	s_addc_u32 s67, s80, s65
	s_cmp_eq_u32 s64, 0x70000
	s_cselect_b32 s78, s81, s19
	s_cselect_b32 s79, s57, s41
	s_cselect_b32 s70, s86, s66
	s_cselect_b32 s71, s85, s67
	s_add_u32 s66, s78, 0x8000
	s_addc_u32 s67, s79, 0
	s_add_i32 s19, s37, 0xc000
	v_lshl_add_u64 v[196:197], v[144:145], 0, s[64:65]
	s_mov_b32 m0, s19
	s_add_i32 s41, s37, 0xe000
	ds_read_b128 v[192:195], v154
	ds_read_b128 v[200:203], v154 offset:1024
	ds_read_b128 v[204:207], v154 offset:2048
	ds_read_b128 v[208:211], v154 offset:3072
	ds_read_b128 v[212:215], v154 offset:4096
	ds_read_b128 v[216:219], v154 offset:5120
	ds_read_b128 v[220:223], v154 offset:6144
	ds_read_b128 v[224:227], v154 offset:7168
	global_load_lds_dwordx4 v[196:197], off sc1
	v_lshl_add_u64 v[196:197], v[146:147], 0, s[64:65]
	s_mov_b32 m0, s41
	s_nop 0
	global_load_lds_dwordx4 v[196:197], off sc1
	s_waitcnt vmcnt(8)
	s_waitcnt lgkmcnt(0)
	s_barrier
	s_waitcnt lgkmcnt(0)
	v_mfma_f32_16x16x32_bf16 v[112:115], v[156:159], v[192:195], 0
	v_mfma_f32_16x16x32_bf16 v[116:119], v[164:167], v[192:195], 0
	v_mfma_f32_16x16x32_bf16 v[96:99], v[156:159], v[204:207], 0
	v_mfma_f32_16x16x32_bf16 v[100:103], v[164:167], v[204:207], 0
	v_mfma_f32_16x16x32_bf16 v[80:83], v[156:159], v[212:215], 0
	v_mfma_f32_16x16x32_bf16 v[84:87], v[164:167], v[212:215], 0
	v_mfma_f32_16x16x32_bf16 v[64:67], v[156:159], v[220:223], 0
	v_mfma_f32_16x16x32_bf16 v[68:71], v[164:167], v[220:223], 0
	v_mfma_f32_16x16x32_bf16 v[112:115], v[160:163], v[200:203], v[112:115]
	v_mfma_f32_16x16x32_bf16 v[116:119], v[168:171], v[200:203], v[116:119]
	v_mfma_f32_16x16x32_bf16 v[96:99], v[160:163], v[208:211], v[96:99]
	v_mfma_f32_16x16x32_bf16 v[100:103], v[168:171], v[208:211], v[100:103]
	v_mfma_f32_16x16x32_bf16 v[80:83], v[160:163], v[216:219], v[80:83]
	v_mfma_f32_16x16x32_bf16 v[84:87], v[168:171], v[216:219], v[84:87]
	v_mfma_f32_16x16x32_bf16 v[64:67], v[160:163], v[224:227], v[64:67]
	v_mfma_f32_16x16x32_bf16 v[68:71], v[168:171], v[224:227], v[68:71]
	v_mfma_f32_16x16x32_bf16 v[120:123], v[172:175], v[192:195], 0
	v_mfma_f32_16x16x32_bf16 v[124:127], v[180:183], v[192:195], 0
	v_mfma_f32_16x16x32_bf16 v[104:107], v[172:175], v[204:207], 0
	v_mfma_f32_16x16x32_bf16 v[108:111], v[180:183], v[204:207], 0
	v_mfma_f32_16x16x32_bf16 v[88:91], v[172:175], v[212:215], 0
	v_mfma_f32_16x16x32_bf16 v[92:95], v[180:183], v[212:215], 0
	v_mfma_f32_16x16x32_bf16 v[72:75], v[172:175], v[220:223], 0
	v_mfma_f32_16x16x32_bf16 v[76:79], v[180:183], v[220:223], 0
	v_mfma_f32_16x16x32_bf16 v[120:123], v[176:179], v[200:203], v[120:123]
	v_mfma_f32_16x16x32_bf16 v[124:127], v[184:187], v[200:203], v[124:127]
	v_mfma_f32_16x16x32_bf16 v[104:107], v[176:179], v[208:211], v[104:107]
	v_mfma_f32_16x16x32_bf16 v[108:111], v[184:187], v[208:211], v[108:111]
	v_mfma_f32_16x16x32_bf16 v[88:91], v[176:179], v[216:219], v[88:91]
	v_mfma_f32_16x16x32_bf16 v[92:95], v[184:187], v[216:219], v[92:95]
	v_mfma_f32_16x16x32_bf16 v[72:75], v[176:179], v[224:227], v[72:75]
	v_mfma_f32_16x16x32_bf16 v[76:79], v[184:187], v[224:227], v[76:79]
	s_barrier
	s_add_i32 s88, s49, s35
	s_mov_b32 m0, s88
	ds_read_b128 v[192:195], v154 offset:16384
	ds_read_b128 v[200:203], v154 offset:17408
	ds_read_b128 v[204:207], v154 offset:18432
	ds_read_b128 v[208:211], v154 offset:19456
	ds_read_b128 v[212:215], v154 offset:20480
	ds_read_b128 v[216:219], v154 offset:21504
	ds_read_b128 v[220:223], v154 offset:22528
	ds_read_b128 v[224:227], v154 offset:23552
	global_load_lds_dwordx4 v130, s[70:71] sc1
	s_add_i32 m0, s88, 0x2000
	s_add_u32 s88, s70, 0x4000
	s_addc_u32 s89, s71, 0
	s_add_i32 s90, s51, s35
	global_load_lds_dwordx4 v134, s[70:71] sc1
	s_mov_b32 m0, s90
	s_nop 0
	global_load_lds_dwordx4 v130, s[88:89] sc1
	s_add_i32 m0, s90, 0x2000
	s_nop 0
	global_load_lds_dwordx4 v134, s[88:89] sc1
	s_mov_b32 m0, s37
	s_nop 0
	global_load_lds_dwordx4 v128, s[78:79] sc1
	s_mov_b32 m0, s43
	s_nop 0
	global_load_lds_dwordx4 v132, s[78:79] sc1
	s_waitcnt vmcnt(8)
	s_waitcnt lgkmcnt(0)
	s_barrier
	s_waitcnt lgkmcnt(0)
	v_mfma_f32_16x16x32_bf16 v[48:51], v[156:159], v[192:195], 0
	v_mfma_f32_16x16x32_bf16 v[52:55], v[164:167], v[192:195], 0
	v_mfma_f32_16x16x32_bf16 v[32:35], v[156:159], v[204:207], 0
	v_mfma_f32_16x16x32_bf16 v[36:39], v[164:167], v[204:207], 0
	v_mfma_f32_16x16x32_bf16 v[16:19], v[156:159], v[212:215], 0
	v_mfma_f32_16x16x32_bf16 v[20:23], v[164:167], v[212:215], 0
	v_mfma_f32_16x16x32_bf16 v[0:3], v[156:159], v[220:223], 0
	v_mfma_f32_16x16x32_bf16 v[4:7], v[164:167], v[220:223], 0
	v_mfma_f32_16x16x32_bf16 v[48:51], v[160:163], v[200:203], v[48:51]
	v_mfma_f32_16x16x32_bf16 v[52:55], v[168:171], v[200:203], v[52:55]
	v_mfma_f32_16x16x32_bf16 v[32:35], v[160:163], v[208:211], v[32:35]
	v_mfma_f32_16x16x32_bf16 v[36:39], v[168:171], v[208:211], v[36:39]
	v_mfma_f32_16x16x32_bf16 v[16:19], v[160:163], v[216:219], v[16:19]
	v_mfma_f32_16x16x32_bf16 v[20:23], v[168:171], v[216:219], v[20:23]
	v_mfma_f32_16x16x32_bf16 v[0:3], v[160:163], v[224:227], v[0:3]
	v_mfma_f32_16x16x32_bf16 v[4:7], v[168:171], v[224:227], v[4:7]
	v_mfma_f32_16x16x32_bf16 v[56:59], v[172:175], v[192:195], 0
	v_mfma_f32_16x16x32_bf16 v[60:63], v[180:183], v[192:195], 0
	v_mfma_f32_16x16x32_bf16 v[40:43], v[172:175], v[204:207], 0
	v_mfma_f32_16x16x32_bf16 v[44:47], v[180:183], v[204:207], 0
	v_mfma_f32_16x16x32_bf16 v[24:27], v[172:175], v[212:215], 0
	v_mfma_f32_16x16x32_bf16 v[28:31], v[180:183], v[212:215], 0
	v_mfma_f32_16x16x32_bf16 v[8:11], v[172:175], v[220:223], 0
	v_mfma_f32_16x16x32_bf16 v[12:15], v[180:183], v[220:223], 0
	v_mfma_f32_16x16x32_bf16 v[56:59], v[176:179], v[200:203], v[56:59]
	v_mfma_f32_16x16x32_bf16 v[60:63], v[184:187], v[200:203], v[60:63]
	v_mfma_f32_16x16x32_bf16 v[40:43], v[176:179], v[208:211], v[40:43]
	v_mfma_f32_16x16x32_bf16 v[44:47], v[184:187], v[208:211], v[44:47]
	v_mfma_f32_16x16x32_bf16 v[24:27], v[176:179], v[216:219], v[24:27]
	v_mfma_f32_16x16x32_bf16 v[28:31], v[184:187], v[216:219], v[28:31]
	v_mfma_f32_16x16x32_bf16 v[8:11], v[176:179], v[224:227], v[8:11]
	v_mfma_f32_16x16x32_bf16 v[12:15], v[184:187], v[224:227], v[12:15]
	s_barrier
	v_add_u32_e32 v168, s54, v151
	v_add_u32_e32 v184, s55, v151
	ds_read_b128 v[156:159], v168
	ds_read_b128 v[160:163], v168 offset:1024
	ds_read_b128 v[164:167], v168 offset:2048
	ds_read_b128 v[168:171], v168 offset:3072
	ds_read_b128 v[172:175], v184
	ds_read_b128 v[176:179], v184 offset:1024
	ds_read_b128 v[180:183], v184 offset:2048
	ds_read_b128 v[184:187], v184 offset:3072
	s_add_u32 s78, s78, 0x4000
	s_addc_u32 s79, s79, 0
	s_mov_b32 m0, s44
	ds_read_b128 v[192:195], v154 offset:32768
	ds_read_b128 v[200:203], v154 offset:33792
	ds_read_b128 v[204:207], v154 offset:34816
	ds_read_b128 v[208:211], v154 offset:35840
	ds_read_b128 v[212:215], v154 offset:36864
	ds_read_b128 v[216:219], v154 offset:37888
	ds_read_b128 v[220:223], v154 offset:38912
	ds_read_b128 v[224:227], v154 offset:39936
	global_load_lds_dwordx4 v128, s[78:79] sc1
	s_mov_b32 m0, s45
	s_nop 0
	global_load_lds_dwordx4 v132, s[78:79] sc1
	s_waitcnt vmcnt(8)
	s_waitcnt lgkmcnt(0)
	s_barrier
	s_waitcnt lgkmcnt(0)
	v_mfma_f32_16x16x32_bf16 v[112:115], v[156:159], v[192:195], v[112:115]
	v_mfma_f32_16x16x32_bf16 v[116:119], v[164:167], v[192:195], v[116:119]
	v_mfma_f32_16x16x32_bf16 v[96:99], v[156:159], v[204:207], v[96:99]
	v_mfma_f32_16x16x32_bf16 v[100:103], v[164:167], v[204:207], v[100:103]
	v_mfma_f32_16x16x32_bf16 v[80:83], v[156:159], v[212:215], v[80:83]
	v_mfma_f32_16x16x32_bf16 v[84:87], v[164:167], v[212:215], v[84:87]
	v_mfma_f32_16x16x32_bf16 v[64:67], v[156:159], v[220:223], v[64:67]
	v_mfma_f32_16x16x32_bf16 v[68:71], v[164:167], v[220:223], v[68:71]
	v_mfma_f32_16x16x32_bf16 v[112:115], v[160:163], v[200:203], v[112:115]
	v_mfma_f32_16x16x32_bf16 v[116:119], v[168:171], v[200:203], v[116:119]
	v_mfma_f32_16x16x32_bf16 v[96:99], v[160:163], v[208:211], v[96:99]
	v_mfma_f32_16x16x32_bf16 v[100:103], v[168:171], v[208:211], v[100:103]
	v_mfma_f32_16x16x32_bf16 v[80:83], v[160:163], v[216:219], v[80:83]
	v_mfma_f32_16x16x32_bf16 v[84:87], v[168:171], v[216:219], v[84:87]
	v_mfma_f32_16x16x32_bf16 v[64:67], v[160:163], v[224:227], v[64:67]
	v_mfma_f32_16x16x32_bf16 v[68:71], v[168:171], v[224:227], v[68:71]
	v_mfma_f32_16x16x32_bf16 v[120:123], v[172:175], v[192:195], v[120:123]
	v_mfma_f32_16x16x32_bf16 v[124:127], v[180:183], v[192:195], v[124:127]
	v_mfma_f32_16x16x32_bf16 v[104:107], v[172:175], v[204:207], v[104:107]
	v_mfma_f32_16x16x32_bf16 v[108:111], v[180:183], v[204:207], v[108:111]
	v_mfma_f32_16x16x32_bf16 v[88:91], v[172:175], v[212:215], v[88:91]
	v_mfma_f32_16x16x32_bf16 v[92:95], v[180:183], v[212:215], v[92:95]
	v_mfma_f32_16x16x32_bf16 v[72:75], v[172:175], v[220:223], v[72:75]
	v_mfma_f32_16x16x32_bf16 v[76:79], v[180:183], v[220:223], v[76:79]
	v_mfma_f32_16x16x32_bf16 v[120:123], v[176:179], v[200:203], v[120:123]
	v_mfma_f32_16x16x32_bf16 v[124:127], v[184:187], v[200:203], v[124:127]
	v_mfma_f32_16x16x32_bf16 v[104:107], v[176:179], v[208:211], v[104:107]
	v_mfma_f32_16x16x32_bf16 v[108:111], v[184:187], v[208:211], v[108:111]
	v_mfma_f32_16x16x32_bf16 v[88:91], v[176:179], v[216:219], v[88:91]
	v_mfma_f32_16x16x32_bf16 v[92:95], v[184:187], v[216:219], v[92:95]
	v_mfma_f32_16x16x32_bf16 v[72:75], v[176:179], v[224:227], v[72:75]
	v_mfma_f32_16x16x32_bf16 v[76:79], v[184:187], v[224:227], v[76:79]
	s_barrier
	s_add_u32 s78, s70, 0x8000
	s_addc_u32 s79, s71, 0
	s_add_i32 s88, s54, s35
	s_mov_b32 m0, s88
	ds_read_b128 v[192:195], v154 offset:49152
	ds_read_b128 v[200:203], v154 offset:50176
	ds_read_b128 v[204:207], v154 offset:51200
	ds_read_b128 v[208:211], v154 offset:52224
	ds_read_b128 v[212:215], v154 offset:53248
	ds_read_b128 v[216:219], v154 offset:54272
	ds_read_b128 v[220:223], v154 offset:55296
	ds_read_b128 v[224:227], v154 offset:56320
	global_load_lds_dwordx4 v130, s[78:79] sc1
	s_add_i32 m0, s88, 0x2000
	s_add_u32 s70, s70, 0xc000
	global_load_lds_dwordx4 v134, s[78:79] sc1
	s_addc_u32 s71, s71, 0
	s_add_i32 s78, s55, s35
	s_mov_b32 m0, s78
	s_nop 0
	global_load_lds_dwordx4 v130, s[70:71] sc1
	s_add_i32 m0, s78, 0x2000
	s_nop 0
	global_load_lds_dwordx4 v134, s[70:71] sc1
	s_mov_b32 m0, s47
	s_nop 0
	global_load_lds_dwordx4 v128, s[66:67] sc1
	s_mov_b32 m0, s48
	s_nop 0
	global_load_lds_dwordx4 v132, s[66:67] sc1
	s_waitcnt vmcnt(8)
	s_waitcnt lgkmcnt(0)
	s_barrier
	s_waitcnt lgkmcnt(0)
	v_mfma_f32_16x16x32_bf16 v[48:51], v[156:159], v[192:195], v[48:51]
	v_mfma_f32_16x16x32_bf16 v[52:55], v[164:167], v[192:195], v[52:55]
	v_mfma_f32_16x16x32_bf16 v[32:35], v[156:159], v[204:207], v[32:35]
	v_mfma_f32_16x16x32_bf16 v[36:39], v[164:167], v[204:207], v[36:39]
	v_mfma_f32_16x16x32_bf16 v[16:19], v[156:159], v[212:215], v[16:19]
	v_mfma_f32_16x16x32_bf16 v[20:23], v[164:167], v[212:215], v[20:23]
	v_mfma_f32_16x16x32_bf16 v[0:3], v[156:159], v[220:223], v[0:3]
	v_mfma_f32_16x16x32_bf16 v[4:7], v[164:167], v[220:223], v[4:7]
	v_mfma_f32_16x16x32_bf16 v[48:51], v[160:163], v[200:203], v[48:51]
	v_mfma_f32_16x16x32_bf16 v[52:55], v[168:171], v[200:203], v[52:55]
	v_mfma_f32_16x16x32_bf16 v[32:35], v[160:163], v[208:211], v[32:35]
	v_mfma_f32_16x16x32_bf16 v[36:39], v[168:171], v[208:211], v[36:39]
	v_mfma_f32_16x16x32_bf16 v[16:19], v[160:163], v[216:219], v[16:19]
	v_mfma_f32_16x16x32_bf16 v[20:23], v[168:171], v[216:219], v[20:23]
	v_mfma_f32_16x16x32_bf16 v[0:3], v[160:163], v[224:227], v[0:3]
	v_mfma_f32_16x16x32_bf16 v[4:7], v[168:171], v[224:227], v[4:7]
	v_mfma_f32_16x16x32_bf16 v[56:59], v[172:175], v[192:195], v[56:59]
	v_mfma_f32_16x16x32_bf16 v[60:63], v[180:183], v[192:195], v[60:63]
	v_mfma_f32_16x16x32_bf16 v[40:43], v[172:175], v[204:207], v[40:43]
	v_mfma_f32_16x16x32_bf16 v[44:47], v[180:183], v[204:207], v[44:47]
	v_mfma_f32_16x16x32_bf16 v[24:27], v[172:175], v[212:215], v[24:27]
	v_mfma_f32_16x16x32_bf16 v[28:31], v[180:183], v[212:215], v[28:31]
	v_mfma_f32_16x16x32_bf16 v[8:11], v[172:175], v[220:223], v[8:11]
	v_mfma_f32_16x16x32_bf16 v[12:15], v[180:183], v[220:223], v[12:15]
	v_mfma_f32_16x16x32_bf16 v[56:59], v[176:179], v[200:203], v[56:59]
	v_mfma_f32_16x16x32_bf16 v[60:63], v[184:187], v[200:203], v[60:63]
	v_mfma_f32_16x16x32_bf16 v[40:43], v[176:179], v[208:211], v[40:43]
	v_mfma_f32_16x16x32_bf16 v[44:47], v[184:187], v[208:211], v[44:47]
	v_mfma_f32_16x16x32_bf16 v[24:27], v[176:179], v[216:219], v[24:27]
	v_mfma_f32_16x16x32_bf16 v[28:31], v[184:187], v[216:219], v[28:31]
	v_mfma_f32_16x16x32_bf16 v[8:11], v[176:179], v[224:227], v[8:11]
	v_mfma_f32_16x16x32_bf16 v[12:15], v[184:187], v[224:227], v[12:15]
	s_barrier
	s_add_i32 s87, s87, 2
	s_add_u32 s64, s64, 0x10000
	s_addc_u32 s65, s65, 0
	s_cmp_gt_u32 s87, 13
.LBB0_884:
	s_add_u32 s19, s38, s64
	s_addc_u32 s41, s39, s65
	v_add_u32_e32 v168, s49, v151
	v_add_u32_e32 v184, s51, v151
	s_add_u32 s19, s19, 0x10000
	ds_read_b128 v[156:159], v168
	ds_read_b128 v[160:163], v168 offset:1024
	ds_read_b128 v[164:167], v168 offset:2048
	ds_read_b128 v[168:171], v168 offset:3072
	ds_read_b128 v[172:175], v184
	ds_read_b128 v[176:179], v184 offset:1024
	ds_read_b128 v[180:183], v184 offset:2048
	ds_read_b128 v[184:187], v184 offset:3072
	s_addc_u32 s41, s41, 0
	s_add_u32 s66, s69, s64
	s_addc_u32 s67, s80, s65
	s_cmp_eq_u32 s64, 0x70000
	s_cselect_b32 s78, s81, s19
	s_cselect_b32 s79, s57, s41
	s_cselect_b32 s70, s86, s66
	s_cselect_b32 s71, s85, s67
	s_add_u32 s66, s78, 0x8000
	s_addc_u32 s67, s79, 0
	s_add_i32 s19, s37, 0xc000
	v_lshl_add_u64 v[196:197], v[144:145], 0, s[64:65]
	s_mov_b32 m0, s19
	s_add_i32 s41, s37, 0xe000
	ds_read_b128 v[192:195], v154
	ds_read_b128 v[200:203], v154 offset:1024
	ds_read_b128 v[204:207], v154 offset:2048
	ds_read_b128 v[208:211], v154 offset:3072
	ds_read_b128 v[212:215], v154 offset:4096
	ds_read_b128 v[216:219], v154 offset:5120
	ds_read_b128 v[220:223], v154 offset:6144
	ds_read_b128 v[224:227], v154 offset:7168
	global_load_lds_dwordx4 v[196:197], off sc1
	v_lshl_add_u64 v[196:197], v[146:147], 0, s[64:65]
	s_mov_b32 m0, s41
	s_nop 0
	global_load_lds_dwordx4 v[196:197], off sc1
	s_waitcnt vmcnt(8)
	s_waitcnt lgkmcnt(0)
	s_barrier
	s_waitcnt lgkmcnt(0)
	v_mfma_f32_16x16x32_bf16 v[112:115], v[156:159], v[192:195], v[112:115]
	v_mfma_f32_16x16x32_bf16 v[116:119], v[164:167], v[192:195], v[116:119]
	v_mfma_f32_16x16x32_bf16 v[96:99], v[156:159], v[204:207], v[96:99]
	v_mfma_f32_16x16x32_bf16 v[100:103], v[164:167], v[204:207], v[100:103]
	v_mfma_f32_16x16x32_bf16 v[80:83], v[156:159], v[212:215], v[80:83]
	v_mfma_f32_16x16x32_bf16 v[84:87], v[164:167], v[212:215], v[84:87]
	v_mfma_f32_16x16x32_bf16 v[64:67], v[156:159], v[220:223], v[64:67]
	v_mfma_f32_16x16x32_bf16 v[68:71], v[164:167], v[220:223], v[68:71]
	v_mfma_f32_16x16x32_bf16 v[112:115], v[160:163], v[200:203], v[112:115]
	v_mfma_f32_16x16x32_bf16 v[116:119], v[168:171], v[200:203], v[116:119]
	v_mfma_f32_16x16x32_bf16 v[96:99], v[160:163], v[208:211], v[96:99]
	v_mfma_f32_16x16x32_bf16 v[100:103], v[168:171], v[208:211], v[100:103]
	v_mfma_f32_16x16x32_bf16 v[80:83], v[160:163], v[216:219], v[80:83]
	v_mfma_f32_16x16x32_bf16 v[84:87], v[168:171], v[216:219], v[84:87]
	v_mfma_f32_16x16x32_bf16 v[64:67], v[160:163], v[224:227], v[64:67]
	v_mfma_f32_16x16x32_bf16 v[68:71], v[168:171], v[224:227], v[68:71]
	v_mfma_f32_16x16x32_bf16 v[120:123], v[172:175], v[192:195], v[120:123]
	v_mfma_f32_16x16x32_bf16 v[124:127], v[180:183], v[192:195], v[124:127]
	v_mfma_f32_16x16x32_bf16 v[104:107], v[172:175], v[204:207], v[104:107]
	v_mfma_f32_16x16x32_bf16 v[108:111], v[180:183], v[204:207], v[108:111]
	v_mfma_f32_16x16x32_bf16 v[88:91], v[172:175], v[212:215], v[88:91]
	v_mfma_f32_16x16x32_bf16 v[92:95], v[180:183], v[212:215], v[92:95]
	v_mfma_f32_16x16x32_bf16 v[72:75], v[172:175], v[220:223], v[72:75]
	v_mfma_f32_16x16x32_bf16 v[76:79], v[180:183], v[220:223], v[76:79]
	v_mfma_f32_16x16x32_bf16 v[120:123], v[176:179], v[200:203], v[120:123]
	v_mfma_f32_16x16x32_bf16 v[124:127], v[184:187], v[200:203], v[124:127]
	v_mfma_f32_16x16x32_bf16 v[104:107], v[176:179], v[208:211], v[104:107]
	v_mfma_f32_16x16x32_bf16 v[108:111], v[184:187], v[208:211], v[108:111]
	v_mfma_f32_16x16x32_bf16 v[88:91], v[176:179], v[216:219], v[88:91]
	v_mfma_f32_16x16x32_bf16 v[92:95], v[184:187], v[216:219], v[92:95]
	v_mfma_f32_16x16x32_bf16 v[72:75], v[176:179], v[224:227], v[72:75]
	v_mfma_f32_16x16x32_bf16 v[76:79], v[184:187], v[224:227], v[76:79]
	s_barrier
	s_add_i32 s88, s49, s35
	s_mov_b32 m0, s88
	ds_read_b128 v[192:195], v154 offset:16384
	ds_read_b128 v[200:203], v154 offset:17408
	ds_read_b128 v[204:207], v154 offset:18432
	ds_read_b128 v[208:211], v154 offset:19456
	ds_read_b128 v[212:215], v154 offset:20480
	ds_read_b128 v[216:219], v154 offset:21504
	ds_read_b128 v[220:223], v154 offset:22528
	ds_read_b128 v[224:227], v154 offset:23552
	global_load_lds_dwordx4 v130, s[70:71] sc1
	s_add_i32 m0, s88, 0x2000
	s_add_u32 s88, s70, 0x4000
	s_addc_u32 s89, s71, 0
	s_add_i32 s90, s51, s35
	global_load_lds_dwordx4 v134, s[70:71] sc1
	s_mov_b32 m0, s90
	s_nop 0
	global_load_lds_dwordx4 v130, s[88:89] sc1
	s_add_i32 m0, s90, 0x2000
	s_nop 0
	global_load_lds_dwordx4 v134, s[88:89] sc1
	s_mov_b32 m0, s37
	s_nop 0
	global_load_lds_dwordx4 v128, s[78:79] sc1
	s_mov_b32 m0, s43
	s_nop 0
	global_load_lds_dwordx4 v132, s[78:79] sc1
	s_waitcnt vmcnt(8)
	s_waitcnt lgkmcnt(0)
	s_barrier
	s_waitcnt lgkmcnt(0)
	v_mfma_f32_16x16x32_bf16 v[48:51], v[156:159], v[192:195], v[48:51]
	v_mfma_f32_16x16x32_bf16 v[52:55], v[164:167], v[192:195], v[52:55]
	v_mfma_f32_16x16x32_bf16 v[32:35], v[156:159], v[204:207], v[32:35]
	v_mfma_f32_16x16x32_bf16 v[36:39], v[164:167], v[204:207], v[36:39]
	v_mfma_f32_16x16x32_bf16 v[16:19], v[156:159], v[212:215], v[16:19]
	v_mfma_f32_16x16x32_bf16 v[20:23], v[164:167], v[212:215], v[20:23]
	v_mfma_f32_16x16x32_bf16 v[0:3], v[156:159], v[220:223], v[0:3]
	v_mfma_f32_16x16x32_bf16 v[4:7], v[164:167], v[220:223], v[4:7]
	v_mfma_f32_16x16x32_bf16 v[48:51], v[160:163], v[200:203], v[48:51]
	v_mfma_f32_16x16x32_bf16 v[52:55], v[168:171], v[200:203], v[52:55]
	v_mfma_f32_16x16x32_bf16 v[32:35], v[160:163], v[208:211], v[32:35]
	v_mfma_f32_16x16x32_bf16 v[36:39], v[168:171], v[208:211], v[36:39]
	v_mfma_f32_16x16x32_bf16 v[16:19], v[160:163], v[216:219], v[16:19]
	v_mfma_f32_16x16x32_bf16 v[20:23], v[168:171], v[216:219], v[20:23]
	v_mfma_f32_16x16x32_bf16 v[0:3], v[160:163], v[224:227], v[0:3]
	v_mfma_f32_16x16x32_bf16 v[4:7], v[168:171], v[224:227], v[4:7]
	v_mfma_f32_16x16x32_bf16 v[56:59], v[172:175], v[192:195], v[56:59]
	v_mfma_f32_16x16x32_bf16 v[60:63], v[180:183], v[192:195], v[60:63]
	v_mfma_f32_16x16x32_bf16 v[40:43], v[172:175], v[204:207], v[40:43]
	v_mfma_f32_16x16x32_bf16 v[44:47], v[180:183], v[204:207], v[44:47]
	v_mfma_f32_16x16x32_bf16 v[24:27], v[172:175], v[212:215], v[24:27]
	v_mfma_f32_16x16x32_bf16 v[28:31], v[180:183], v[212:215], v[28:31]
	v_mfma_f32_16x16x32_bf16 v[8:11], v[172:175], v[220:223], v[8:11]
	v_mfma_f32_16x16x32_bf16 v[12:15], v[180:183], v[220:223], v[12:15]
	v_mfma_f32_16x16x32_bf16 v[56:59], v[176:179], v[200:203], v[56:59]
	v_mfma_f32_16x16x32_bf16 v[60:63], v[184:187], v[200:203], v[60:63]
	v_mfma_f32_16x16x32_bf16 v[40:43], v[176:179], v[208:211], v[40:43]
	v_mfma_f32_16x16x32_bf16 v[44:47], v[184:187], v[208:211], v[44:47]
	v_mfma_f32_16x16x32_bf16 v[24:27], v[176:179], v[216:219], v[24:27]
	v_mfma_f32_16x16x32_bf16 v[28:31], v[184:187], v[216:219], v[28:31]
	v_mfma_f32_16x16x32_bf16 v[8:11], v[176:179], v[224:227], v[8:11]
	v_mfma_f32_16x16x32_bf16 v[12:15], v[184:187], v[224:227], v[12:15]
	s_barrier
	v_add_u32_e32 v168, s54, v151
	v_add_u32_e32 v184, s55, v151
	ds_read_b128 v[156:159], v168
	ds_read_b128 v[160:163], v168 offset:1024
	ds_read_b128 v[164:167], v168 offset:2048
	ds_read_b128 v[168:171], v168 offset:3072
	ds_read_b128 v[172:175], v184
	ds_read_b128 v[176:179], v184 offset:1024
	ds_read_b128 v[180:183], v184 offset:2048
	ds_read_b128 v[184:187], v184 offset:3072
	s_add_u32 s78, s78, 0x4000
	s_addc_u32 s79, s79, 0
	s_mov_b32 m0, s44
	ds_read_b128 v[192:195], v154 offset:32768
	ds_read_b128 v[200:203], v154 offset:33792
	ds_read_b128 v[204:207], v154 offset:34816
	ds_read_b128 v[208:211], v154 offset:35840
	ds_read_b128 v[212:215], v154 offset:36864
	ds_read_b128 v[216:219], v154 offset:37888
	ds_read_b128 v[220:223], v154 offset:38912
	ds_read_b128 v[224:227], v154 offset:39936
	global_load_lds_dwordx4 v128, s[78:79] sc1
	s_mov_b32 m0, s45
	s_nop 0
	global_load_lds_dwordx4 v132, s[78:79] sc1
	s_waitcnt vmcnt(8)
	s_waitcnt lgkmcnt(0)
	s_barrier
	s_waitcnt lgkmcnt(0)
	v_mfma_f32_16x16x32_bf16 v[112:115], v[156:159], v[192:195], v[112:115]
	v_mfma_f32_16x16x32_bf16 v[116:119], v[164:167], v[192:195], v[116:119]
	v_mfma_f32_16x16x32_bf16 v[96:99], v[156:159], v[204:207], v[96:99]
	v_mfma_f32_16x16x32_bf16 v[100:103], v[164:167], v[204:207], v[100:103]
	v_mfma_f32_16x16x32_bf16 v[80:83], v[156:159], v[212:215], v[80:83]
	v_mfma_f32_16x16x32_bf16 v[84:87], v[164:167], v[212:215], v[84:87]
	v_mfma_f32_16x16x32_bf16 v[64:67], v[156:159], v[220:223], v[64:67]
	v_mfma_f32_16x16x32_bf16 v[68:71], v[164:167], v[220:223], v[68:71]
	v_mfma_f32_16x16x32_bf16 v[112:115], v[160:163], v[200:203], v[112:115]
	v_mfma_f32_16x16x32_bf16 v[116:119], v[168:171], v[200:203], v[116:119]
	v_mfma_f32_16x16x32_bf16 v[96:99], v[160:163], v[208:211], v[96:99]
	v_mfma_f32_16x16x32_bf16 v[100:103], v[168:171], v[208:211], v[100:103]
	v_mfma_f32_16x16x32_bf16 v[80:83], v[160:163], v[216:219], v[80:83]
	v_mfma_f32_16x16x32_bf16 v[84:87], v[168:171], v[216:219], v[84:87]
	v_mfma_f32_16x16x32_bf16 v[64:67], v[160:163], v[224:227], v[64:67]
	v_mfma_f32_16x16x32_bf16 v[68:71], v[168:171], v[224:227], v[68:71]
	v_mfma_f32_16x16x32_bf16 v[120:123], v[172:175], v[192:195], v[120:123]
	v_mfma_f32_16x16x32_bf16 v[124:127], v[180:183], v[192:195], v[124:127]
	v_mfma_f32_16x16x32_bf16 v[104:107], v[172:175], v[204:207], v[104:107]
	v_mfma_f32_16x16x32_bf16 v[108:111], v[180:183], v[204:207], v[108:111]
	v_mfma_f32_16x16x32_bf16 v[88:91], v[172:175], v[212:215], v[88:91]
	v_mfma_f32_16x16x32_bf16 v[92:95], v[180:183], v[212:215], v[92:95]
	v_mfma_f32_16x16x32_bf16 v[72:75], v[172:175], v[220:223], v[72:75]
	v_mfma_f32_16x16x32_bf16 v[76:79], v[180:183], v[220:223], v[76:79]
	v_mfma_f32_16x16x32_bf16 v[120:123], v[176:179], v[200:203], v[120:123]
	v_mfma_f32_16x16x32_bf16 v[124:127], v[184:187], v[200:203], v[124:127]
	v_mfma_f32_16x16x32_bf16 v[104:107], v[176:179], v[208:211], v[104:107]
	v_mfma_f32_16x16x32_bf16 v[108:111], v[184:187], v[208:211], v[108:111]
	v_mfma_f32_16x16x32_bf16 v[88:91], v[176:179], v[216:219], v[88:91]
	v_mfma_f32_16x16x32_bf16 v[92:95], v[184:187], v[216:219], v[92:95]
	v_mfma_f32_16x16x32_bf16 v[72:75], v[176:179], v[224:227], v[72:75]
	v_mfma_f32_16x16x32_bf16 v[76:79], v[184:187], v[224:227], v[76:79]
	s_barrier
	s_add_u32 s78, s70, 0x8000
	s_addc_u32 s79, s71, 0
	s_add_i32 s88, s54, s35
	s_mov_b32 m0, s88
	ds_read_b128 v[192:195], v154 offset:49152
	ds_read_b128 v[200:203], v154 offset:50176
	ds_read_b128 v[204:207], v154 offset:51200
	ds_read_b128 v[208:211], v154 offset:52224
	ds_read_b128 v[212:215], v154 offset:53248
	ds_read_b128 v[216:219], v154 offset:54272
	ds_read_b128 v[220:223], v154 offset:55296
	ds_read_b128 v[224:227], v154 offset:56320
	global_load_lds_dwordx4 v130, s[78:79] sc1
	s_add_i32 m0, s88, 0x2000
	s_add_u32 s70, s70, 0xc000
	global_load_lds_dwordx4 v134, s[78:79] sc1
	s_addc_u32 s71, s71, 0
	s_add_i32 s78, s55, s35
	s_mov_b32 m0, s78
	s_nop 0
	global_load_lds_dwordx4 v130, s[70:71] sc1
	s_add_i32 m0, s78, 0x2000
	s_nop 0
	global_load_lds_dwordx4 v134, s[70:71] sc1
	s_mov_b32 m0, s47
	s_nop 0
	global_load_lds_dwordx4 v128, s[66:67] sc1
	s_mov_b32 m0, s48
	s_nop 0
	global_load_lds_dwordx4 v132, s[66:67] sc1
	s_waitcnt vmcnt(8)
	s_waitcnt lgkmcnt(0)
	s_barrier
	s_waitcnt lgkmcnt(0)
	v_mfma_f32_16x16x32_bf16 v[48:51], v[156:159], v[192:195], v[48:51]
	v_mfma_f32_16x16x32_bf16 v[52:55], v[164:167], v[192:195], v[52:55]
	v_mfma_f32_16x16x32_bf16 v[32:35], v[156:159], v[204:207], v[32:35]
	v_mfma_f32_16x16x32_bf16 v[36:39], v[164:167], v[204:207], v[36:39]
	v_mfma_f32_16x16x32_bf16 v[16:19], v[156:159], v[212:215], v[16:19]
	v_mfma_f32_16x16x32_bf16 v[20:23], v[164:167], v[212:215], v[20:23]
	v_mfma_f32_16x16x32_bf16 v[0:3], v[156:159], v[220:223], v[0:3]
	v_mfma_f32_16x16x32_bf16 v[4:7], v[164:167], v[220:223], v[4:7]
	v_mfma_f32_16x16x32_bf16 v[48:51], v[160:163], v[200:203], v[48:51]
	v_mfma_f32_16x16x32_bf16 v[52:55], v[168:171], v[200:203], v[52:55]
	v_mfma_f32_16x16x32_bf16 v[32:35], v[160:163], v[208:211], v[32:35]
	v_mfma_f32_16x16x32_bf16 v[36:39], v[168:171], v[208:211], v[36:39]
	v_mfma_f32_16x16x32_bf16 v[16:19], v[160:163], v[216:219], v[16:19]
	v_mfma_f32_16x16x32_bf16 v[20:23], v[168:171], v[216:219], v[20:23]
	v_mfma_f32_16x16x32_bf16 v[0:3], v[160:163], v[224:227], v[0:3]
	v_mfma_f32_16x16x32_bf16 v[4:7], v[168:171], v[224:227], v[4:7]
	v_mfma_f32_16x16x32_bf16 v[56:59], v[172:175], v[192:195], v[56:59]
	v_mfma_f32_16x16x32_bf16 v[60:63], v[180:183], v[192:195], v[60:63]
	v_mfma_f32_16x16x32_bf16 v[40:43], v[172:175], v[204:207], v[40:43]
	v_mfma_f32_16x16x32_bf16 v[44:47], v[180:183], v[204:207], v[44:47]
	v_mfma_f32_16x16x32_bf16 v[24:27], v[172:175], v[212:215], v[24:27]
	v_mfma_f32_16x16x32_bf16 v[28:31], v[180:183], v[212:215], v[28:31]
	v_mfma_f32_16x16x32_bf16 v[8:11], v[172:175], v[220:223], v[8:11]
	v_mfma_f32_16x16x32_bf16 v[12:15], v[180:183], v[220:223], v[12:15]
	v_mfma_f32_16x16x32_bf16 v[56:59], v[176:179], v[200:203], v[56:59]
	v_mfma_f32_16x16x32_bf16 v[60:63], v[184:187], v[200:203], v[60:63]
	v_mfma_f32_16x16x32_bf16 v[40:43], v[176:179], v[208:211], v[40:43]
	v_mfma_f32_16x16x32_bf16 v[44:47], v[184:187], v[208:211], v[44:47]
	v_mfma_f32_16x16x32_bf16 v[24:27], v[176:179], v[216:219], v[24:27]
	v_mfma_f32_16x16x32_bf16 v[28:31], v[184:187], v[216:219], v[28:31]
	v_mfma_f32_16x16x32_bf16 v[8:11], v[176:179], v[224:227], v[8:11]
	v_mfma_f32_16x16x32_bf16 v[12:15], v[184:187], v[224:227], v[12:15]
	s_barrier
	s_add_i32 s87, s87, 2
	s_add_u32 s64, s64, 0x10000
	s_addc_u32 s65, s65, 0
	s_cmp_gt_u32 s87, 13
	s_cbranch_scc0 .LBB0_884
	s_add_u32 s64, s69, 0xffff0000
	s_addc_u32 s65, s80, -1
	s_andn2_b64 vcc, exec, s[8:9]
	s_cbranch_vccz .LBB0_876
	s_mov_b64 s[30:31], s[64:65]
	s_andn2_b64 vcc, exec, s[6:7]
	s_cbranch_vccnz .LBB0_877

.LBB0_975:
	s_add_u32 s55, s64, 0x10000
	s_addc_u32 s69, s65, 0
	s_ashr_i32 s41, s40, 31
	s_lshl_b64 s[56:57], s[40:41], 19
	s_add_u32 s62, s60, s56
	s_addc_u32 s63, s33, s57
	s_and_b64 s[56:57], s[8:9], exec
	s_cselect_b32 s41, s63, s19
	s_cselect_b32 s80, s62, s18
	s_ashr_i32 s39, s38, 31
	s_lshl_b64 s[56:57], s[38:39], 19
	s_add_u32 s56, s30, s56
	s_addc_u32 s57, s31, s57
	s_and_b64 s[66:67], s[8:9], exec
	s_cselect_b32 s39, s57, s65
	s_cselect_b32 s81, s56, s64
	v_lshl_add_u64 v[144:145], s[18:19], 0, v[136:137]
	v_lshl_add_u64 v[146:147], s[18:19], 0, v[138:139]
	s_mov_b32 s85, -2
	s_mov_b64 s[64:65], 0
	s_add_u32 s66, s18, s64
	v_add_u32_e32 v151, s48, v149
	s_addc_u32 s67, s19, s65
	ds_read_b128 v[152:155], v151
	ds_read_b128 v[156:159], v151 offset:1024
	ds_read_b128 v[160:163], v151 offset:2048
	ds_read_b128 v[164:167], v151 offset:3072
	v_add_u32_e32 v151, s49, v149
	s_add_u32 s66, s66, 0x10000
	ds_read_b128 v[168:171], v151
	ds_read_b128 v[172:175], v151 offset:1024
	ds_read_b128 v[176:179], v151 offset:2048
	ds_read_b128 v[180:183], v151 offset:3072
	s_addc_u32 s67, s67, 0
	s_add_u32 s70, s55, s64
	s_addc_u32 s71, s69, s65
	s_cmp_eq_u32 s64, 0x70000
	s_cselect_b32 s78, s80, s66
	s_cselect_b32 s79, s41, s67
	s_cselect_b32 s70, s81, s70
	s_cselect_b32 s71, s39, s71
	s_add_u32 s66, s78, 0x8000
	s_addc_u32 s67, s79, 0
	v_lshl_add_u64 v[196:197], v[144:145], 0, s[64:65]
	s_add_i32 m0, s11, 0xc000
	ds_read_b128 v[184:187], v150
	ds_read_b128 v[192:195], v150 offset:1024
	ds_read_b128 v[200:203], v150 offset:2048
	ds_read_b128 v[204:207], v150 offset:3072
	ds_read_b128 v[208:211], v150 offset:4096
	ds_read_b128 v[212:215], v150 offset:5120
	ds_read_b128 v[216:219], v150 offset:6144
	ds_read_b128 v[220:223], v150 offset:7168
	global_load_lds_dwordx4 v[196:197], off sc1
	v_lshl_add_u64 v[196:197], v[146:147], 0, s[64:65]
	s_add_i32 m0, s11, 0xe000
	s_nop 0
	global_load_lds_dwordx4 v[196:197], off sc1
	s_waitcnt vmcnt(8)
	s_waitcnt lgkmcnt(0)
	s_barrier
	s_waitcnt lgkmcnt(0)
	v_mfma_f32_16x16x32_bf16 v[104:107], v[152:155], v[184:187], 0
	v_mfma_f32_16x16x32_bf16 v[108:111], v[160:163], v[184:187], 0
	v_mfma_f32_16x16x32_bf16 v[84:87], v[152:155], v[200:203], 0
	v_mfma_f32_16x16x32_bf16 v[92:95], v[160:163], v[200:203], 0
	v_mfma_f32_16x16x32_bf16 v[72:75], v[152:155], v[208:211], 0
	v_mfma_f32_16x16x32_bf16 v[76:79], v[160:163], v[208:211], 0
	v_mfma_f32_16x16x32_bf16 v[64:67], v[152:155], v[216:219], 0
	v_mfma_f32_16x16x32_bf16 v[68:71], v[160:163], v[216:219], 0
	v_mfma_f32_16x16x32_bf16 v[104:107], v[156:159], v[192:195], v[104:107]
	v_mfma_f32_16x16x32_bf16 v[108:111], v[164:167], v[192:195], v[108:111]
	v_mfma_f32_16x16x32_bf16 v[84:87], v[156:159], v[204:207], v[84:87]
	v_mfma_f32_16x16x32_bf16 v[92:95], v[164:167], v[204:207], v[92:95]
	v_mfma_f32_16x16x32_bf16 v[72:75], v[156:159], v[212:215], v[72:75]
	v_mfma_f32_16x16x32_bf16 v[76:79], v[164:167], v[212:215], v[76:79]
	v_mfma_f32_16x16x32_bf16 v[64:67], v[156:159], v[220:223], v[64:67]
	v_mfma_f32_16x16x32_bf16 v[68:71], v[164:167], v[220:223], v[68:71]
	v_mfma_f32_16x16x32_bf16 v[120:123], v[168:171], v[184:187], 0
	v_mfma_f32_16x16x32_bf16 v[124:127], v[176:179], v[184:187], 0
	v_mfma_f32_16x16x32_bf16 v[112:115], v[168:171], v[200:203], 0
	v_mfma_f32_16x16x32_bf16 v[116:119], v[176:179], v[200:203], 0
	v_mfma_f32_16x16x32_bf16 v[96:99], v[168:171], v[208:211], 0
	v_mfma_f32_16x16x32_bf16 v[100:103], v[176:179], v[208:211], 0
	v_mfma_f32_16x16x32_bf16 v[80:83], v[168:171], v[216:219], 0
	v_mfma_f32_16x16x32_bf16 v[88:91], v[176:179], v[216:219], 0
	v_mfma_f32_16x16x32_bf16 v[120:123], v[172:175], v[192:195], v[120:123]
	v_mfma_f32_16x16x32_bf16 v[124:127], v[180:183], v[192:195], v[124:127]
	v_mfma_f32_16x16x32_bf16 v[112:115], v[172:175], v[204:207], v[112:115]
	v_mfma_f32_16x16x32_bf16 v[116:119], v[180:183], v[204:207], v[116:119]
	v_mfma_f32_16x16x32_bf16 v[96:99], v[172:175], v[212:215], v[96:99]
	v_mfma_f32_16x16x32_bf16 v[100:103], v[180:183], v[212:215], v[100:103]
	v_mfma_f32_16x16x32_bf16 v[80:83], v[172:175], v[220:223], v[80:83]
	v_mfma_f32_16x16x32_bf16 v[88:91], v[180:183], v[220:223], v[88:91]
	s_barrier
	s_add_i32 s86, s48, s37
	s_mov_b32 m0, s86
	ds_read_b128 v[184:187], v150 offset:16384
	ds_read_b128 v[192:195], v150 offset:17408
	ds_read_b128 v[200:203], v150 offset:18432
	ds_read_b128 v[204:207], v150 offset:19456
	ds_read_b128 v[208:211], v150 offset:20480
	ds_read_b128 v[212:215], v150 offset:21504
	ds_read_b128 v[216:219], v150 offset:22528
	ds_read_b128 v[220:223], v150 offset:23552
	global_load_lds_dwordx4 v132, s[70:71] sc1
	s_add_i32 m0, s86, 0x2000
	s_add_u32 s86, s70, 0x4000
	s_addc_u32 s87, s71, 0
	s_add_i32 s88, s49, s37
	global_load_lds_dwordx4 v134, s[70:71] sc1
	s_mov_b32 m0, s88
	s_nop 0
	global_load_lds_dwordx4 v132, s[86:87] sc1
	s_add_i32 m0, s88, 0x2000
	s_nop 0
	global_load_lds_dwordx4 v134, s[86:87] sc1
	s_mov_b32 m0, s11
	s_nop 0
	global_load_lds_dwordx4 v128, s[78:79] sc1
	s_mov_b32 m0, s42
	s_nop 0
	global_load_lds_dwordx4 v130, s[78:79] sc1
	s_waitcnt vmcnt(8)
	s_waitcnt lgkmcnt(0)
	s_barrier
	s_waitcnt lgkmcnt(0)
	v_mfma_f32_16x16x32_bf16 v[36:39], v[152:155], v[184:187], 0
	v_mfma_f32_16x16x32_bf16 v[44:47], v[160:163], v[184:187], 0
	v_mfma_f32_16x16x32_bf16 v[20:23], v[152:155], v[200:203], 0
	v_mfma_f32_16x16x32_bf16 v[28:31], v[160:163], v[200:203], 0
	v_mfma_f32_16x16x32_bf16 v[8:11], v[152:155], v[208:211], 0
	v_mfma_f32_16x16x32_bf16 v[12:15], v[160:163], v[208:211], 0
	v_mfma_f32_16x16x32_bf16 v[0:3], v[152:155], v[216:219], 0
	v_mfma_f32_16x16x32_bf16 v[4:7], v[160:163], v[216:219], 0
	v_mfma_f32_16x16x32_bf16 v[36:39], v[156:159], v[192:195], v[36:39]
	v_mfma_f32_16x16x32_bf16 v[44:47], v[164:167], v[192:195], v[44:47]
	v_mfma_f32_16x16x32_bf16 v[20:23], v[156:159], v[204:207], v[20:23]
	v_mfma_f32_16x16x32_bf16 v[28:31], v[164:167], v[204:207], v[28:31]
	v_mfma_f32_16x16x32_bf16 v[8:11], v[156:159], v[212:215], v[8:11]
	v_mfma_f32_16x16x32_bf16 v[12:15], v[164:167], v[212:215], v[12:15]
	v_mfma_f32_16x16x32_bf16 v[0:3], v[156:159], v[220:223], v[0:3]
	v_mfma_f32_16x16x32_bf16 v[4:7], v[164:167], v[220:223], v[4:7]
	v_mfma_f32_16x16x32_bf16 v[56:59], v[168:171], v[184:187], 0
	v_mfma_f32_16x16x32_bf16 v[60:63], v[176:179], v[184:187], 0
	v_mfma_f32_16x16x32_bf16 v[48:51], v[168:171], v[200:203], 0
	v_mfma_f32_16x16x32_bf16 v[52:55], v[176:179], v[200:203], 0
	v_mfma_f32_16x16x32_bf16 v[32:35], v[168:171], v[208:211], 0
	v_mfma_f32_16x16x32_bf16 v[40:43], v[176:179], v[208:211], 0
	v_mfma_f32_16x16x32_bf16 v[16:19], v[168:171], v[216:219], 0
	v_mfma_f32_16x16x32_bf16 v[24:27], v[176:179], v[216:219], 0
	v_mfma_f32_16x16x32_bf16 v[56:59], v[172:175], v[192:195], v[56:59]
	v_mfma_f32_16x16x32_bf16 v[60:63], v[180:183], v[192:195], v[60:63]
	v_mfma_f32_16x16x32_bf16 v[48:51], v[172:175], v[204:207], v[48:51]
	v_mfma_f32_16x16x32_bf16 v[52:55], v[180:183], v[204:207], v[52:55]
	v_mfma_f32_16x16x32_bf16 v[32:35], v[172:175], v[212:215], v[32:35]
	v_mfma_f32_16x16x32_bf16 v[40:43], v[180:183], v[212:215], v[40:43]
	v_mfma_f32_16x16x32_bf16 v[16:19], v[172:175], v[220:223], v[16:19]
	v_mfma_f32_16x16x32_bf16 v[24:27], v[180:183], v[220:223], v[24:27]
	s_barrier
	v_add_u32_e32 v151, s50, v149
	ds_read_b128 v[152:155], v151
	ds_read_b128 v[156:159], v151 offset:1024
	ds_read_b128 v[160:163], v151 offset:2048
	ds_read_b128 v[164:167], v151 offset:3072
	v_add_u32_e32 v151, s51, v149
	ds_read_b128 v[168:171], v151
	ds_read_b128 v[172:175], v151 offset:1024
	ds_read_b128 v[176:179], v151 offset:2048
	ds_read_b128 v[180:183], v151 offset:3072
	s_add_u32 s78, s78, 0x4000
	s_addc_u32 s79, s79, 0
	s_mov_b32 m0, s43
	ds_read_b128 v[184:187], v150 offset:32768
	ds_read_b128 v[192:195], v150 offset:33792
	ds_read_b128 v[200:203], v150 offset:34816
	ds_read_b128 v[204:207], v150 offset:35840
	ds_read_b128 v[208:211], v150 offset:36864
	ds_read_b128 v[212:215], v150 offset:37888
	ds_read_b128 v[216:219], v150 offset:38912
	ds_read_b128 v[220:223], v150 offset:39936
	global_load_lds_dwordx4 v128, s[78:79] sc1
	s_mov_b32 m0, s44
	s_nop 0
	global_load_lds_dwordx4 v130, s[78:79] sc1
	s_waitcnt vmcnt(8)
	s_waitcnt lgkmcnt(0)
	s_barrier
	s_waitcnt lgkmcnt(0)
	v_mfma_f32_16x16x32_bf16 v[104:107], v[152:155], v[184:187], v[104:107]
	v_mfma_f32_16x16x32_bf16 v[108:111], v[160:163], v[184:187], v[108:111]
	v_mfma_f32_16x16x32_bf16 v[84:87], v[152:155], v[200:203], v[84:87]
	v_mfma_f32_16x16x32_bf16 v[92:95], v[160:163], v[200:203], v[92:95]
	v_mfma_f32_16x16x32_bf16 v[72:75], v[152:155], v[208:211], v[72:75]
	v_mfma_f32_16x16x32_bf16 v[76:79], v[160:163], v[208:211], v[76:79]
	v_mfma_f32_16x16x32_bf16 v[64:67], v[152:155], v[216:219], v[64:67]
	v_mfma_f32_16x16x32_bf16 v[68:71], v[160:163], v[216:219], v[68:71]
	v_mfma_f32_16x16x32_bf16 v[104:107], v[156:159], v[192:195], v[104:107]
	v_mfma_f32_16x16x32_bf16 v[108:111], v[164:167], v[192:195], v[108:111]
	v_mfma_f32_16x16x32_bf16 v[84:87], v[156:159], v[204:207], v[84:87]
	v_mfma_f32_16x16x32_bf16 v[92:95], v[164:167], v[204:207], v[92:95]
	v_mfma_f32_16x16x32_bf16 v[72:75], v[156:159], v[212:215], v[72:75]
	v_mfma_f32_16x16x32_bf16 v[76:79], v[164:167], v[212:215], v[76:79]
	v_mfma_f32_16x16x32_bf16 v[64:67], v[156:159], v[220:223], v[64:67]
	v_mfma_f32_16x16x32_bf16 v[68:71], v[164:167], v[220:223], v[68:71]
	v_mfma_f32_16x16x32_bf16 v[120:123], v[168:171], v[184:187], v[120:123]
	v_mfma_f32_16x16x32_bf16 v[124:127], v[176:179], v[184:187], v[124:127]
	v_mfma_f32_16x16x32_bf16 v[112:115], v[168:171], v[200:203], v[112:115]
	v_mfma_f32_16x16x32_bf16 v[116:119], v[176:179], v[200:203], v[116:119]
	v_mfma_f32_16x16x32_bf16 v[96:99], v[168:171], v[208:211], v[96:99]
	v_mfma_f32_16x16x32_bf16 v[100:103], v[176:179], v[208:211], v[100:103]
	v_mfma_f32_16x16x32_bf16 v[80:83], v[168:171], v[216:219], v[80:83]
	v_mfma_f32_16x16x32_bf16 v[88:91], v[176:179], v[216:219], v[88:91]
	v_mfma_f32_16x16x32_bf16 v[120:123], v[172:175], v[192:195], v[120:123]
	v_mfma_f32_16x16x32_bf16 v[124:127], v[180:183], v[192:195], v[124:127]
	v_mfma_f32_16x16x32_bf16 v[112:115], v[172:175], v[204:207], v[112:115]
	v_mfma_f32_16x16x32_bf16 v[116:119], v[180:183], v[204:207], v[116:119]
	v_mfma_f32_16x16x32_bf16 v[96:99], v[172:175], v[212:215], v[96:99]
	v_mfma_f32_16x16x32_bf16 v[100:103], v[180:183], v[212:215], v[100:103]
	v_mfma_f32_16x16x32_bf16 v[80:83], v[172:175], v[220:223], v[80:83]
	v_mfma_f32_16x16x32_bf16 v[88:91], v[180:183], v[220:223], v[88:91]
	s_barrier
	s_add_u32 s78, s70, 0x8000
	s_addc_u32 s79, s71, 0
	s_add_i32 s86, s50, s37
	s_mov_b32 m0, s86
	ds_read_b128 v[184:187], v150 offset:49152
	ds_read_b128 v[192:195], v150 offset:50176
	ds_read_b128 v[200:203], v150 offset:51200
	ds_read_b128 v[204:207], v150 offset:52224
	ds_read_b128 v[208:211], v150 offset:53248
	ds_read_b128 v[212:215], v150 offset:54272
	ds_read_b128 v[216:219], v150 offset:55296
	ds_read_b128 v[220:223], v150 offset:56320
	global_load_lds_dwordx4 v132, s[78:79] sc1
	s_add_i32 m0, s86, 0x2000
	s_add_u32 s70, s70, 0xc000
	global_load_lds_dwordx4 v134, s[78:79] sc1
	s_addc_u32 s71, s71, 0
	s_add_i32 s78, s51, s37
	s_mov_b32 m0, s78
	s_nop 0
	global_load_lds_dwordx4 v132, s[70:71] sc1
	s_add_i32 m0, s78, 0x2000
	s_nop 0
	global_load_lds_dwordx4 v134, s[70:71] sc1
	s_mov_b32 m0, s17
	s_nop 0
	global_load_lds_dwordx4 v128, s[66:67] sc1
	s_mov_b32 m0, s46
	s_nop 0
	global_load_lds_dwordx4 v130, s[66:67] sc1
	s_waitcnt vmcnt(8)
	s_waitcnt lgkmcnt(0)
	s_barrier
	s_waitcnt lgkmcnt(0)
	v_mfma_f32_16x16x32_bf16 v[36:39], v[152:155], v[184:187], v[36:39]
	v_mfma_f32_16x16x32_bf16 v[44:47], v[160:163], v[184:187], v[44:47]
	v_mfma_f32_16x16x32_bf16 v[20:23], v[152:155], v[200:203], v[20:23]
	v_mfma_f32_16x16x32_bf16 v[28:31], v[160:163], v[200:203], v[28:31]
	v_mfma_f32_16x16x32_bf16 v[8:11], v[152:155], v[208:211], v[8:11]
	v_mfma_f32_16x16x32_bf16 v[12:15], v[160:163], v[208:211], v[12:15]
	v_mfma_f32_16x16x32_bf16 v[0:3], v[152:155], v[216:219], v[0:3]
	v_mfma_f32_16x16x32_bf16 v[4:7], v[160:163], v[216:219], v[4:7]
	v_mfma_f32_16x16x32_bf16 v[36:39], v[156:159], v[192:195], v[36:39]
	v_mfma_f32_16x16x32_bf16 v[44:47], v[164:167], v[192:195], v[44:47]
	v_mfma_f32_16x16x32_bf16 v[20:23], v[156:159], v[204:207], v[20:23]
	v_mfma_f32_16x16x32_bf16 v[28:31], v[164:167], v[204:207], v[28:31]
	v_mfma_f32_16x16x32_bf16 v[8:11], v[156:159], v[212:215], v[8:11]
	v_mfma_f32_16x16x32_bf16 v[12:15], v[164:167], v[212:215], v[12:15]
	v_mfma_f32_16x16x32_bf16 v[0:3], v[156:159], v[220:223], v[0:3]
	v_mfma_f32_16x16x32_bf16 v[4:7], v[164:167], v[220:223], v[4:7]
	v_mfma_f32_16x16x32_bf16 v[56:59], v[168:171], v[184:187], v[56:59]
	v_mfma_f32_16x16x32_bf16 v[60:63], v[176:179], v[184:187], v[60:63]
	v_mfma_f32_16x16x32_bf16 v[48:51], v[168:171], v[200:203], v[48:51]
	v_mfma_f32_16x16x32_bf16 v[52:55], v[176:179], v[200:203], v[52:55]
	v_mfma_f32_16x16x32_bf16 v[32:35], v[168:171], v[208:211], v[32:35]
	v_mfma_f32_16x16x32_bf16 v[40:43], v[176:179], v[208:211], v[40:43]
	v_mfma_f32_16x16x32_bf16 v[16:19], v[168:171], v[216:219], v[16:19]
	v_mfma_f32_16x16x32_bf16 v[24:27], v[176:179], v[216:219], v[24:27]
	v_mfma_f32_16x16x32_bf16 v[56:59], v[172:175], v[192:195], v[56:59]
	v_mfma_f32_16x16x32_bf16 v[60:63], v[180:183], v[192:195], v[60:63]
	v_mfma_f32_16x16x32_bf16 v[48:51], v[172:175], v[204:207], v[48:51]
	v_mfma_f32_16x16x32_bf16 v[52:55], v[180:183], v[204:207], v[52:55]
	v_mfma_f32_16x16x32_bf16 v[32:35], v[172:175], v[212:215], v[32:35]
	v_mfma_f32_16x16x32_bf16 v[40:43], v[180:183], v[212:215], v[40:43]
	v_mfma_f32_16x16x32_bf16 v[16:19], v[172:175], v[220:223], v[16:19]
	v_mfma_f32_16x16x32_bf16 v[24:27], v[180:183], v[220:223], v[24:27]
	s_barrier
	s_add_i32 s85, s85, 2
	s_add_u32 s64, s64, 0x10000
	s_addc_u32 s65, s65, 0
	s_cmp_gt_u32 s85, 13
.LBB0_976:
	s_add_u32 s66, s18, s64
	v_add_u32_e32 v151, s48, v149
	s_addc_u32 s67, s19, s65
	ds_read_b128 v[152:155], v151
	ds_read_b128 v[156:159], v151 offset:1024
	ds_read_b128 v[160:163], v151 offset:2048
	ds_read_b128 v[164:167], v151 offset:3072
	v_add_u32_e32 v151, s49, v149
	s_add_u32 s66, s66, 0x10000
	ds_read_b128 v[168:171], v151
	ds_read_b128 v[172:175], v151 offset:1024
	ds_read_b128 v[176:179], v151 offset:2048
	ds_read_b128 v[180:183], v151 offset:3072
	s_addc_u32 s67, s67, 0
	s_add_u32 s70, s55, s64
	s_addc_u32 s71, s69, s65
	s_cmp_eq_u32 s64, 0x70000
	s_cselect_b32 s78, s80, s66
	s_cselect_b32 s79, s41, s67
	s_cselect_b32 s70, s81, s70
	s_cselect_b32 s71, s39, s71
	s_add_u32 s66, s78, 0x8000
	s_addc_u32 s67, s79, 0
	v_lshl_add_u64 v[196:197], v[144:145], 0, s[64:65]
	s_add_i32 m0, s11, 0xc000
	ds_read_b128 v[184:187], v150
	ds_read_b128 v[192:195], v150 offset:1024
	ds_read_b128 v[200:203], v150 offset:2048
	ds_read_b128 v[204:207], v150 offset:3072
	ds_read_b128 v[208:211], v150 offset:4096
	ds_read_b128 v[212:215], v150 offset:5120
	ds_read_b128 v[216:219], v150 offset:6144
	ds_read_b128 v[220:223], v150 offset:7168
	global_load_lds_dwordx4 v[196:197], off sc1
	v_lshl_add_u64 v[196:197], v[146:147], 0, s[64:65]
	s_add_i32 m0, s11, 0xe000
	s_nop 0
	global_load_lds_dwordx4 v[196:197], off sc1
	s_waitcnt vmcnt(8)
	s_waitcnt lgkmcnt(0)
	s_barrier
	s_waitcnt lgkmcnt(0)
	v_mfma_f32_16x16x32_bf16 v[104:107], v[152:155], v[184:187], v[104:107]
	v_mfma_f32_16x16x32_bf16 v[108:111], v[160:163], v[184:187], v[108:111]
	v_mfma_f32_16x16x32_bf16 v[84:87], v[152:155], v[200:203], v[84:87]
	v_mfma_f32_16x16x32_bf16 v[92:95], v[160:163], v[200:203], v[92:95]
	v_mfma_f32_16x16x32_bf16 v[72:75], v[152:155], v[208:211], v[72:75]
	v_mfma_f32_16x16x32_bf16 v[76:79], v[160:163], v[208:211], v[76:79]
	v_mfma_f32_16x16x32_bf16 v[64:67], v[152:155], v[216:219], v[64:67]
	v_mfma_f32_16x16x32_bf16 v[68:71], v[160:163], v[216:219], v[68:71]
	v_mfma_f32_16x16x32_bf16 v[104:107], v[156:159], v[192:195], v[104:107]
	v_mfma_f32_16x16x32_bf16 v[108:111], v[164:167], v[192:195], v[108:111]
	v_mfma_f32_16x16x32_bf16 v[84:87], v[156:159], v[204:207], v[84:87]
	v_mfma_f32_16x16x32_bf16 v[92:95], v[164:167], v[204:207], v[92:95]
	v_mfma_f32_16x16x32_bf16 v[72:75], v[156:159], v[212:215], v[72:75]
	v_mfma_f32_16x16x32_bf16 v[76:79], v[164:167], v[212:215], v[76:79]
	v_mfma_f32_16x16x32_bf16 v[64:67], v[156:159], v[220:223], v[64:67]
	v_mfma_f32_16x16x32_bf16 v[68:71], v[164:167], v[220:223], v[68:71]
	v_mfma_f32_16x16x32_bf16 v[120:123], v[168:171], v[184:187], v[120:123]
	v_mfma_f32_16x16x32_bf16 v[124:127], v[176:179], v[184:187], v[124:127]
	v_mfma_f32_16x16x32_bf16 v[112:115], v[168:171], v[200:203], v[112:115]
	v_mfma_f32_16x16x32_bf16 v[116:119], v[176:179], v[200:203], v[116:119]
	v_mfma_f32_16x16x32_bf16 v[96:99], v[168:171], v[208:211], v[96:99]
	v_mfma_f32_16x16x32_bf16 v[100:103], v[176:179], v[208:211], v[100:103]
	v_mfma_f32_16x16x32_bf16 v[80:83], v[168:171], v[216:219], v[80:83]
	v_mfma_f32_16x16x32_bf16 v[88:91], v[176:179], v[216:219], v[88:91]
	v_mfma_f32_16x16x32_bf16 v[120:123], v[172:175], v[192:195], v[120:123]
	v_mfma_f32_16x16x32_bf16 v[124:127], v[180:183], v[192:195], v[124:127]
	v_mfma_f32_16x16x32_bf16 v[112:115], v[172:175], v[204:207], v[112:115]
	v_mfma_f32_16x16x32_bf16 v[116:119], v[180:183], v[204:207], v[116:119]
	v_mfma_f32_16x16x32_bf16 v[96:99], v[172:175], v[212:215], v[96:99]
	v_mfma_f32_16x16x32_bf16 v[100:103], v[180:183], v[212:215], v[100:103]
	v_mfma_f32_16x16x32_bf16 v[80:83], v[172:175], v[220:223], v[80:83]
	v_mfma_f32_16x16x32_bf16 v[88:91], v[180:183], v[220:223], v[88:91]
	s_barrier
	s_add_i32 s86, s48, s37
	s_mov_b32 m0, s86
	ds_read_b128 v[184:187], v150 offset:16384
	ds_read_b128 v[192:195], v150 offset:17408
	ds_read_b128 v[200:203], v150 offset:18432
	ds_read_b128 v[204:207], v150 offset:19456
	ds_read_b128 v[208:211], v150 offset:20480
	ds_read_b128 v[212:215], v150 offset:21504
	ds_read_b128 v[216:219], v150 offset:22528
	ds_read_b128 v[220:223], v150 offset:23552
	global_load_lds_dwordx4 v132, s[70:71] sc1
	s_add_i32 m0, s86, 0x2000
	s_add_u32 s86, s70, 0x4000
	s_addc_u32 s87, s71, 0
	s_add_i32 s88, s49, s37
	global_load_lds_dwordx4 v134, s[70:71] sc1
	s_mov_b32 m0, s88
	s_nop 0
	global_load_lds_dwordx4 v132, s[86:87] sc1
	s_add_i32 m0, s88, 0x2000
	s_nop 0
	global_load_lds_dwordx4 v134, s[86:87] sc1
	s_mov_b32 m0, s11
	s_nop 0
	global_load_lds_dwordx4 v128, s[78:79] sc1
	s_mov_b32 m0, s42
	s_nop 0
	global_load_lds_dwordx4 v130, s[78:79] sc1
	s_waitcnt vmcnt(8)
	s_waitcnt lgkmcnt(0)
	s_barrier
	s_waitcnt lgkmcnt(0)
	v_mfma_f32_16x16x32_bf16 v[36:39], v[152:155], v[184:187], v[36:39]
	v_mfma_f32_16x16x32_bf16 v[44:47], v[160:163], v[184:187], v[44:47]
	v_mfma_f32_16x16x32_bf16 v[20:23], v[152:155], v[200:203], v[20:23]
	v_mfma_f32_16x16x32_bf16 v[28:31], v[160:163], v[200:203], v[28:31]
	v_mfma_f32_16x16x32_bf16 v[8:11], v[152:155], v[208:211], v[8:11]
	v_mfma_f32_16x16x32_bf16 v[12:15], v[160:163], v[208:211], v[12:15]
	v_mfma_f32_16x16x32_bf16 v[0:3], v[152:155], v[216:219], v[0:3]
	v_mfma_f32_16x16x32_bf16 v[4:7], v[160:163], v[216:219], v[4:7]
	v_mfma_f32_16x16x32_bf16 v[36:39], v[156:159], v[192:195], v[36:39]
	v_mfma_f32_16x16x32_bf16 v[44:47], v[164:167], v[192:195], v[44:47]
	v_mfma_f32_16x16x32_bf16 v[20:23], v[156:159], v[204:207], v[20:23]
	v_mfma_f32_16x16x32_bf16 v[28:31], v[164:167], v[204:207], v[28:31]
	v_mfma_f32_16x16x32_bf16 v[8:11], v[156:159], v[212:215], v[8:11]
	v_mfma_f32_16x16x32_bf16 v[12:15], v[164:167], v[212:215], v[12:15]
	v_mfma_f32_16x16x32_bf16 v[0:3], v[156:159], v[220:223], v[0:3]
	v_mfma_f32_16x16x32_bf16 v[4:7], v[164:167], v[220:223], v[4:7]
	v_mfma_f32_16x16x32_bf16 v[56:59], v[168:171], v[184:187], v[56:59]
	v_mfma_f32_16x16x32_bf16 v[60:63], v[176:179], v[184:187], v[60:63]
	v_mfma_f32_16x16x32_bf16 v[48:51], v[168:171], v[200:203], v[48:51]
	v_mfma_f32_16x16x32_bf16 v[52:55], v[176:179], v[200:203], v[52:55]
	v_mfma_f32_16x16x32_bf16 v[32:35], v[168:171], v[208:211], v[32:35]
	v_mfma_f32_16x16x32_bf16 v[40:43], v[176:179], v[208:211], v[40:43]
	v_mfma_f32_16x16x32_bf16 v[16:19], v[168:171], v[216:219], v[16:19]
	v_mfma_f32_16x16x32_bf16 v[24:27], v[176:179], v[216:219], v[24:27]
	v_mfma_f32_16x16x32_bf16 v[56:59], v[172:175], v[192:195], v[56:59]
	v_mfma_f32_16x16x32_bf16 v[60:63], v[180:183], v[192:195], v[60:63]
	v_mfma_f32_16x16x32_bf16 v[48:51], v[172:175], v[204:207], v[48:51]
	v_mfma_f32_16x16x32_bf16 v[52:55], v[180:183], v[204:207], v[52:55]
	v_mfma_f32_16x16x32_bf16 v[32:35], v[172:175], v[212:215], v[32:35]
	v_mfma_f32_16x16x32_bf16 v[40:43], v[180:183], v[212:215], v[40:43]
	v_mfma_f32_16x16x32_bf16 v[16:19], v[172:175], v[220:223], v[16:19]
	v_mfma_f32_16x16x32_bf16 v[24:27], v[180:183], v[220:223], v[24:27]
	s_barrier
	v_add_u32_e32 v151, s50, v149
	ds_read_b128 v[152:155], v151
	ds_read_b128 v[156:159], v151 offset:1024
	ds_read_b128 v[160:163], v151 offset:2048
	ds_read_b128 v[164:167], v151 offset:3072
	v_add_u32_e32 v151, s51, v149
	ds_read_b128 v[168:171], v151
	ds_read_b128 v[172:175], v151 offset:1024
	ds_read_b128 v[176:179], v151 offset:2048
	ds_read_b128 v[180:183], v151 offset:3072
	s_add_u32 s78, s78, 0x4000
	s_addc_u32 s79, s79, 0
	s_mov_b32 m0, s43
	ds_read_b128 v[184:187], v150 offset:32768
	ds_read_b128 v[192:195], v150 offset:33792
	ds_read_b128 v[200:203], v150 offset:34816
	ds_read_b128 v[204:207], v150 offset:35840
	ds_read_b128 v[208:211], v150 offset:36864
	ds_read_b128 v[212:215], v150 offset:37888
	ds_read_b128 v[216:219], v150 offset:38912
	ds_read_b128 v[220:223], v150 offset:39936
	global_load_lds_dwordx4 v128, s[78:79] sc1
	s_mov_b32 m0, s44
	s_nop 0
	global_load_lds_dwordx4 v130, s[78:79] sc1
	s_waitcnt vmcnt(8)
	s_waitcnt lgkmcnt(0)
	s_barrier
	s_waitcnt lgkmcnt(0)
	v_mfma_f32_16x16x32_bf16 v[104:107], v[152:155], v[184:187], v[104:107]
	v_mfma_f32_16x16x32_bf16 v[108:111], v[160:163], v[184:187], v[108:111]
	v_mfma_f32_16x16x32_bf16 v[84:87], v[152:155], v[200:203], v[84:87]
	v_mfma_f32_16x16x32_bf16 v[92:95], v[160:163], v[200:203], v[92:95]
	v_mfma_f32_16x16x32_bf16 v[72:75], v[152:155], v[208:211], v[72:75]
	v_mfma_f32_16x16x32_bf16 v[76:79], v[160:163], v[208:211], v[76:79]
	v_mfma_f32_16x16x32_bf16 v[64:67], v[152:155], v[216:219], v[64:67]
	v_mfma_f32_16x16x32_bf16 v[68:71], v[160:163], v[216:219], v[68:71]
	v_mfma_f32_16x16x32_bf16 v[104:107], v[156:159], v[192:195], v[104:107]
	v_mfma_f32_16x16x32_bf16 v[108:111], v[164:167], v[192:195], v[108:111]
	v_mfma_f32_16x16x32_bf16 v[84:87], v[156:159], v[204:207], v[84:87]
	v_mfma_f32_16x16x32_bf16 v[92:95], v[164:167], v[204:207], v[92:95]
	v_mfma_f32_16x16x32_bf16 v[72:75], v[156:159], v[212:215], v[72:75]
	v_mfma_f32_16x16x32_bf16 v[76:79], v[164:167], v[212:215], v[76:79]
	v_mfma_f32_16x16x32_bf16 v[64:67], v[156:159], v[220:223], v[64:67]
	v_mfma_f32_16x16x32_bf16 v[68:71], v[164:167], v[220:223], v[68:71]
	v_mfma_f32_16x16x32_bf16 v[120:123], v[168:171], v[184:187], v[120:123]
	v_mfma_f32_16x16x32_bf16 v[124:127], v[176:179], v[184:187], v[124:127]
	v_mfma_f32_16x16x32_bf16 v[112:115], v[168:171], v[200:203], v[112:115]
	v_mfma_f32_16x16x32_bf16 v[116:119], v[176:179], v[200:203], v[116:119]
	v_mfma_f32_16x16x32_bf16 v[96:99], v[168:171], v[208:211], v[96:99]
	v_mfma_f32_16x16x32_bf16 v[100:103], v[176:179], v[208:211], v[100:103]
	v_mfma_f32_16x16x32_bf16 v[80:83], v[168:171], v[216:219], v[80:83]
	v_mfma_f32_16x16x32_bf16 v[88:91], v[176:179], v[216:219], v[88:91]
	v_mfma_f32_16x16x32_bf16 v[120:123], v[172:175], v[192:195], v[120:123]
	v_mfma_f32_16x16x32_bf16 v[124:127], v[180:183], v[192:195], v[124:127]
	v_mfma_f32_16x16x32_bf16 v[112:115], v[172:175], v[204:207], v[112:115]
	v_mfma_f32_16x16x32_bf16 v[116:119], v[180:183], v[204:207], v[116:119]
	v_mfma_f32_16x16x32_bf16 v[96:99], v[172:175], v[212:215], v[96:99]
	v_mfma_f32_16x16x32_bf16 v[100:103], v[180:183], v[212:215], v[100:103]
	v_mfma_f32_16x16x32_bf16 v[80:83], v[172:175], v[220:223], v[80:83]
	v_mfma_f32_16x16x32_bf16 v[88:91], v[180:183], v[220:223], v[88:91]
	s_barrier
	s_add_u32 s78, s70, 0x8000
	s_addc_u32 s79, s71, 0
	s_add_i32 s86, s50, s37
	s_mov_b32 m0, s86
	ds_read_b128 v[184:187], v150 offset:49152
	ds_read_b128 v[192:195], v150 offset:50176
	ds_read_b128 v[200:203], v150 offset:51200
	ds_read_b128 v[204:207], v150 offset:52224
	ds_read_b128 v[208:211], v150 offset:53248
	ds_read_b128 v[212:215], v150 offset:54272
	ds_read_b128 v[216:219], v150 offset:55296
	ds_read_b128 v[220:223], v150 offset:56320
	global_load_lds_dwordx4 v132, s[78:79] sc1
	s_add_i32 m0, s86, 0x2000
	s_add_u32 s70, s70, 0xc000
	global_load_lds_dwordx4 v134, s[78:79] sc1
	s_addc_u32 s71, s71, 0
	s_add_i32 s78, s51, s37
	s_mov_b32 m0, s78
	s_nop 0
	global_load_lds_dwordx4 v132, s[70:71] sc1
	s_add_i32 m0, s78, 0x2000
	s_nop 0
	global_load_lds_dwordx4 v134, s[70:71] sc1
	s_mov_b32 m0, s17
	s_nop 0
	global_load_lds_dwordx4 v128, s[66:67] sc1
	s_mov_b32 m0, s46
	s_nop 0
	global_load_lds_dwordx4 v130, s[66:67] sc1
	s_waitcnt vmcnt(8)
	s_waitcnt lgkmcnt(0)
	s_barrier
	s_waitcnt lgkmcnt(0)
	v_mfma_f32_16x16x32_bf16 v[36:39], v[152:155], v[184:187], v[36:39]
	v_mfma_f32_16x16x32_bf16 v[44:47], v[160:163], v[184:187], v[44:47]
	v_mfma_f32_16x16x32_bf16 v[20:23], v[152:155], v[200:203], v[20:23]
	v_mfma_f32_16x16x32_bf16 v[28:31], v[160:163], v[200:203], v[28:31]
	v_mfma_f32_16x16x32_bf16 v[8:11], v[152:155], v[208:211], v[8:11]
	v_mfma_f32_16x16x32_bf16 v[12:15], v[160:163], v[208:211], v[12:15]
	v_mfma_f32_16x16x32_bf16 v[0:3], v[152:155], v[216:219], v[0:3]
	v_mfma_f32_16x16x32_bf16 v[4:7], v[160:163], v[216:219], v[4:7]
	v_mfma_f32_16x16x32_bf16 v[36:39], v[156:159], v[192:195], v[36:39]
	v_mfma_f32_16x16x32_bf16 v[44:47], v[164:167], v[192:195], v[44:47]
	v_mfma_f32_16x16x32_bf16 v[20:23], v[156:159], v[204:207], v[20:23]
	v_mfma_f32_16x16x32_bf16 v[28:31], v[164:167], v[204:207], v[28:31]
	v_mfma_f32_16x16x32_bf16 v[8:11], v[156:159], v[212:215], v[8:11]
	v_mfma_f32_16x16x32_bf16 v[12:15], v[164:167], v[212:215], v[12:15]
	v_mfma_f32_16x16x32_bf16 v[0:3], v[156:159], v[220:223], v[0:3]
	v_mfma_f32_16x16x32_bf16 v[4:7], v[164:167], v[220:223], v[4:7]
	v_mfma_f32_16x16x32_bf16 v[56:59], v[168:171], v[184:187], v[56:59]
	v_mfma_f32_16x16x32_bf16 v[60:63], v[176:179], v[184:187], v[60:63]
	v_mfma_f32_16x16x32_bf16 v[48:51], v[168:171], v[200:203], v[48:51]
	v_mfma_f32_16x16x32_bf16 v[52:55], v[176:179], v[200:203], v[52:55]
	v_mfma_f32_16x16x32_bf16 v[32:35], v[168:171], v[208:211], v[32:35]
	v_mfma_f32_16x16x32_bf16 v[40:43], v[176:179], v[208:211], v[40:43]
	v_mfma_f32_16x16x32_bf16 v[16:19], v[168:171], v[216:219], v[16:19]
	v_mfma_f32_16x16x32_bf16 v[24:27], v[176:179], v[216:219], v[24:27]
	v_mfma_f32_16x16x32_bf16 v[56:59], v[172:175], v[192:195], v[56:59]
	v_mfma_f32_16x16x32_bf16 v[60:63], v[180:183], v[192:195], v[60:63]
	v_mfma_f32_16x16x32_bf16 v[48:51], v[172:175], v[204:207], v[48:51]
	v_mfma_f32_16x16x32_bf16 v[52:55], v[180:183], v[204:207], v[52:55]
	v_mfma_f32_16x16x32_bf16 v[32:35], v[172:175], v[212:215], v[32:35]
	v_mfma_f32_16x16x32_bf16 v[40:43], v[180:183], v[212:215], v[40:43]
	v_mfma_f32_16x16x32_bf16 v[16:19], v[172:175], v[220:223], v[16:19]
	v_mfma_f32_16x16x32_bf16 v[24:27], v[180:183], v[220:223], v[24:27]
	s_barrier
	s_add_i32 s85, s85, 2
	s_add_u32 s64, s64, 0x10000
	s_addc_u32 s65, s65, 0
	s_cmp_gt_u32 s85, 13
	s_cbranch_scc0 .LBB0_976
	s_add_u32 s64, s55, 0xffff0000
	s_addc_u32 s65, s69, -1
	s_andn2_b64 vcc, exec, s[8:9]
	s_cbranch_vccnz .LBB0_967
	s_mov_b32 s16, s38
	s_mov_b32 s10, s40
	s_mov_b64 s[18:19], s[62:63]
	s_mov_b32 s47, s54
	s_andn2_b64 vcc, exec, s[6:7]
	s_cbranch_vccnz .LBB0_968

.LBB0_1028:
	s_add_u32 s77, s62, 0x10000
	s_addc_u32 s82, s63, 0
	s_ashr_i32 s65, s64, 31
	s_lshl_b64 s[62:63], s[64:65], 19
	s_add_u32 s62, s38, s62
	s_addc_u32 s63, s39, s63
	s_lshl_b32 s70, s18, 2
	s_ashr_i32 s41, s40, 31
	s_ashr_i32 s71, s70, 31
	s_lshl_b64 s[78:79], s[40:41], 19
	s_lshl_b64 s[70:71], s[70:71], 15
	s_add_u32 s41, s60, s70
	s_addc_u32 s65, s33, s71
	s_add_u32 s41, s41, s78
	s_addc_u32 s65, s65, s79
	s_add_u32 s70, s41, 0x10000
	s_addc_u32 s71, s65, 0
	s_and_b64 s[10:11], s[10:11], exec
	s_cselect_b32 s83, s67, s71
	s_cselect_b32 s84, s66, s70
	s_cselect_b32 s85, s63, s65
	s_cselect_b32 s86, s62, s41
	v_lshl_add_u64 v[144:145], s[56:57], 0, v[136:137]
	v_lshl_add_u64 v[146:147], s[56:57], 0, v[138:139]
	s_mov_b32 s87, -2
	s_mov_b64 s[10:11], 0
	s_add_u32 s41, s56, s10
	s_addc_u32 s65, s57, s11
	v_add_u32_e32 v168, s50, v151
	v_add_u32_e32 v184, s51, v151
	s_add_u32 s41, s41, 0x10000
	ds_read_b128 v[156:159], v168
	ds_read_b128 v[160:163], v168 offset:1024
	ds_read_b128 v[164:167], v168 offset:2048
	ds_read_b128 v[168:171], v168 offset:3072
	ds_read_b128 v[172:175], v184
	ds_read_b128 v[176:179], v184 offset:1024
	ds_read_b128 v[180:183], v184 offset:2048
	ds_read_b128 v[184:187], v184 offset:3072
	s_addc_u32 s65, s65, 0
	s_add_u32 s70, s77, s10
	s_addc_u32 s71, s82, s11
	s_cmp_eq_u32 s10, 0x70000
	s_cselect_b32 s80, s84, s41
	s_cselect_b32 s81, s83, s65
	s_cselect_b32 s78, s86, s70
	s_cselect_b32 s79, s85, s71
	s_add_u32 s70, s80, 0x8000
	s_addc_u32 s71, s81, 0
	s_add_i32 s41, s42, 0xc000
	v_lshl_add_u64 v[196:197], v[144:145], 0, s[10:11]
	s_mov_b32 m0, s41
	s_add_i32 s65, s42, 0xe000
	ds_read_b128 v[192:195], v154
	ds_read_b128 v[200:203], v154 offset:1024
	ds_read_b128 v[204:207], v154 offset:2048
	ds_read_b128 v[208:211], v154 offset:3072
	ds_read_b128 v[212:215], v154 offset:4096
	ds_read_b128 v[216:219], v154 offset:5120
	ds_read_b128 v[220:223], v154 offset:6144
	ds_read_b128 v[224:227], v154 offset:7168
	global_load_lds_dwordx4 v[196:197], off sc1
	v_lshl_add_u64 v[196:197], v[146:147], 0, s[10:11]
	s_mov_b32 m0, s65
	s_nop 0
	global_load_lds_dwordx4 v[196:197], off sc1
	s_waitcnt vmcnt(8)
	s_waitcnt lgkmcnt(0)
	s_barrier
	s_waitcnt lgkmcnt(0)
	v_mfma_f32_16x16x32_bf16 v[112:115], v[156:159], v[192:195], 0
	v_mfma_f32_16x16x32_bf16 v[116:119], v[164:167], v[192:195], 0
	v_mfma_f32_16x16x32_bf16 v[96:99], v[156:159], v[204:207], 0
	v_mfma_f32_16x16x32_bf16 v[100:103], v[164:167], v[204:207], 0
	v_mfma_f32_16x16x32_bf16 v[80:83], v[156:159], v[212:215], 0
	v_mfma_f32_16x16x32_bf16 v[84:87], v[164:167], v[212:215], 0
	v_mfma_f32_16x16x32_bf16 v[64:67], v[156:159], v[220:223], 0
	v_mfma_f32_16x16x32_bf16 v[68:71], v[164:167], v[220:223], 0
	v_mfma_f32_16x16x32_bf16 v[112:115], v[160:163], v[200:203], v[112:115]
	v_mfma_f32_16x16x32_bf16 v[116:119], v[168:171], v[200:203], v[116:119]
	v_mfma_f32_16x16x32_bf16 v[96:99], v[160:163], v[208:211], v[96:99]
	v_mfma_f32_16x16x32_bf16 v[100:103], v[168:171], v[208:211], v[100:103]
	v_mfma_f32_16x16x32_bf16 v[80:83], v[160:163], v[216:219], v[80:83]
	v_mfma_f32_16x16x32_bf16 v[84:87], v[168:171], v[216:219], v[84:87]
	v_mfma_f32_16x16x32_bf16 v[64:67], v[160:163], v[224:227], v[64:67]
	v_mfma_f32_16x16x32_bf16 v[68:71], v[168:171], v[224:227], v[68:71]
	v_mfma_f32_16x16x32_bf16 v[120:123], v[172:175], v[192:195], 0
	v_mfma_f32_16x16x32_bf16 v[124:127], v[180:183], v[192:195], 0
	v_mfma_f32_16x16x32_bf16 v[104:107], v[172:175], v[204:207], 0
	v_mfma_f32_16x16x32_bf16 v[108:111], v[180:183], v[204:207], 0
	v_mfma_f32_16x16x32_bf16 v[88:91], v[172:175], v[212:215], 0
	v_mfma_f32_16x16x32_bf16 v[92:95], v[180:183], v[212:215], 0
	v_mfma_f32_16x16x32_bf16 v[72:75], v[172:175], v[220:223], 0
	v_mfma_f32_16x16x32_bf16 v[76:79], v[180:183], v[220:223], 0
	v_mfma_f32_16x16x32_bf16 v[120:123], v[176:179], v[200:203], v[120:123]
	v_mfma_f32_16x16x32_bf16 v[124:127], v[184:187], v[200:203], v[124:127]
	v_mfma_f32_16x16x32_bf16 v[104:107], v[176:179], v[208:211], v[104:107]
	v_mfma_f32_16x16x32_bf16 v[108:111], v[184:187], v[208:211], v[108:111]
	v_mfma_f32_16x16x32_bf16 v[88:91], v[176:179], v[216:219], v[88:91]
	v_mfma_f32_16x16x32_bf16 v[92:95], v[184:187], v[216:219], v[92:95]
	v_mfma_f32_16x16x32_bf16 v[72:75], v[176:179], v[224:227], v[72:75]
	v_mfma_f32_16x16x32_bf16 v[76:79], v[184:187], v[224:227], v[76:79]
	s_barrier
	s_add_i32 s88, s50, s35
	s_mov_b32 m0, s88
	ds_read_b128 v[192:195], v154 offset:16384
	ds_read_b128 v[200:203], v154 offset:17408
	ds_read_b128 v[204:207], v154 offset:18432
	ds_read_b128 v[208:211], v154 offset:19456
	ds_read_b128 v[212:215], v154 offset:20480
	ds_read_b128 v[216:219], v154 offset:21504
	ds_read_b128 v[220:223], v154 offset:22528
	ds_read_b128 v[224:227], v154 offset:23552
	global_load_lds_dwordx4 v132, s[78:79] sc1
	s_add_i32 m0, s88, 0x2000
	s_add_u32 s88, s78, 0x4000
	s_addc_u32 s89, s79, 0
	s_add_i32 s90, s51, s35
	global_load_lds_dwordx4 v134, s[78:79] sc1
	s_mov_b32 m0, s90
	s_nop 0
	global_load_lds_dwordx4 v132, s[88:89] sc1
	s_add_i32 m0, s90, 0x2000
	s_nop 0
	global_load_lds_dwordx4 v134, s[88:89] sc1
	s_mov_b32 m0, s42
	s_nop 0
	global_load_lds_dwordx4 v128, s[80:81] sc1
	s_mov_b32 m0, s43
	s_nop 0
	global_load_lds_dwordx4 v130, s[80:81] sc1
	s_waitcnt vmcnt(8)
	s_waitcnt lgkmcnt(0)
	s_barrier
	s_waitcnt lgkmcnt(0)
	v_mfma_f32_16x16x32_bf16 v[48:51], v[156:159], v[192:195], 0
	v_mfma_f32_16x16x32_bf16 v[52:55], v[164:167], v[192:195], 0
	v_mfma_f32_16x16x32_bf16 v[32:35], v[156:159], v[204:207], 0
	v_mfma_f32_16x16x32_bf16 v[36:39], v[164:167], v[204:207], 0
	v_mfma_f32_16x16x32_bf16 v[16:19], v[156:159], v[212:215], 0
	v_mfma_f32_16x16x32_bf16 v[20:23], v[164:167], v[212:215], 0
	v_mfma_f32_16x16x32_bf16 v[0:3], v[156:159], v[220:223], 0
	v_mfma_f32_16x16x32_bf16 v[4:7], v[164:167], v[220:223], 0
	v_mfma_f32_16x16x32_bf16 v[48:51], v[160:163], v[200:203], v[48:51]
	v_mfma_f32_16x16x32_bf16 v[52:55], v[168:171], v[200:203], v[52:55]
	v_mfma_f32_16x16x32_bf16 v[32:35], v[160:163], v[208:211], v[32:35]
	v_mfma_f32_16x16x32_bf16 v[36:39], v[168:171], v[208:211], v[36:39]
	v_mfma_f32_16x16x32_bf16 v[16:19], v[160:163], v[216:219], v[16:19]
	v_mfma_f32_16x16x32_bf16 v[20:23], v[168:171], v[216:219], v[20:23]
	v_mfma_f32_16x16x32_bf16 v[0:3], v[160:163], v[224:227], v[0:3]
	v_mfma_f32_16x16x32_bf16 v[4:7], v[168:171], v[224:227], v[4:7]
	v_mfma_f32_16x16x32_bf16 v[56:59], v[172:175], v[192:195], 0
	v_mfma_f32_16x16x32_bf16 v[60:63], v[180:183], v[192:195], 0
	v_mfma_f32_16x16x32_bf16 v[40:43], v[172:175], v[204:207], 0
	v_mfma_f32_16x16x32_bf16 v[44:47], v[180:183], v[204:207], 0
	v_mfma_f32_16x16x32_bf16 v[24:27], v[172:175], v[212:215], 0
	v_mfma_f32_16x16x32_bf16 v[28:31], v[180:183], v[212:215], 0
	v_mfma_f32_16x16x32_bf16 v[8:11], v[172:175], v[220:223], 0
	v_mfma_f32_16x16x32_bf16 v[12:15], v[180:183], v[220:223], 0
	v_mfma_f32_16x16x32_bf16 v[56:59], v[176:179], v[200:203], v[56:59]
	v_mfma_f32_16x16x32_bf16 v[60:63], v[184:187], v[200:203], v[60:63]
	v_mfma_f32_16x16x32_bf16 v[40:43], v[176:179], v[208:211], v[40:43]
	v_mfma_f32_16x16x32_bf16 v[44:47], v[184:187], v[208:211], v[44:47]
	v_mfma_f32_16x16x32_bf16 v[24:27], v[176:179], v[216:219], v[24:27]
	v_mfma_f32_16x16x32_bf16 v[28:31], v[184:187], v[216:219], v[28:31]
	v_mfma_f32_16x16x32_bf16 v[8:11], v[176:179], v[224:227], v[8:11]
	v_mfma_f32_16x16x32_bf16 v[12:15], v[184:187], v[224:227], v[12:15]
	s_barrier
	v_add_u32_e32 v168, s54, v151
	v_add_u32_e32 v184, s55, v151
	ds_read_b128 v[156:159], v168
	ds_read_b128 v[160:163], v168 offset:1024
	ds_read_b128 v[164:167], v168 offset:2048
	ds_read_b128 v[168:171], v168 offset:3072
	ds_read_b128 v[172:175], v184
	ds_read_b128 v[176:179], v184 offset:1024
	ds_read_b128 v[180:183], v184 offset:2048
	ds_read_b128 v[184:187], v184 offset:3072
	s_add_u32 s80, s80, 0x4000
	s_addc_u32 s81, s81, 0
	s_mov_b32 m0, s44
	ds_read_b128 v[192:195], v154 offset:32768
	ds_read_b128 v[200:203], v154 offset:33792
	ds_read_b128 v[204:207], v154 offset:34816
	ds_read_b128 v[208:211], v154 offset:35840
	ds_read_b128 v[212:215], v154 offset:36864
	ds_read_b128 v[216:219], v154 offset:37888
	ds_read_b128 v[220:223], v154 offset:38912
	ds_read_b128 v[224:227], v154 offset:39936
	global_load_lds_dwordx4 v128, s[80:81] sc1
	s_mov_b32 m0, s45
	s_nop 0
	global_load_lds_dwordx4 v130, s[80:81] sc1
	s_waitcnt vmcnt(8)
	s_waitcnt lgkmcnt(0)
	s_barrier
	s_waitcnt lgkmcnt(0)
	v_mfma_f32_16x16x32_bf16 v[112:115], v[156:159], v[192:195], v[112:115]
	v_mfma_f32_16x16x32_bf16 v[116:119], v[164:167], v[192:195], v[116:119]
	v_mfma_f32_16x16x32_bf16 v[96:99], v[156:159], v[204:207], v[96:99]
	v_mfma_f32_16x16x32_bf16 v[100:103], v[164:167], v[204:207], v[100:103]
	v_mfma_f32_16x16x32_bf16 v[80:83], v[156:159], v[212:215], v[80:83]
	v_mfma_f32_16x16x32_bf16 v[84:87], v[164:167], v[212:215], v[84:87]
	v_mfma_f32_16x16x32_bf16 v[64:67], v[156:159], v[220:223], v[64:67]
	v_mfma_f32_16x16x32_bf16 v[68:71], v[164:167], v[220:223], v[68:71]
	v_mfma_f32_16x16x32_bf16 v[112:115], v[160:163], v[200:203], v[112:115]
	v_mfma_f32_16x16x32_bf16 v[116:119], v[168:171], v[200:203], v[116:119]
	v_mfma_f32_16x16x32_bf16 v[96:99], v[160:163], v[208:211], v[96:99]
	v_mfma_f32_16x16x32_bf16 v[100:103], v[168:171], v[208:211], v[100:103]
	v_mfma_f32_16x16x32_bf16 v[80:83], v[160:163], v[216:219], v[80:83]
	v_mfma_f32_16x16x32_bf16 v[84:87], v[168:171], v[216:219], v[84:87]
	v_mfma_f32_16x16x32_bf16 v[64:67], v[160:163], v[224:227], v[64:67]
	v_mfma_f32_16x16x32_bf16 v[68:71], v[168:171], v[224:227], v[68:71]
	v_mfma_f32_16x16x32_bf16 v[120:123], v[172:175], v[192:195], v[120:123]
	v_mfma_f32_16x16x32_bf16 v[124:127], v[180:183], v[192:195], v[124:127]
	v_mfma_f32_16x16x32_bf16 v[104:107], v[172:175], v[204:207], v[104:107]
	v_mfma_f32_16x16x32_bf16 v[108:111], v[180:183], v[204:207], v[108:111]
	v_mfma_f32_16x16x32_bf16 v[88:91], v[172:175], v[212:215], v[88:91]
	v_mfma_f32_16x16x32_bf16 v[92:95], v[180:183], v[212:215], v[92:95]
	v_mfma_f32_16x16x32_bf16 v[72:75], v[172:175], v[220:223], v[72:75]
	v_mfma_f32_16x16x32_bf16 v[76:79], v[180:183], v[220:223], v[76:79]
	v_mfma_f32_16x16x32_bf16 v[120:123], v[176:179], v[200:203], v[120:123]
	v_mfma_f32_16x16x32_bf16 v[124:127], v[184:187], v[200:203], v[124:127]
	v_mfma_f32_16x16x32_bf16 v[104:107], v[176:179], v[208:211], v[104:107]
	v_mfma_f32_16x16x32_bf16 v[108:111], v[184:187], v[208:211], v[108:111]
	v_mfma_f32_16x16x32_bf16 v[88:91], v[176:179], v[216:219], v[88:91]
	v_mfma_f32_16x16x32_bf16 v[92:95], v[184:187], v[216:219], v[92:95]
	v_mfma_f32_16x16x32_bf16 v[72:75], v[176:179], v[224:227], v[72:75]
	v_mfma_f32_16x16x32_bf16 v[76:79], v[184:187], v[224:227], v[76:79]
	s_barrier
	s_add_u32 s80, s78, 0x8000
	s_addc_u32 s81, s79, 0
	s_add_i32 s88, s54, s35
	s_mov_b32 m0, s88
	ds_read_b128 v[192:195], v154 offset:49152
	ds_read_b128 v[200:203], v154 offset:50176
	ds_read_b128 v[204:207], v154 offset:51200
	ds_read_b128 v[208:211], v154 offset:52224
	ds_read_b128 v[212:215], v154 offset:53248
	ds_read_b128 v[216:219], v154 offset:54272
	ds_read_b128 v[220:223], v154 offset:55296
	ds_read_b128 v[224:227], v154 offset:56320
	global_load_lds_dwordx4 v132, s[80:81] sc1
	s_add_i32 m0, s88, 0x2000
	s_add_u32 s78, s78, 0xc000
	global_load_lds_dwordx4 v134, s[80:81] sc1
	s_addc_u32 s79, s79, 0
	s_add_i32 s80, s55, s35
	s_mov_b32 m0, s80
	s_nop 0
	global_load_lds_dwordx4 v132, s[78:79] sc1
	s_add_i32 m0, s80, 0x2000
	s_nop 0
	global_load_lds_dwordx4 v134, s[78:79] sc1
	s_mov_b32 m0, s47
	s_nop 0
	global_load_lds_dwordx4 v128, s[70:71] sc1
	s_mov_b32 m0, s48
	s_nop 0
	global_load_lds_dwordx4 v130, s[70:71] sc1
	s_waitcnt vmcnt(8)
	s_waitcnt lgkmcnt(0)
	s_barrier
	s_waitcnt lgkmcnt(0)
	v_mfma_f32_16x16x32_bf16 v[48:51], v[156:159], v[192:195], v[48:51]
	v_mfma_f32_16x16x32_bf16 v[52:55], v[164:167], v[192:195], v[52:55]
	v_mfma_f32_16x16x32_bf16 v[32:35], v[156:159], v[204:207], v[32:35]
	v_mfma_f32_16x16x32_bf16 v[36:39], v[164:167], v[204:207], v[36:39]
	v_mfma_f32_16x16x32_bf16 v[16:19], v[156:159], v[212:215], v[16:19]
	v_mfma_f32_16x16x32_bf16 v[20:23], v[164:167], v[212:215], v[20:23]
	v_mfma_f32_16x16x32_bf16 v[0:3], v[156:159], v[220:223], v[0:3]
	v_mfma_f32_16x16x32_bf16 v[4:7], v[164:167], v[220:223], v[4:7]
	v_mfma_f32_16x16x32_bf16 v[48:51], v[160:163], v[200:203], v[48:51]
	v_mfma_f32_16x16x32_bf16 v[52:55], v[168:171], v[200:203], v[52:55]
	v_mfma_f32_16x16x32_bf16 v[32:35], v[160:163], v[208:211], v[32:35]
	v_mfma_f32_16x16x32_bf16 v[36:39], v[168:171], v[208:211], v[36:39]
	v_mfma_f32_16x16x32_bf16 v[16:19], v[160:163], v[216:219], v[16:19]
	v_mfma_f32_16x16x32_bf16 v[20:23], v[168:171], v[216:219], v[20:23]
	v_mfma_f32_16x16x32_bf16 v[0:3], v[160:163], v[224:227], v[0:3]
	v_mfma_f32_16x16x32_bf16 v[4:7], v[168:171], v[224:227], v[4:7]
	v_mfma_f32_16x16x32_bf16 v[56:59], v[172:175], v[192:195], v[56:59]
	v_mfma_f32_16x16x32_bf16 v[60:63], v[180:183], v[192:195], v[60:63]
	v_mfma_f32_16x16x32_bf16 v[40:43], v[172:175], v[204:207], v[40:43]
	v_mfma_f32_16x16x32_bf16 v[44:47], v[180:183], v[204:207], v[44:47]
	v_mfma_f32_16x16x32_bf16 v[24:27], v[172:175], v[212:215], v[24:27]
	v_mfma_f32_16x16x32_bf16 v[28:31], v[180:183], v[212:215], v[28:31]
	v_mfma_f32_16x16x32_bf16 v[8:11], v[172:175], v[220:223], v[8:11]
	v_mfma_f32_16x16x32_bf16 v[12:15], v[180:183], v[220:223], v[12:15]
	v_mfma_f32_16x16x32_bf16 v[56:59], v[176:179], v[200:203], v[56:59]
	v_mfma_f32_16x16x32_bf16 v[60:63], v[184:187], v[200:203], v[60:63]
	v_mfma_f32_16x16x32_bf16 v[40:43], v[176:179], v[208:211], v[40:43]
	v_mfma_f32_16x16x32_bf16 v[44:47], v[184:187], v[208:211], v[44:47]
	v_mfma_f32_16x16x32_bf16 v[24:27], v[176:179], v[216:219], v[24:27]
	v_mfma_f32_16x16x32_bf16 v[28:31], v[184:187], v[216:219], v[28:31]
	v_mfma_f32_16x16x32_bf16 v[8:11], v[176:179], v[224:227], v[8:11]
	v_mfma_f32_16x16x32_bf16 v[12:15], v[184:187], v[224:227], v[12:15]
	s_barrier
	s_add_i32 s87, s87, 2
	s_add_u32 s10, s10, 0x10000
	s_addc_u32 s11, s11, 0
	s_cmp_gt_u32 s87, 13
.LBB0_1029:
	s_add_u32 s41, s56, s10
	s_addc_u32 s65, s57, s11
	v_add_u32_e32 v168, s50, v151
	v_add_u32_e32 v184, s51, v151
	s_add_u32 s41, s41, 0x10000
	ds_read_b128 v[156:159], v168
	ds_read_b128 v[160:163], v168 offset:1024
	ds_read_b128 v[164:167], v168 offset:2048
	ds_read_b128 v[168:171], v168 offset:3072
	ds_read_b128 v[172:175], v184
	ds_read_b128 v[176:179], v184 offset:1024
	ds_read_b128 v[180:183], v184 offset:2048
	ds_read_b128 v[184:187], v184 offset:3072
	s_addc_u32 s65, s65, 0
	s_add_u32 s70, s77, s10
	s_addc_u32 s71, s82, s11
	s_cmp_eq_u32 s10, 0x70000
	s_cselect_b32 s80, s84, s41
	s_cselect_b32 s81, s83, s65
	s_cselect_b32 s78, s86, s70
	s_cselect_b32 s79, s85, s71
	s_add_u32 s70, s80, 0x8000
	s_addc_u32 s71, s81, 0
	s_add_i32 s41, s42, 0xc000
	v_lshl_add_u64 v[196:197], v[144:145], 0, s[10:11]
	s_mov_b32 m0, s41
	s_add_i32 s65, s42, 0xe000
	ds_read_b128 v[192:195], v154
	ds_read_b128 v[200:203], v154 offset:1024
	ds_read_b128 v[204:207], v154 offset:2048
	ds_read_b128 v[208:211], v154 offset:3072
	ds_read_b128 v[212:215], v154 offset:4096
	ds_read_b128 v[216:219], v154 offset:5120
	ds_read_b128 v[220:223], v154 offset:6144
	ds_read_b128 v[224:227], v154 offset:7168
	global_load_lds_dwordx4 v[196:197], off sc1
	v_lshl_add_u64 v[196:197], v[146:147], 0, s[10:11]
	s_mov_b32 m0, s65
	s_nop 0
	global_load_lds_dwordx4 v[196:197], off sc1
	s_waitcnt vmcnt(8)
	s_waitcnt lgkmcnt(0)
	s_barrier
	s_waitcnt lgkmcnt(0)
	v_mfma_f32_16x16x32_bf16 v[112:115], v[156:159], v[192:195], v[112:115]
	v_mfma_f32_16x16x32_bf16 v[116:119], v[164:167], v[192:195], v[116:119]
	v_mfma_f32_16x16x32_bf16 v[96:99], v[156:159], v[204:207], v[96:99]
	v_mfma_f32_16x16x32_bf16 v[100:103], v[164:167], v[204:207], v[100:103]
	v_mfma_f32_16x16x32_bf16 v[80:83], v[156:159], v[212:215], v[80:83]
	v_mfma_f32_16x16x32_bf16 v[84:87], v[164:167], v[212:215], v[84:87]
	v_mfma_f32_16x16x32_bf16 v[64:67], v[156:159], v[220:223], v[64:67]
	v_mfma_f32_16x16x32_bf16 v[68:71], v[164:167], v[220:223], v[68:71]
	v_mfma_f32_16x16x32_bf16 v[112:115], v[160:163], v[200:203], v[112:115]
	v_mfma_f32_16x16x32_bf16 v[116:119], v[168:171], v[200:203], v[116:119]
	v_mfma_f32_16x16x32_bf16 v[96:99], v[160:163], v[208:211], v[96:99]
	v_mfma_f32_16x16x32_bf16 v[100:103], v[168:171], v[208:211], v[100:103]
	v_mfma_f32_16x16x32_bf16 v[80:83], v[160:163], v[216:219], v[80:83]
	v_mfma_f32_16x16x32_bf16 v[84:87], v[168:171], v[216:219], v[84:87]
	v_mfma_f32_16x16x32_bf16 v[64:67], v[160:163], v[224:227], v[64:67]
	v_mfma_f32_16x16x32_bf16 v[68:71], v[168:171], v[224:227], v[68:71]
	v_mfma_f32_16x16x32_bf16 v[120:123], v[172:175], v[192:195], v[120:123]
	v_mfma_f32_16x16x32_bf16 v[124:127], v[180:183], v[192:195], v[124:127]
	v_mfma_f32_16x16x32_bf16 v[104:107], v[172:175], v[204:207], v[104:107]
	v_mfma_f32_16x16x32_bf16 v[108:111], v[180:183], v[204:207], v[108:111]
	v_mfma_f32_16x16x32_bf16 v[88:91], v[172:175], v[212:215], v[88:91]
	v_mfma_f32_16x16x32_bf16 v[92:95], v[180:183], v[212:215], v[92:95]
	v_mfma_f32_16x16x32_bf16 v[72:75], v[172:175], v[220:223], v[72:75]
	v_mfma_f32_16x16x32_bf16 v[76:79], v[180:183], v[220:223], v[76:79]
	v_mfma_f32_16x16x32_bf16 v[120:123], v[176:179], v[200:203], v[120:123]
	v_mfma_f32_16x16x32_bf16 v[124:127], v[184:187], v[200:203], v[124:127]
	v_mfma_f32_16x16x32_bf16 v[104:107], v[176:179], v[208:211], v[104:107]
	v_mfma_f32_16x16x32_bf16 v[108:111], v[184:187], v[208:211], v[108:111]
	v_mfma_f32_16x16x32_bf16 v[88:91], v[176:179], v[216:219], v[88:91]
	v_mfma_f32_16x16x32_bf16 v[92:95], v[184:187], v[216:219], v[92:95]
	v_mfma_f32_16x16x32_bf16 v[72:75], v[176:179], v[224:227], v[72:75]
	v_mfma_f32_16x16x32_bf16 v[76:79], v[184:187], v[224:227], v[76:79]
	s_barrier
	s_add_i32 s88, s50, s35
	s_mov_b32 m0, s88
	ds_read_b128 v[192:195], v154 offset:16384
	ds_read_b128 v[200:203], v154 offset:17408
	ds_read_b128 v[204:207], v154 offset:18432
	ds_read_b128 v[208:211], v154 offset:19456
	ds_read_b128 v[212:215], v154 offset:20480
	ds_read_b128 v[216:219], v154 offset:21504
	ds_read_b128 v[220:223], v154 offset:22528
	ds_read_b128 v[224:227], v154 offset:23552
	global_load_lds_dwordx4 v132, s[78:79] sc1
	s_add_i32 m0, s88, 0x2000
	s_add_u32 s88, s78, 0x4000
	s_addc_u32 s89, s79, 0
	s_add_i32 s90, s51, s35
	global_load_lds_dwordx4 v134, s[78:79] sc1
	s_mov_b32 m0, s90
	s_nop 0
	global_load_lds_dwordx4 v132, s[88:89] sc1
	s_add_i32 m0, s90, 0x2000
	s_nop 0
	global_load_lds_dwordx4 v134, s[88:89] sc1
	s_mov_b32 m0, s42
	s_nop 0
	global_load_lds_dwordx4 v128, s[80:81] sc1
	s_mov_b32 m0, s43
	s_nop 0
	global_load_lds_dwordx4 v130, s[80:81] sc1
	s_waitcnt vmcnt(8)
	s_waitcnt lgkmcnt(0)
	s_barrier
	s_waitcnt lgkmcnt(0)
	v_mfma_f32_16x16x32_bf16 v[48:51], v[156:159], v[192:195], v[48:51]
	v_mfma_f32_16x16x32_bf16 v[52:55], v[164:167], v[192:195], v[52:55]
	v_mfma_f32_16x16x32_bf16 v[32:35], v[156:159], v[204:207], v[32:35]
	v_mfma_f32_16x16x32_bf16 v[36:39], v[164:167], v[204:207], v[36:39]
	v_mfma_f32_16x16x32_bf16 v[16:19], v[156:159], v[212:215], v[16:19]
	v_mfma_f32_16x16x32_bf16 v[20:23], v[164:167], v[212:215], v[20:23]
	v_mfma_f32_16x16x32_bf16 v[0:3], v[156:159], v[220:223], v[0:3]
	v_mfma_f32_16x16x32_bf16 v[4:7], v[164:167], v[220:223], v[4:7]
	v_mfma_f32_16x16x32_bf16 v[48:51], v[160:163], v[200:203], v[48:51]
	v_mfma_f32_16x16x32_bf16 v[52:55], v[168:171], v[200:203], v[52:55]
	v_mfma_f32_16x16x32_bf16 v[32:35], v[160:163], v[208:211], v[32:35]
	v_mfma_f32_16x16x32_bf16 v[36:39], v[168:171], v[208:211], v[36:39]
	v_mfma_f32_16x16x32_bf16 v[16:19], v[160:163], v[216:219], v[16:19]
	v_mfma_f32_16x16x32_bf16 v[20:23], v[168:171], v[216:219], v[20:23]
	v_mfma_f32_16x16x32_bf16 v[0:3], v[160:163], v[224:227], v[0:3]
	v_mfma_f32_16x16x32_bf16 v[4:7], v[168:171], v[224:227], v[4:7]
	v_mfma_f32_16x16x32_bf16 v[56:59], v[172:175], v[192:195], v[56:59]
	v_mfma_f32_16x16x32_bf16 v[60:63], v[180:183], v[192:195], v[60:63]
	v_mfma_f32_16x16x32_bf16 v[40:43], v[172:175], v[204:207], v[40:43]
	v_mfma_f32_16x16x32_bf16 v[44:47], v[180:183], v[204:207], v[44:47]
	v_mfma_f32_16x16x32_bf16 v[24:27], v[172:175], v[212:215], v[24:27]
	v_mfma_f32_16x16x32_bf16 v[28:31], v[180:183], v[212:215], v[28:31]
	v_mfma_f32_16x16x32_bf16 v[8:11], v[172:175], v[220:223], v[8:11]
	v_mfma_f32_16x16x32_bf16 v[12:15], v[180:183], v[220:223], v[12:15]
	v_mfma_f32_16x16x32_bf16 v[56:59], v[176:179], v[200:203], v[56:59]
	v_mfma_f32_16x16x32_bf16 v[60:63], v[184:187], v[200:203], v[60:63]
	v_mfma_f32_16x16x32_bf16 v[40:43], v[176:179], v[208:211], v[40:43]
	v_mfma_f32_16x16x32_bf16 v[44:47], v[184:187], v[208:211], v[44:47]
	v_mfma_f32_16x16x32_bf16 v[24:27], v[176:179], v[216:219], v[24:27]
	v_mfma_f32_16x16x32_bf16 v[28:31], v[184:187], v[216:219], v[28:31]
	v_mfma_f32_16x16x32_bf16 v[8:11], v[176:179], v[224:227], v[8:11]
	v_mfma_f32_16x16x32_bf16 v[12:15], v[184:187], v[224:227], v[12:15]
	s_barrier
	v_add_u32_e32 v168, s54, v151
	v_add_u32_e32 v184, s55, v151
	ds_read_b128 v[156:159], v168
	ds_read_b128 v[160:163], v168 offset:1024
	ds_read_b128 v[164:167], v168 offset:2048
	ds_read_b128 v[168:171], v168 offset:3072
	ds_read_b128 v[172:175], v184
	ds_read_b128 v[176:179], v184 offset:1024
	ds_read_b128 v[180:183], v184 offset:2048
	ds_read_b128 v[184:187], v184 offset:3072
	s_add_u32 s80, s80, 0x4000
	s_addc_u32 s81, s81, 0
	s_mov_b32 m0, s44
	ds_read_b128 v[192:195], v154 offset:32768
	ds_read_b128 v[200:203], v154 offset:33792
	ds_read_b128 v[204:207], v154 offset:34816
	ds_read_b128 v[208:211], v154 offset:35840
	ds_read_b128 v[212:215], v154 offset:36864
	ds_read_b128 v[216:219], v154 offset:37888
	ds_read_b128 v[220:223], v154 offset:38912
	ds_read_b128 v[224:227], v154 offset:39936
	global_load_lds_dwordx4 v128, s[80:81] sc1
	s_mov_b32 m0, s45
	s_nop 0
	global_load_lds_dwordx4 v130, s[80:81] sc1
	s_waitcnt vmcnt(8)
	s_waitcnt lgkmcnt(0)
	s_barrier
	s_waitcnt lgkmcnt(0)
	v_mfma_f32_16x16x32_bf16 v[112:115], v[156:159], v[192:195], v[112:115]
	v_mfma_f32_16x16x32_bf16 v[116:119], v[164:167], v[192:195], v[116:119]
	v_mfma_f32_16x16x32_bf16 v[96:99], v[156:159], v[204:207], v[96:99]
	v_mfma_f32_16x16x32_bf16 v[100:103], v[164:167], v[204:207], v[100:103]
	v_mfma_f32_16x16x32_bf16 v[80:83], v[156:159], v[212:215], v[80:83]
	v_mfma_f32_16x16x32_bf16 v[84:87], v[164:167], v[212:215], v[84:87]
	v_mfma_f32_16x16x32_bf16 v[64:67], v[156:159], v[220:223], v[64:67]
	v_mfma_f32_16x16x32_bf16 v[68:71], v[164:167], v[220:223], v[68:71]
	v_mfma_f32_16x16x32_bf16 v[112:115], v[160:163], v[200:203], v[112:115]
	v_mfma_f32_16x16x32_bf16 v[116:119], v[168:171], v[200:203], v[116:119]
	v_mfma_f32_16x16x32_bf16 v[96:99], v[160:163], v[208:211], v[96:99]
	v_mfma_f32_16x16x32_bf16 v[100:103], v[168:171], v[208:211], v[100:103]
	v_mfma_f32_16x16x32_bf16 v[80:83], v[160:163], v[216:219], v[80:83]
	v_mfma_f32_16x16x32_bf16 v[84:87], v[168:171], v[216:219], v[84:87]
	v_mfma_f32_16x16x32_bf16 v[64:67], v[160:163], v[224:227], v[64:67]
	v_mfma_f32_16x16x32_bf16 v[68:71], v[168:171], v[224:227], v[68:71]
	v_mfma_f32_16x16x32_bf16 v[120:123], v[172:175], v[192:195], v[120:123]
	v_mfma_f32_16x16x32_bf16 v[124:127], v[180:183], v[192:195], v[124:127]
	v_mfma_f32_16x16x32_bf16 v[104:107], v[172:175], v[204:207], v[104:107]
	v_mfma_f32_16x16x32_bf16 v[108:111], v[180:183], v[204:207], v[108:111]
	v_mfma_f32_16x16x32_bf16 v[88:91], v[172:175], v[212:215], v[88:91]
	v_mfma_f32_16x16x32_bf16 v[92:95], v[180:183], v[212:215], v[92:95]
	v_mfma_f32_16x16x32_bf16 v[72:75], v[172:175], v[220:223], v[72:75]
	v_mfma_f32_16x16x32_bf16 v[76:79], v[180:183], v[220:223], v[76:79]
	v_mfma_f32_16x16x32_bf16 v[120:123], v[176:179], v[200:203], v[120:123]
	v_mfma_f32_16x16x32_bf16 v[124:127], v[184:187], v[200:203], v[124:127]
	v_mfma_f32_16x16x32_bf16 v[104:107], v[176:179], v[208:211], v[104:107]
	v_mfma_f32_16x16x32_bf16 v[108:111], v[184:187], v[208:211], v[108:111]
	v_mfma_f32_16x16x32_bf16 v[88:91], v[176:179], v[216:219], v[88:91]
	v_mfma_f32_16x16x32_bf16 v[92:95], v[184:187], v[216:219], v[92:95]
	v_mfma_f32_16x16x32_bf16 v[72:75], v[176:179], v[224:227], v[72:75]
	v_mfma_f32_16x16x32_bf16 v[76:79], v[184:187], v[224:227], v[76:79]
	s_barrier
	s_add_u32 s80, s78, 0x8000
	s_addc_u32 s81, s79, 0
	s_add_i32 s88, s54, s35
	s_mov_b32 m0, s88
	ds_read_b128 v[192:195], v154 offset:49152
	ds_read_b128 v[200:203], v154 offset:50176
	ds_read_b128 v[204:207], v154 offset:51200
	ds_read_b128 v[208:211], v154 offset:52224
	ds_read_b128 v[212:215], v154 offset:53248
	ds_read_b128 v[216:219], v154 offset:54272
	ds_read_b128 v[220:223], v154 offset:55296
	ds_read_b128 v[224:227], v154 offset:56320
	global_load_lds_dwordx4 v132, s[80:81] sc1
	s_add_i32 m0, s88, 0x2000
	s_add_u32 s78, s78, 0xc000
	global_load_lds_dwordx4 v134, s[80:81] sc1
	s_addc_u32 s79, s79, 0
	s_add_i32 s80, s55, s35
	s_mov_b32 m0, s80
	s_nop 0
	global_load_lds_dwordx4 v132, s[78:79] sc1
	s_add_i32 m0, s80, 0x2000
	s_nop 0
	global_load_lds_dwordx4 v134, s[78:79] sc1
	s_mov_b32 m0, s47
	s_nop 0
	global_load_lds_dwordx4 v128, s[70:71] sc1
	s_mov_b32 m0, s48
	s_nop 0
	global_load_lds_dwordx4 v130, s[70:71] sc1
	s_waitcnt vmcnt(8)
	s_waitcnt lgkmcnt(0)
	s_barrier
	s_waitcnt lgkmcnt(0)
	v_mfma_f32_16x16x32_bf16 v[48:51], v[156:159], v[192:195], v[48:51]
	v_mfma_f32_16x16x32_bf16 v[52:55], v[164:167], v[192:195], v[52:55]
	v_mfma_f32_16x16x32_bf16 v[32:35], v[156:159], v[204:207], v[32:35]
	v_mfma_f32_16x16x32_bf16 v[36:39], v[164:167], v[204:207], v[36:39]
	v_mfma_f32_16x16x32_bf16 v[16:19], v[156:159], v[212:215], v[16:19]
	v_mfma_f32_16x16x32_bf16 v[20:23], v[164:167], v[212:215], v[20:23]
	v_mfma_f32_16x16x32_bf16 v[0:3], v[156:159], v[220:223], v[0:3]
	v_mfma_f32_16x16x32_bf16 v[4:7], v[164:167], v[220:223], v[4:7]
	v_mfma_f32_16x16x32_bf16 v[48:51], v[160:163], v[200:203], v[48:51]
	v_mfma_f32_16x16x32_bf16 v[52:55], v[168:171], v[200:203], v[52:55]
	v_mfma_f32_16x16x32_bf16 v[32:35], v[160:163], v[208:211], v[32:35]
	v_mfma_f32_16x16x32_bf16 v[36:39], v[168:171], v[208:211], v[36:39]
	v_mfma_f32_16x16x32_bf16 v[16:19], v[160:163], v[216:219], v[16:19]
	v_mfma_f32_16x16x32_bf16 v[20:23], v[168:171], v[216:219], v[20:23]
	v_mfma_f32_16x16x32_bf16 v[0:3], v[160:163], v[224:227], v[0:3]
	v_mfma_f32_16x16x32_bf16 v[4:7], v[168:171], v[224:227], v[4:7]
	v_mfma_f32_16x16x32_bf16 v[56:59], v[172:175], v[192:195], v[56:59]
	v_mfma_f32_16x16x32_bf16 v[60:63], v[180:183], v[192:195], v[60:63]
	v_mfma_f32_16x16x32_bf16 v[40:43], v[172:175], v[204:207], v[40:43]
	v_mfma_f32_16x16x32_bf16 v[44:47], v[180:183], v[204:207], v[44:47]
	v_mfma_f32_16x16x32_bf16 v[24:27], v[172:175], v[212:215], v[24:27]
	v_mfma_f32_16x16x32_bf16 v[28:31], v[180:183], v[212:215], v[28:31]
	v_mfma_f32_16x16x32_bf16 v[8:11], v[172:175], v[220:223], v[8:11]
	v_mfma_f32_16x16x32_bf16 v[12:15], v[180:183], v[220:223], v[12:15]
	v_mfma_f32_16x16x32_bf16 v[56:59], v[176:179], v[200:203], v[56:59]
	v_mfma_f32_16x16x32_bf16 v[60:63], v[184:187], v[200:203], v[60:63]
	v_mfma_f32_16x16x32_bf16 v[40:43], v[176:179], v[208:211], v[40:43]
	v_mfma_f32_16x16x32_bf16 v[44:47], v[184:187], v[208:211], v[44:47]
	v_mfma_f32_16x16x32_bf16 v[24:27], v[176:179], v[216:219], v[24:27]
	v_mfma_f32_16x16x32_bf16 v[28:31], v[184:187], v[216:219], v[28:31]
	v_mfma_f32_16x16x32_bf16 v[8:11], v[176:179], v[224:227], v[8:11]
	v_mfma_f32_16x16x32_bf16 v[12:15], v[184:187], v[224:227], v[12:15]
	s_barrier
	s_add_i32 s87, s87, 2
	s_add_u32 s10, s10, 0x10000
	s_addc_u32 s11, s11, 0
	s_cmp_gt_u32 s87, 13
	s_cbranch_scc0 .LBB0_1029
	s_add_u32 s10, s77, 0xffff0000
	s_addc_u32 s11, s82, -1
	s_and_b64 vcc, exec, s[8:9]
	s_cbranch_vccz .LBB0_1019
	s_mov_b64 s[62:63], s[10:11]
	s_andn2_b64 vcc, exec, s[6:7]
	s_cbranch_vccnz .LBB0_1020

.LBB0_1092:
	s_mov_b32 s54, s35
	s_add_i32 s35, s35, 1
	s_cmp_lt_u32 s35, s12
	s_mov_b64 s[40:41], s[16:17]
	s_mov_b32 s16, s61
	s_cselect_b64 s[56:57], -1, 0
	s_add_i32 s61, s35, s6
	s_mov_b64 s[18:19], s[0:1]
	s_and_b64 s[0:1], s[56:57], exec
	s_cselect_b32 s0, s58, s58
	s_cselect_b32 s16, s61, s16
	s_ashr_i32 s1, s0, 31
	s_lshl_b64 s[0:1], s[0:1], 19
	s_add_u32 s0, s60, s0
	s_addc_u32 s1, s33, s1
	s_and_b64 s[62:63], s[56:57], exec
	s_cselect_b32 s55, s1, s19
	s_cselect_b32 s69, s0, s18
	s_ashr_i32 s17, s16, 31
	s_lshl_b64 s[16:17], s[16:17], 19
	s_add_u32 s16, s66, s16
	s_addc_u32 s17, s67, s17
	s_and_b64 s[56:57], s[56:57], exec
	s_cselect_b32 s70, s17, s41
	s_cselect_b32 s71, s16, s40
	s_add_u32 s76, s40, 0x10000
	s_addc_u32 s77, s41, 0
	s_mov_b32 s78, -2
	v_add_u32_e32 v155, s47, v148
	ds_read_b128 v[156:159], v155
	ds_read_b128 v[160:163], v155 offset:1024
	ds_read_b128 v[164:167], v155 offset:2048
	ds_read_b128 v[168:171], v155 offset:3072
	v_add_u32_e32 v155, s48, v148
	ds_read_b128 v[172:175], v155
	ds_read_b128 v[176:179], v155 offset:1024
	ds_read_b128 v[180:183], v155 offset:2048
	ds_read_b128 v[184:187], v155 offset:3072
	s_add_u32 s40, s18, 0x10000
	s_addc_u32 s41, s19, 0
	s_cmp_eq_u32 s78, 12
	s_cselect_b32 s64, s69, s40
	s_cselect_b32 s65, s55, s41
	s_cselect_b32 s62, s71, s76
	s_cselect_b32 s63, s70, s77
	s_add_u32 s56, s64, 0x8000
	s_addc_u32 s57, s65, 0
	s_add_i32 m0, s37, 0xc000
	ds_read_b128 v[192:195], v154
	ds_read_b128 v[200:203], v154 offset:1024
	ds_read_b128 v[204:207], v154 offset:2048
	ds_read_b128 v[208:211], v154 offset:3072
	ds_read_b128 v[212:215], v154 offset:4096
	ds_read_b128 v[216:219], v154 offset:5120
	ds_read_b128 v[220:223], v154 offset:6144
	ds_read_b128 v[224:227], v154 offset:7168
	global_load_lds_dwordx4 v144, s[18:19] sc1
	s_add_i32 m0, s37, 0xe000
	s_nop 0
	global_load_lds_dwordx4 v146, s[18:19] sc1
	s_waitcnt vmcnt(8)
	s_waitcnt lgkmcnt(0)
	s_barrier
	s_waitcnt lgkmcnt(0)
	v_mfma_f32_16x16x32_bf16 v[116:119], v[156:159], v[192:195], 0
	v_mfma_f32_16x16x32_bf16 v[108:111], v[164:167], v[192:195], 0
	v_mfma_f32_16x16x32_bf16 v[100:103], v[156:159], v[204:207], 0
	v_mfma_f32_16x16x32_bf16 v[92:95], v[164:167], v[204:207], 0
	v_mfma_f32_16x16x32_bf16 v[84:87], v[156:159], v[212:215], 0
	v_mfma_f32_16x16x32_bf16 v[76:79], v[164:167], v[212:215], 0
	v_mfma_f32_16x16x32_bf16 v[60:63], v[156:159], v[220:223], 0
	v_mfma_f32_16x16x32_bf16 v[52:55], v[164:167], v[220:223], 0
	v_mfma_f32_16x16x32_bf16 v[116:119], v[160:163], v[200:203], v[116:119]
	v_mfma_f32_16x16x32_bf16 v[108:111], v[168:171], v[200:203], v[108:111]
	v_mfma_f32_16x16x32_bf16 v[100:103], v[160:163], v[208:211], v[100:103]
	v_mfma_f32_16x16x32_bf16 v[92:95], v[168:171], v[208:211], v[92:95]
	v_mfma_f32_16x16x32_bf16 v[84:87], v[160:163], v[216:219], v[84:87]
	v_mfma_f32_16x16x32_bf16 v[76:79], v[168:171], v[216:219], v[76:79]
	v_mfma_f32_16x16x32_bf16 v[60:63], v[160:163], v[224:227], v[60:63]
	v_mfma_f32_16x16x32_bf16 v[52:55], v[168:171], v[224:227], v[52:55]
	v_mfma_f32_16x16x32_bf16 v[124:127], v[172:175], v[192:195], 0
	v_mfma_f32_16x16x32_bf16 v[120:123], v[180:183], v[192:195], 0
	v_mfma_f32_16x16x32_bf16 v[112:115], v[172:175], v[204:207], 0
	v_mfma_f32_16x16x32_bf16 v[104:107], v[180:183], v[204:207], 0
	v_mfma_f32_16x16x32_bf16 v[96:99], v[172:175], v[212:215], 0
	v_mfma_f32_16x16x32_bf16 v[88:91], v[180:183], v[212:215], 0
	v_mfma_f32_16x16x32_bf16 v[80:83], v[172:175], v[220:223], 0
	v_mfma_f32_16x16x32_bf16 v[68:71], v[180:183], v[220:223], 0
	v_mfma_f32_16x16x32_bf16 v[124:127], v[176:179], v[200:203], v[124:127]
	v_mfma_f32_16x16x32_bf16 v[120:123], v[184:187], v[200:203], v[120:123]
	v_mfma_f32_16x16x32_bf16 v[112:115], v[176:179], v[208:211], v[112:115]
	v_mfma_f32_16x16x32_bf16 v[104:107], v[184:187], v[208:211], v[104:107]
	v_mfma_f32_16x16x32_bf16 v[96:99], v[176:179], v[216:219], v[96:99]
	v_mfma_f32_16x16x32_bf16 v[88:91], v[184:187], v[216:219], v[88:91]
	v_mfma_f32_16x16x32_bf16 v[80:83], v[176:179], v[224:227], v[80:83]
	v_mfma_f32_16x16x32_bf16 v[68:71], v[184:187], v[224:227], v[68:71]
	s_barrier
	s_add_i32 s18, s47, s36
	s_mov_b32 m0, s18
	ds_read_b128 v[192:195], v154 offset:16384
	ds_read_b128 v[200:203], v154 offset:17408
	ds_read_b128 v[204:207], v154 offset:18432
	ds_read_b128 v[208:211], v154 offset:19456
	ds_read_b128 v[212:215], v154 offset:20480
	ds_read_b128 v[216:219], v154 offset:21504
	ds_read_b128 v[220:223], v154 offset:22528
	ds_read_b128 v[224:227], v154 offset:23552
	global_load_lds_dwordx4 v132, s[62:63] sc1
	s_add_i32 m0, s18, 0x2000
	s_add_u32 s18, s62, 0x4000
	s_addc_u32 s19, s63, 0
	s_add_i32 s79, s48, s36
	global_load_lds_dwordx4 v134, s[62:63] sc1
	s_mov_b32 m0, s79
	s_nop 0
	global_load_lds_dwordx4 v132, s[18:19] sc1
	s_add_i32 m0, s79, 0x2000
	s_nop 0
	global_load_lds_dwordx4 v134, s[18:19] sc1
	s_mov_b32 m0, s37
	s_nop 0
	global_load_lds_dwordx4 v130, s[64:65] sc1
	s_mov_b32 m0, s42
	s_nop 0
	global_load_lds_dwordx4 v128, s[64:65] sc1
	s_waitcnt vmcnt(8)
	s_waitcnt lgkmcnt(0)
	s_barrier
	s_waitcnt lgkmcnt(0)
	v_mfma_f32_16x16x32_bf16 v[56:59], v[156:159], v[192:195], 0
	v_mfma_f32_16x16x32_bf16 v[44:47], v[164:167], v[192:195], 0
	v_mfma_f32_16x16x32_bf16 v[36:39], v[156:159], v[204:207], 0
	v_mfma_f32_16x16x32_bf16 v[28:31], v[164:167], v[204:207], 0
	v_mfma_f32_16x16x32_bf16 v[20:23], v[156:159], v[212:215], 0
	v_mfma_f32_16x16x32_bf16 v[12:15], v[164:167], v[212:215], 0
	v_mfma_f32_16x16x32_bf16 v[4:7], v[156:159], v[220:223], 0
	v_mfma_f32_16x16x32_bf16 v[0:3], v[164:167], v[220:223], 0
	v_mfma_f32_16x16x32_bf16 v[56:59], v[160:163], v[200:203], v[56:59]
	v_mfma_f32_16x16x32_bf16 v[44:47], v[168:171], v[200:203], v[44:47]
	v_mfma_f32_16x16x32_bf16 v[36:39], v[160:163], v[208:211], v[36:39]
	v_mfma_f32_16x16x32_bf16 v[28:31], v[168:171], v[208:211], v[28:31]
	v_mfma_f32_16x16x32_bf16 v[20:23], v[160:163], v[216:219], v[20:23]
	v_mfma_f32_16x16x32_bf16 v[12:15], v[168:171], v[216:219], v[12:15]
	v_mfma_f32_16x16x32_bf16 v[4:7], v[160:163], v[224:227], v[4:7]
	v_mfma_f32_16x16x32_bf16 v[0:3], v[168:171], v[224:227], v[0:3]
	v_mfma_f32_16x16x32_bf16 v[72:75], v[172:175], v[192:195], 0
	v_mfma_f32_16x16x32_bf16 v[64:67], v[180:183], v[192:195], 0
	v_mfma_f32_16x16x32_bf16 v[48:51], v[172:175], v[204:207], 0
	v_mfma_f32_16x16x32_bf16 v[40:43], v[180:183], v[204:207], 0
	v_mfma_f32_16x16x32_bf16 v[32:35], v[172:175], v[212:215], 0
	v_mfma_f32_16x16x32_bf16 v[24:27], v[180:183], v[212:215], 0
	v_mfma_f32_16x16x32_bf16 v[16:19], v[172:175], v[220:223], 0
	v_mfma_f32_16x16x32_bf16 v[8:11], v[180:183], v[220:223], 0
	v_mfma_f32_16x16x32_bf16 v[72:75], v[176:179], v[200:203], v[72:75]
	v_mfma_f32_16x16x32_bf16 v[64:67], v[184:187], v[200:203], v[64:67]
	v_mfma_f32_16x16x32_bf16 v[48:51], v[176:179], v[208:211], v[48:51]
	v_mfma_f32_16x16x32_bf16 v[40:43], v[184:187], v[208:211], v[40:43]
	v_mfma_f32_16x16x32_bf16 v[32:35], v[176:179], v[216:219], v[32:35]
	v_mfma_f32_16x16x32_bf16 v[24:27], v[184:187], v[216:219], v[24:27]
	v_mfma_f32_16x16x32_bf16 v[16:19], v[176:179], v[224:227], v[16:19]
	v_mfma_f32_16x16x32_bf16 v[8:11], v[184:187], v[224:227], v[8:11]
	s_barrier
	v_add_u32_e32 v155, s49, v148
	ds_read_b128 v[156:159], v155
	ds_read_b128 v[160:163], v155 offset:1024
	ds_read_b128 v[164:167], v155 offset:2048
	ds_read_b128 v[168:171], v155 offset:3072
	v_add_u32_e32 v155, s50, v148
	ds_read_b128 v[172:175], v155
	ds_read_b128 v[176:179], v155 offset:1024
	ds_read_b128 v[180:183], v155 offset:2048
	ds_read_b128 v[184:187], v155 offset:3072
	s_add_u32 s18, s64, 0x4000
	s_addc_u32 s19, s65, 0
	s_mov_b32 m0, s43
	ds_read_b128 v[192:195], v154 offset:32768
	ds_read_b128 v[200:203], v154 offset:33792
	ds_read_b128 v[204:207], v154 offset:34816
	ds_read_b128 v[208:211], v154 offset:35840
	ds_read_b128 v[212:215], v154 offset:36864
	ds_read_b128 v[216:219], v154 offset:37888
	ds_read_b128 v[220:223], v154 offset:38912
	ds_read_b128 v[224:227], v154 offset:39936
	global_load_lds_dwordx4 v130, s[18:19] sc1
	s_mov_b32 m0, s44
	s_nop 0
	global_load_lds_dwordx4 v128, s[18:19] sc1
	s_waitcnt vmcnt(8)
	s_waitcnt lgkmcnt(0)
	s_barrier
	s_waitcnt lgkmcnt(0)
	v_mfma_f32_16x16x32_bf16 v[116:119], v[156:159], v[192:195], v[116:119]
	v_mfma_f32_16x16x32_bf16 v[108:111], v[164:167], v[192:195], v[108:111]
	v_mfma_f32_16x16x32_bf16 v[100:103], v[156:159], v[204:207], v[100:103]
	v_mfma_f32_16x16x32_bf16 v[92:95], v[164:167], v[204:207], v[92:95]
	v_mfma_f32_16x16x32_bf16 v[84:87], v[156:159], v[212:215], v[84:87]
	v_mfma_f32_16x16x32_bf16 v[76:79], v[164:167], v[212:215], v[76:79]
	v_mfma_f32_16x16x32_bf16 v[60:63], v[156:159], v[220:223], v[60:63]
	v_mfma_f32_16x16x32_bf16 v[52:55], v[164:167], v[220:223], v[52:55]
	v_mfma_f32_16x16x32_bf16 v[116:119], v[160:163], v[200:203], v[116:119]
	v_mfma_f32_16x16x32_bf16 v[108:111], v[168:171], v[200:203], v[108:111]
	v_mfma_f32_16x16x32_bf16 v[100:103], v[160:163], v[208:211], v[100:103]
	v_mfma_f32_16x16x32_bf16 v[92:95], v[168:171], v[208:211], v[92:95]
	v_mfma_f32_16x16x32_bf16 v[84:87], v[160:163], v[216:219], v[84:87]
	v_mfma_f32_16x16x32_bf16 v[76:79], v[168:171], v[216:219], v[76:79]
	v_mfma_f32_16x16x32_bf16 v[60:63], v[160:163], v[224:227], v[60:63]
	v_mfma_f32_16x16x32_bf16 v[52:55], v[168:171], v[224:227], v[52:55]
	v_mfma_f32_16x16x32_bf16 v[124:127], v[172:175], v[192:195], v[124:127]
	v_mfma_f32_16x16x32_bf16 v[120:123], v[180:183], v[192:195], v[120:123]
	v_mfma_f32_16x16x32_bf16 v[112:115], v[172:175], v[204:207], v[112:115]
	v_mfma_f32_16x16x32_bf16 v[104:107], v[180:183], v[204:207], v[104:107]
	v_mfma_f32_16x16x32_bf16 v[96:99], v[172:175], v[212:215], v[96:99]
	v_mfma_f32_16x16x32_bf16 v[88:91], v[180:183], v[212:215], v[88:91]
	v_mfma_f32_16x16x32_bf16 v[80:83], v[172:175], v[220:223], v[80:83]
	v_mfma_f32_16x16x32_bf16 v[68:71], v[180:183], v[220:223], v[68:71]
	v_mfma_f32_16x16x32_bf16 v[124:127], v[176:179], v[200:203], v[124:127]
	v_mfma_f32_16x16x32_bf16 v[120:123], v[184:187], v[200:203], v[120:123]
	v_mfma_f32_16x16x32_bf16 v[112:115], v[176:179], v[208:211], v[112:115]
	v_mfma_f32_16x16x32_bf16 v[104:107], v[184:187], v[208:211], v[104:107]
	v_mfma_f32_16x16x32_bf16 v[96:99], v[176:179], v[216:219], v[96:99]
	v_mfma_f32_16x16x32_bf16 v[88:91], v[184:187], v[216:219], v[88:91]
	v_mfma_f32_16x16x32_bf16 v[80:83], v[176:179], v[224:227], v[80:83]
	v_mfma_f32_16x16x32_bf16 v[68:71], v[184:187], v[224:227], v[68:71]
	s_barrier
	s_add_u32 s18, s62, 0x8000
	s_addc_u32 s19, s63, 0
	s_add_i32 s64, s49, s36
	s_mov_b32 m0, s64
	ds_read_b128 v[192:195], v154 offset:49152
	ds_read_b128 v[200:203], v154 offset:50176
	ds_read_b128 v[204:207], v154 offset:51200
	ds_read_b128 v[208:211], v154 offset:52224
	ds_read_b128 v[212:215], v154 offset:53248
	ds_read_b128 v[216:219], v154 offset:54272
	ds_read_b128 v[220:223], v154 offset:55296
	ds_read_b128 v[224:227], v154 offset:56320
	global_load_lds_dwordx4 v132, s[18:19] sc1
	s_add_i32 m0, s64, 0x2000
	s_nop 0
	global_load_lds_dwordx4 v134, s[18:19] sc1
	s_add_u32 s18, s62, 0xc000
	s_addc_u32 s19, s63, 0
	s_add_i32 s62, s50, s36
	s_mov_b32 m0, s62
	s_nop 0
	global_load_lds_dwordx4 v132, s[18:19] sc1
	s_add_i32 m0, s62, 0x2000
	s_nop 0
	global_load_lds_dwordx4 v134, s[18:19] sc1
	s_mov_b32 m0, s7
	s_nop 0
	global_load_lds_dwordx4 v130, s[56:57] sc1
	s_mov_b32 m0, s45
	s_nop 0
	global_load_lds_dwordx4 v128, s[56:57] sc1
	s_waitcnt vmcnt(8)
	s_waitcnt lgkmcnt(0)
	s_barrier
	s_waitcnt lgkmcnt(0)
	v_mfma_f32_16x16x32_bf16 v[56:59], v[156:159], v[192:195], v[56:59]
	v_mfma_f32_16x16x32_bf16 v[44:47], v[164:167], v[192:195], v[44:47]
	v_mfma_f32_16x16x32_bf16 v[36:39], v[156:159], v[204:207], v[36:39]
	v_mfma_f32_16x16x32_bf16 v[28:31], v[164:167], v[204:207], v[28:31]
	v_mfma_f32_16x16x32_bf16 v[20:23], v[156:159], v[212:215], v[20:23]
	v_mfma_f32_16x16x32_bf16 v[12:15], v[164:167], v[212:215], v[12:15]
	v_mfma_f32_16x16x32_bf16 v[4:7], v[156:159], v[220:223], v[4:7]
	v_mfma_f32_16x16x32_bf16 v[0:3], v[164:167], v[220:223], v[0:3]
	v_mfma_f32_16x16x32_bf16 v[56:59], v[160:163], v[200:203], v[56:59]
	v_mfma_f32_16x16x32_bf16 v[44:47], v[168:171], v[200:203], v[44:47]
	v_mfma_f32_16x16x32_bf16 v[36:39], v[160:163], v[208:211], v[36:39]
	v_mfma_f32_16x16x32_bf16 v[28:31], v[168:171], v[208:211], v[28:31]
	v_mfma_f32_16x16x32_bf16 v[20:23], v[160:163], v[216:219], v[20:23]
	v_mfma_f32_16x16x32_bf16 v[12:15], v[168:171], v[216:219], v[12:15]
	v_mfma_f32_16x16x32_bf16 v[4:7], v[160:163], v[224:227], v[4:7]
	v_mfma_f32_16x16x32_bf16 v[0:3], v[168:171], v[224:227], v[0:3]
	v_mfma_f32_16x16x32_bf16 v[72:75], v[172:175], v[192:195], v[72:75]
	v_mfma_f32_16x16x32_bf16 v[64:67], v[180:183], v[192:195], v[64:67]
	v_mfma_f32_16x16x32_bf16 v[48:51], v[172:175], v[204:207], v[48:51]
	v_mfma_f32_16x16x32_bf16 v[40:43], v[180:183], v[204:207], v[40:43]
	v_mfma_f32_16x16x32_bf16 v[32:35], v[172:175], v[212:215], v[32:35]
	v_mfma_f32_16x16x32_bf16 v[24:27], v[180:183], v[212:215], v[24:27]
	v_mfma_f32_16x16x32_bf16 v[16:19], v[172:175], v[220:223], v[16:19]
	v_mfma_f32_16x16x32_bf16 v[8:11], v[180:183], v[220:223], v[8:11]
	v_mfma_f32_16x16x32_bf16 v[72:75], v[176:179], v[200:203], v[72:75]
	v_mfma_f32_16x16x32_bf16 v[64:67], v[184:187], v[200:203], v[64:67]
	v_mfma_f32_16x16x32_bf16 v[48:51], v[176:179], v[208:211], v[48:51]
	v_mfma_f32_16x16x32_bf16 v[40:43], v[184:187], v[208:211], v[40:43]
	v_mfma_f32_16x16x32_bf16 v[32:35], v[176:179], v[216:219], v[32:35]
	v_mfma_f32_16x16x32_bf16 v[24:27], v[184:187], v[216:219], v[24:27]
	v_mfma_f32_16x16x32_bf16 v[16:19], v[176:179], v[224:227], v[16:19]
	v_mfma_f32_16x16x32_bf16 v[8:11], v[184:187], v[224:227], v[8:11]
	s_barrier
	s_add_i32 s78, s78, 2
	s_add_u32 s76, s76, 0x10000
	s_addc_u32 s77, s77, 0
	s_cmp_gt_u32 s78, 13
	s_mov_b64 s[18:19], s[40:41]
.LBB0_1093:
	v_add_u32_e32 v155, s47, v148
	ds_read_b128 v[156:159], v155
	ds_read_b128 v[160:163], v155 offset:1024
	ds_read_b128 v[164:167], v155 offset:2048
	ds_read_b128 v[168:171], v155 offset:3072
	v_add_u32_e32 v155, s48, v148
	ds_read_b128 v[172:175], v155
	ds_read_b128 v[176:179], v155 offset:1024
	ds_read_b128 v[180:183], v155 offset:2048
	ds_read_b128 v[184:187], v155 offset:3072
	s_add_u32 s40, s18, 0x10000
	s_addc_u32 s41, s19, 0
	s_cmp_eq_u32 s78, 12
	s_cselect_b32 s64, s69, s40
	s_cselect_b32 s65, s55, s41
	s_cselect_b32 s62, s71, s76
	s_cselect_b32 s63, s70, s77
	s_add_u32 s56, s64, 0x8000
	s_addc_u32 s57, s65, 0
	s_add_i32 m0, s37, 0xc000
	ds_read_b128 v[192:195], v154
	ds_read_b128 v[200:203], v154 offset:1024
	ds_read_b128 v[204:207], v154 offset:2048
	ds_read_b128 v[208:211], v154 offset:3072
	ds_read_b128 v[212:215], v154 offset:4096
	ds_read_b128 v[216:219], v154 offset:5120
	ds_read_b128 v[220:223], v154 offset:6144
	ds_read_b128 v[224:227], v154 offset:7168
	global_load_lds_dwordx4 v144, s[18:19] sc1
	s_add_i32 m0, s37, 0xe000
	s_nop 0
	global_load_lds_dwordx4 v146, s[18:19] sc1
	s_waitcnt vmcnt(8)
	s_waitcnt lgkmcnt(0)
	s_barrier
	s_waitcnt lgkmcnt(0)
	v_mfma_f32_16x16x32_bf16 v[116:119], v[156:159], v[192:195], v[116:119]
	v_mfma_f32_16x16x32_bf16 v[108:111], v[164:167], v[192:195], v[108:111]
	v_mfma_f32_16x16x32_bf16 v[100:103], v[156:159], v[204:207], v[100:103]
	v_mfma_f32_16x16x32_bf16 v[92:95], v[164:167], v[204:207], v[92:95]
	v_mfma_f32_16x16x32_bf16 v[84:87], v[156:159], v[212:215], v[84:87]
	v_mfma_f32_16x16x32_bf16 v[76:79], v[164:167], v[212:215], v[76:79]
	v_mfma_f32_16x16x32_bf16 v[60:63], v[156:159], v[220:223], v[60:63]
	v_mfma_f32_16x16x32_bf16 v[52:55], v[164:167], v[220:223], v[52:55]
	v_mfma_f32_16x16x32_bf16 v[116:119], v[160:163], v[200:203], v[116:119]
	v_mfma_f32_16x16x32_bf16 v[108:111], v[168:171], v[200:203], v[108:111]
	v_mfma_f32_16x16x32_bf16 v[100:103], v[160:163], v[208:211], v[100:103]
	v_mfma_f32_16x16x32_bf16 v[92:95], v[168:171], v[208:211], v[92:95]
	v_mfma_f32_16x16x32_bf16 v[84:87], v[160:163], v[216:219], v[84:87]
	v_mfma_f32_16x16x32_bf16 v[76:79], v[168:171], v[216:219], v[76:79]
	v_mfma_f32_16x16x32_bf16 v[60:63], v[160:163], v[224:227], v[60:63]
	v_mfma_f32_16x16x32_bf16 v[52:55], v[168:171], v[224:227], v[52:55]
	v_mfma_f32_16x16x32_bf16 v[124:127], v[172:175], v[192:195], v[124:127]
	v_mfma_f32_16x16x32_bf16 v[120:123], v[180:183], v[192:195], v[120:123]
	v_mfma_f32_16x16x32_bf16 v[112:115], v[172:175], v[204:207], v[112:115]
	v_mfma_f32_16x16x32_bf16 v[104:107], v[180:183], v[204:207], v[104:107]
	v_mfma_f32_16x16x32_bf16 v[96:99], v[172:175], v[212:215], v[96:99]
	v_mfma_f32_16x16x32_bf16 v[88:91], v[180:183], v[212:215], v[88:91]
	v_mfma_f32_16x16x32_bf16 v[80:83], v[172:175], v[220:223], v[80:83]
	v_mfma_f32_16x16x32_bf16 v[68:71], v[180:183], v[220:223], v[68:71]
	v_mfma_f32_16x16x32_bf16 v[124:127], v[176:179], v[200:203], v[124:127]
	v_mfma_f32_16x16x32_bf16 v[120:123], v[184:187], v[200:203], v[120:123]
	v_mfma_f32_16x16x32_bf16 v[112:115], v[176:179], v[208:211], v[112:115]
	v_mfma_f32_16x16x32_bf16 v[104:107], v[184:187], v[208:211], v[104:107]
	v_mfma_f32_16x16x32_bf16 v[96:99], v[176:179], v[216:219], v[96:99]
	v_mfma_f32_16x16x32_bf16 v[88:91], v[184:187], v[216:219], v[88:91]
	v_mfma_f32_16x16x32_bf16 v[80:83], v[176:179], v[224:227], v[80:83]
	v_mfma_f32_16x16x32_bf16 v[68:71], v[184:187], v[224:227], v[68:71]
	s_barrier
	s_add_i32 s18, s47, s36
	s_mov_b32 m0, s18
	ds_read_b128 v[192:195], v154 offset:16384
	ds_read_b128 v[200:203], v154 offset:17408
	ds_read_b128 v[204:207], v154 offset:18432
	ds_read_b128 v[208:211], v154 offset:19456
	ds_read_b128 v[212:215], v154 offset:20480
	ds_read_b128 v[216:219], v154 offset:21504
	ds_read_b128 v[220:223], v154 offset:22528
	ds_read_b128 v[224:227], v154 offset:23552
	global_load_lds_dwordx4 v132, s[62:63] sc1
	s_add_i32 m0, s18, 0x2000
	s_add_u32 s18, s62, 0x4000
	s_addc_u32 s19, s63, 0
	s_add_i32 s79, s48, s36
	global_load_lds_dwordx4 v134, s[62:63] sc1
	s_mov_b32 m0, s79
	s_nop 0
	global_load_lds_dwordx4 v132, s[18:19] sc1
	s_add_i32 m0, s79, 0x2000
	s_nop 0
	global_load_lds_dwordx4 v134, s[18:19] sc1
	s_mov_b32 m0, s37
	s_nop 0
	global_load_lds_dwordx4 v130, s[64:65] sc1
	s_mov_b32 m0, s42
	s_nop 0
	global_load_lds_dwordx4 v128, s[64:65] sc1
	s_waitcnt vmcnt(8)
	s_waitcnt lgkmcnt(0)
	s_barrier
	s_waitcnt lgkmcnt(0)
	v_mfma_f32_16x16x32_bf16 v[56:59], v[156:159], v[192:195], v[56:59]
	v_mfma_f32_16x16x32_bf16 v[44:47], v[164:167], v[192:195], v[44:47]
	v_mfma_f32_16x16x32_bf16 v[36:39], v[156:159], v[204:207], v[36:39]
	v_mfma_f32_16x16x32_bf16 v[28:31], v[164:167], v[204:207], v[28:31]
	v_mfma_f32_16x16x32_bf16 v[20:23], v[156:159], v[212:215], v[20:23]
	v_mfma_f32_16x16x32_bf16 v[12:15], v[164:167], v[212:215], v[12:15]
	v_mfma_f32_16x16x32_bf16 v[4:7], v[156:159], v[220:223], v[4:7]
	v_mfma_f32_16x16x32_bf16 v[0:3], v[164:167], v[220:223], v[0:3]
	v_mfma_f32_16x16x32_bf16 v[56:59], v[160:163], v[200:203], v[56:59]
	v_mfma_f32_16x16x32_bf16 v[44:47], v[168:171], v[200:203], v[44:47]
	v_mfma_f32_16x16x32_bf16 v[36:39], v[160:163], v[208:211], v[36:39]
	v_mfma_f32_16x16x32_bf16 v[28:31], v[168:171], v[208:211], v[28:31]
	v_mfma_f32_16x16x32_bf16 v[20:23], v[160:163], v[216:219], v[20:23]
	v_mfma_f32_16x16x32_bf16 v[12:15], v[168:171], v[216:219], v[12:15]
	v_mfma_f32_16x16x32_bf16 v[4:7], v[160:163], v[224:227], v[4:7]
	v_mfma_f32_16x16x32_bf16 v[0:3], v[168:171], v[224:227], v[0:3]
	v_mfma_f32_16x16x32_bf16 v[72:75], v[172:175], v[192:195], v[72:75]
	v_mfma_f32_16x16x32_bf16 v[64:67], v[180:183], v[192:195], v[64:67]
	v_mfma_f32_16x16x32_bf16 v[48:51], v[172:175], v[204:207], v[48:51]
	v_mfma_f32_16x16x32_bf16 v[40:43], v[180:183], v[204:207], v[40:43]
	v_mfma_f32_16x16x32_bf16 v[32:35], v[172:175], v[212:215], v[32:35]
	v_mfma_f32_16x16x32_bf16 v[24:27], v[180:183], v[212:215], v[24:27]
	v_mfma_f32_16x16x32_bf16 v[16:19], v[172:175], v[220:223], v[16:19]
	v_mfma_f32_16x16x32_bf16 v[8:11], v[180:183], v[220:223], v[8:11]
	v_mfma_f32_16x16x32_bf16 v[72:75], v[176:179], v[200:203], v[72:75]
	v_mfma_f32_16x16x32_bf16 v[64:67], v[184:187], v[200:203], v[64:67]
	v_mfma_f32_16x16x32_bf16 v[48:51], v[176:179], v[208:211], v[48:51]
	v_mfma_f32_16x16x32_bf16 v[40:43], v[184:187], v[208:211], v[40:43]
	v_mfma_f32_16x16x32_bf16 v[32:35], v[176:179], v[216:219], v[32:35]
	v_mfma_f32_16x16x32_bf16 v[24:27], v[184:187], v[216:219], v[24:27]
	v_mfma_f32_16x16x32_bf16 v[16:19], v[176:179], v[224:227], v[16:19]
	v_mfma_f32_16x16x32_bf16 v[8:11], v[184:187], v[224:227], v[8:11]
	s_barrier
	v_add_u32_e32 v155, s49, v148
	ds_read_b128 v[156:159], v155
	ds_read_b128 v[160:163], v155 offset:1024
	ds_read_b128 v[164:167], v155 offset:2048
	ds_read_b128 v[168:171], v155 offset:3072
	v_add_u32_e32 v155, s50, v148
	ds_read_b128 v[172:175], v155
	ds_read_b128 v[176:179], v155 offset:1024
	ds_read_b128 v[180:183], v155 offset:2048
	ds_read_b128 v[184:187], v155 offset:3072
	s_add_u32 s18, s64, 0x4000
	s_addc_u32 s19, s65, 0
	s_mov_b32 m0, s43
	ds_read_b128 v[192:195], v154 offset:32768
	ds_read_b128 v[200:203], v154 offset:33792
	ds_read_b128 v[204:207], v154 offset:34816
	ds_read_b128 v[208:211], v154 offset:35840
	ds_read_b128 v[212:215], v154 offset:36864
	ds_read_b128 v[216:219], v154 offset:37888
	ds_read_b128 v[220:223], v154 offset:38912
	ds_read_b128 v[224:227], v154 offset:39936
	global_load_lds_dwordx4 v130, s[18:19] sc1
	s_mov_b32 m0, s44
	s_nop 0
	global_load_lds_dwordx4 v128, s[18:19] sc1
	s_waitcnt vmcnt(8)
	s_waitcnt lgkmcnt(0)
	s_barrier
	s_waitcnt lgkmcnt(0)
	v_mfma_f32_16x16x32_bf16 v[116:119], v[156:159], v[192:195], v[116:119]
	v_mfma_f32_16x16x32_bf16 v[108:111], v[164:167], v[192:195], v[108:111]
	v_mfma_f32_16x16x32_bf16 v[100:103], v[156:159], v[204:207], v[100:103]
	v_mfma_f32_16x16x32_bf16 v[92:95], v[164:167], v[204:207], v[92:95]
	v_mfma_f32_16x16x32_bf16 v[84:87], v[156:159], v[212:215], v[84:87]
	v_mfma_f32_16x16x32_bf16 v[76:79], v[164:167], v[212:215], v[76:79]
	v_mfma_f32_16x16x32_bf16 v[60:63], v[156:159], v[220:223], v[60:63]
	v_mfma_f32_16x16x32_bf16 v[52:55], v[164:167], v[220:223], v[52:55]
	v_mfma_f32_16x16x32_bf16 v[116:119], v[160:163], v[200:203], v[116:119]
	v_mfma_f32_16x16x32_bf16 v[108:111], v[168:171], v[200:203], v[108:111]
	v_mfma_f32_16x16x32_bf16 v[100:103], v[160:163], v[208:211], v[100:103]
	v_mfma_f32_16x16x32_bf16 v[92:95], v[168:171], v[208:211], v[92:95]
	v_mfma_f32_16x16x32_bf16 v[84:87], v[160:163], v[216:219], v[84:87]
	v_mfma_f32_16x16x32_bf16 v[76:79], v[168:171], v[216:219], v[76:79]
	v_mfma_f32_16x16x32_bf16 v[60:63], v[160:163], v[224:227], v[60:63]
	v_mfma_f32_16x16x32_bf16 v[52:55], v[168:171], v[224:227], v[52:55]
	v_mfma_f32_16x16x32_bf16 v[124:127], v[172:175], v[192:195], v[124:127]
	v_mfma_f32_16x16x32_bf16 v[120:123], v[180:183], v[192:195], v[120:123]
	v_mfma_f32_16x16x32_bf16 v[112:115], v[172:175], v[204:207], v[112:115]
	v_mfma_f32_16x16x32_bf16 v[104:107], v[180:183], v[204:207], v[104:107]
	v_mfma_f32_16x16x32_bf16 v[96:99], v[172:175], v[212:215], v[96:99]
	v_mfma_f32_16x16x32_bf16 v[88:91], v[180:183], v[212:215], v[88:91]
	v_mfma_f32_16x16x32_bf16 v[80:83], v[172:175], v[220:223], v[80:83]
	v_mfma_f32_16x16x32_bf16 v[68:71], v[180:183], v[220:223], v[68:71]
	v_mfma_f32_16x16x32_bf16 v[124:127], v[176:179], v[200:203], v[124:127]
	v_mfma_f32_16x16x32_bf16 v[120:123], v[184:187], v[200:203], v[120:123]
	v_mfma_f32_16x16x32_bf16 v[112:115], v[176:179], v[208:211], v[112:115]
	v_mfma_f32_16x16x32_bf16 v[104:107], v[184:187], v[208:211], v[104:107]
	v_mfma_f32_16x16x32_bf16 v[96:99], v[176:179], v[216:219], v[96:99]
	v_mfma_f32_16x16x32_bf16 v[88:91], v[184:187], v[216:219], v[88:91]
	v_mfma_f32_16x16x32_bf16 v[80:83], v[176:179], v[224:227], v[80:83]
	v_mfma_f32_16x16x32_bf16 v[68:71], v[184:187], v[224:227], v[68:71]
	s_barrier
	s_add_u32 s18, s62, 0x8000
	s_addc_u32 s19, s63, 0
	s_add_i32 s64, s49, s36
	s_mov_b32 m0, s64
	ds_read_b128 v[192:195], v154 offset:49152
	ds_read_b128 v[200:203], v154 offset:50176
	ds_read_b128 v[204:207], v154 offset:51200
	ds_read_b128 v[208:211], v154 offset:52224
	ds_read_b128 v[212:215], v154 offset:53248
	ds_read_b128 v[216:219], v154 offset:54272
	ds_read_b128 v[220:223], v154 offset:55296
	ds_read_b128 v[224:227], v154 offset:56320
	global_load_lds_dwordx4 v132, s[18:19] sc1
	s_add_i32 m0, s64, 0x2000
	s_nop 0
	global_load_lds_dwordx4 v134, s[18:19] sc1
	s_add_u32 s18, s62, 0xc000
	s_addc_u32 s19, s63, 0
	s_add_i32 s62, s50, s36
	s_mov_b32 m0, s62
	s_nop 0
	global_load_lds_dwordx4 v132, s[18:19] sc1
	s_add_i32 m0, s62, 0x2000
	s_nop 0
	global_load_lds_dwordx4 v134, s[18:19] sc1
	s_mov_b32 m0, s7
	s_nop 0
	global_load_lds_dwordx4 v130, s[56:57] sc1
	s_mov_b32 m0, s45
	s_nop 0
	global_load_lds_dwordx4 v128, s[56:57] sc1
	s_waitcnt vmcnt(8)
	s_waitcnt lgkmcnt(0)
	s_barrier
	s_waitcnt lgkmcnt(0)
	v_mfma_f32_16x16x32_bf16 v[56:59], v[156:159], v[192:195], v[56:59]
	v_mfma_f32_16x16x32_bf16 v[44:47], v[164:167], v[192:195], v[44:47]
	v_mfma_f32_16x16x32_bf16 v[36:39], v[156:159], v[204:207], v[36:39]
	v_mfma_f32_16x16x32_bf16 v[28:31], v[164:167], v[204:207], v[28:31]
	v_mfma_f32_16x16x32_bf16 v[20:23], v[156:159], v[212:215], v[20:23]
	v_mfma_f32_16x16x32_bf16 v[12:15], v[164:167], v[212:215], v[12:15]
	v_mfma_f32_16x16x32_bf16 v[4:7], v[156:159], v[220:223], v[4:7]
	v_mfma_f32_16x16x32_bf16 v[0:3], v[164:167], v[220:223], v[0:3]
	v_mfma_f32_16x16x32_bf16 v[56:59], v[160:163], v[200:203], v[56:59]
	v_mfma_f32_16x16x32_bf16 v[44:47], v[168:171], v[200:203], v[44:47]
	v_mfma_f32_16x16x32_bf16 v[36:39], v[160:163], v[208:211], v[36:39]
	v_mfma_f32_16x16x32_bf16 v[28:31], v[168:171], v[208:211], v[28:31]
	v_mfma_f32_16x16x32_bf16 v[20:23], v[160:163], v[216:219], v[20:23]
	v_mfma_f32_16x16x32_bf16 v[12:15], v[168:171], v[216:219], v[12:15]
	v_mfma_f32_16x16x32_bf16 v[4:7], v[160:163], v[224:227], v[4:7]
	v_mfma_f32_16x16x32_bf16 v[0:3], v[168:171], v[224:227], v[0:3]
	v_mfma_f32_16x16x32_bf16 v[72:75], v[172:175], v[192:195], v[72:75]
	v_mfma_f32_16x16x32_bf16 v[64:67], v[180:183], v[192:195], v[64:67]
	v_mfma_f32_16x16x32_bf16 v[48:51], v[172:175], v[204:207], v[48:51]
	v_mfma_f32_16x16x32_bf16 v[40:43], v[180:183], v[204:207], v[40:43]
	v_mfma_f32_16x16x32_bf16 v[32:35], v[172:175], v[212:215], v[32:35]
	v_mfma_f32_16x16x32_bf16 v[24:27], v[180:183], v[212:215], v[24:27]
	v_mfma_f32_16x16x32_bf16 v[16:19], v[172:175], v[220:223], v[16:19]
	v_mfma_f32_16x16x32_bf16 v[8:11], v[180:183], v[220:223], v[8:11]
	v_mfma_f32_16x16x32_bf16 v[72:75], v[176:179], v[200:203], v[72:75]
	v_mfma_f32_16x16x32_bf16 v[64:67], v[184:187], v[200:203], v[64:67]
	v_mfma_f32_16x16x32_bf16 v[48:51], v[176:179], v[208:211], v[48:51]
	v_mfma_f32_16x16x32_bf16 v[40:43], v[184:187], v[208:211], v[40:43]
	v_mfma_f32_16x16x32_bf16 v[32:35], v[176:179], v[216:219], v[32:35]
	v_mfma_f32_16x16x32_bf16 v[24:27], v[184:187], v[216:219], v[24:27]
	v_mfma_f32_16x16x32_bf16 v[16:19], v[176:179], v[224:227], v[16:19]
	v_mfma_f32_16x16x32_bf16 v[8:11], v[184:187], v[224:227], v[8:11]
	s_barrier
	s_add_i32 s78, s78, 2
	s_add_u32 s76, s76, 0x10000
	s_addc_u32 s77, s77, 0
	s_cmp_gt_u32 s78, 13
	s_mov_b64 s[18:19], s[40:41]
	s_cbranch_scc0 .LBB0_1093
	s_and_b64 vcc, exec, s[10:11]
	s_cbranch_vccz .LBB0_1096
	s_barrier

.LBB0_1248:
	s_add_u32 s49, s18, 0x10000
	s_addc_u32 s50, s19, 0
	s_lshl_b32 s18, s8, 2
	s_ashr_i32 s11, s10, 31
	s_ashr_i32 s19, s18, 31
	s_lshl_b64 s[20:21], s[10:11], 19
	s_lshl_b64 s[18:19], s[18:19], 15
	s_add_u32 s11, s60, s18
	s_addc_u32 s18, s33, s19
	s_add_u32 s11, s11, s20
	s_addc_u32 s18, s18, s21
	s_add_u32 s19, s11, 0x10000
	s_addc_u32 s20, s18, 0
	s_and_b64 s[6:7], s[6:7], exec
	s_cselect_b32 s51, s17, s20
	s_cselect_b32 s52, s16, s19
	s_cselect_b32 s53, s15, s18
	s_cselect_b32 s54, s14, s11
	v_lshl_add_u64 v[144:145], s[12:13], 0, v[8:9]
	v_lshl_add_u64 v[146:147], s[12:13], 0, v[10:11]
	s_mov_b32 s55, -2
	s_mov_b64 s[6:7], 0
	s_add_u32 s11, s12, s6
	v_add_u32_e32 v160, s40, v150
	s_addc_u32 s18, s13, s7
	ds_read_b128 v[152:155], v160
	ds_read_b128 v[156:159], v160 offset:1024
	ds_read_b128 v[164:167], v160 offset:2048
	ds_read_b128 v[168:171], v160 offset:3072
	v_add_u32_e32 v160, s41, v150
	s_add_u32 s11, s11, 0x10000
	ds_read_b128 v[172:175], v160
	ds_read_b128 v[182:185], v160 offset:1024
	ds_read_b128 v[190:193], v160 offset:2048
	ds_read_b128 v[194:197], v160 offset:3072
	s_addc_u32 s18, s18, 0
	s_add_u32 s19, s49, s6
	s_addc_u32 s21, s50, s7
	s_cmp_eq_u32 s6, 0x150000
	s_cselect_b32 s22, s52, s11
	s_cselect_b32 s23, s51, s18
	s_cselect_b32 s20, s54, s19
	s_cselect_b32 s21, s53, s21
	s_add_u32 s18, s22, 0x8000
	s_addc_u32 s19, s23, 0
	s_add_i32 s11, s29, 0xc000
	v_lshl_add_u64 v[160:161], v[144:145], 0, s[6:7]
	s_mov_b32 m0, s11
	s_add_i32 s48, s29, 0xe000
	ds_read_b128 v[198:201], v151
	ds_read_b128 v[202:205], v151 offset:1024
	ds_read_b128 v[206:209], v151 offset:2048
	ds_read_b128 v[210:213], v151 offset:3072
	ds_read_b128 v[214:217], v151 offset:4096
	ds_read_b128 v[218:221], v151 offset:5120
	ds_read_b128 v[222:225], v151 offset:6144
	ds_read_b128 v[226:229], v151 offset:7168
	global_load_lds_dwordx4 v[160:161], off sc1
	v_lshl_add_u64 v[160:161], v[146:147], 0, s[6:7]
	s_mov_b32 m0, s48
	s_nop 0
	global_load_lds_dwordx4 v[160:161], off sc1
	s_waitcnt vmcnt(8)
	s_waitcnt lgkmcnt(0)
	s_barrier
	s_waitcnt lgkmcnt(0)
	v_mfma_f32_16x16x32_bf16 v[128:131], v[152:155], v[198:201], 0
	v_mfma_f32_16x16x32_bf16 v[132:135], v[164:167], v[198:201], 0
	v_mfma_f32_16x16x32_bf16 v[112:115], v[152:155], v[206:209], 0
	v_mfma_f32_16x16x32_bf16 v[116:119], v[164:167], v[206:209], 0
	v_mfma_f32_16x16x32_bf16 v[96:99], v[152:155], v[214:217], 0
	v_mfma_f32_16x16x32_bf16 v[100:103], v[164:167], v[214:217], 0
	v_mfma_f32_16x16x32_bf16 v[72:75], v[152:155], v[222:225], 0
	v_mfma_f32_16x16x32_bf16 v[76:79], v[164:167], v[222:225], 0
	v_mfma_f32_16x16x32_bf16 v[128:131], v[156:159], v[202:205], v[128:131]
	v_mfma_f32_16x16x32_bf16 v[132:135], v[168:171], v[202:205], v[132:135]
	v_mfma_f32_16x16x32_bf16 v[112:115], v[156:159], v[210:213], v[112:115]
	v_mfma_f32_16x16x32_bf16 v[116:119], v[168:171], v[210:213], v[116:119]
	v_mfma_f32_16x16x32_bf16 v[96:99], v[156:159], v[218:221], v[96:99]
	v_mfma_f32_16x16x32_bf16 v[100:103], v[168:171], v[218:221], v[100:103]
	v_mfma_f32_16x16x32_bf16 v[72:75], v[156:159], v[226:229], v[72:75]
	v_mfma_f32_16x16x32_bf16 v[76:79], v[168:171], v[226:229], v[76:79]
	v_mfma_f32_16x16x32_bf16 v[136:139], v[172:175], v[198:201], 0
	v_mfma_f32_16x16x32_bf16 v[140:143], v[190:193], v[198:201], 0
	v_mfma_f32_16x16x32_bf16 v[120:123], v[172:175], v[206:209], 0
	v_mfma_f32_16x16x32_bf16 v[124:127], v[190:193], v[206:209], 0
	v_mfma_f32_16x16x32_bf16 v[104:107], v[172:175], v[214:217], 0
	v_mfma_f32_16x16x32_bf16 v[108:111], v[190:193], v[214:217], 0
	v_mfma_f32_16x16x32_bf16 v[88:91], v[172:175], v[222:225], 0
	v_mfma_f32_16x16x32_bf16 v[92:95], v[190:193], v[222:225], 0
	v_mfma_f32_16x16x32_bf16 v[136:139], v[182:185], v[202:205], v[136:139]
	v_mfma_f32_16x16x32_bf16 v[140:143], v[194:197], v[202:205], v[140:143]
	v_mfma_f32_16x16x32_bf16 v[120:123], v[182:185], v[210:213], v[120:123]
	v_mfma_f32_16x16x32_bf16 v[124:127], v[194:197], v[210:213], v[124:127]
	v_mfma_f32_16x16x32_bf16 v[104:107], v[182:185], v[218:221], v[104:107]
	v_mfma_f32_16x16x32_bf16 v[108:111], v[194:197], v[218:221], v[108:111]
	v_mfma_f32_16x16x32_bf16 v[88:91], v[182:185], v[226:229], v[88:91]
	v_mfma_f32_16x16x32_bf16 v[92:95], v[194:197], v[226:229], v[92:95]
	s_barrier
	s_add_i32 s56, s40, s27
	s_mov_b32 m0, s56
	ds_read_b128 v[198:201], v151 offset:16384
	ds_read_b128 v[202:205], v151 offset:17408
	ds_read_b128 v[206:209], v151 offset:18432
	ds_read_b128 v[210:213], v151 offset:19456
	ds_read_b128 v[214:217], v151 offset:20480
	ds_read_b128 v[218:221], v151 offset:21504
	ds_read_b128 v[222:225], v151 offset:22528
	ds_read_b128 v[226:229], v151 offset:23552
	global_load_lds_dwordx4 v2, s[20:21] sc1
	s_add_i32 m0, s56, 0x2000
	s_add_u32 s56, s20, 0x4000
	s_addc_u32 s57, s21, 0
	s_add_i32 s58, s41, s27
	global_load_lds_dwordx4 v6, s[20:21] sc1
	s_mov_b32 m0, s58
	s_nop 0
	global_load_lds_dwordx4 v2, s[56:57] sc1
	s_add_i32 m0, s58, 0x2000
	s_nop 0
	global_load_lds_dwordx4 v6, s[56:57] sc1
	s_mov_b32 m0, s29
	s_nop 0
	global_load_lds_dwordx4 v0, s[22:23] sc1
	s_mov_b32 m0, s30
	s_nop 0
	global_load_lds_dwordx4 v4, s[22:23] sc1
	s_waitcnt vmcnt(8)
	s_waitcnt lgkmcnt(0)
	s_barrier
	s_waitcnt lgkmcnt(0)
	v_mfma_f32_16x16x32_bf16 v[64:67], v[152:155], v[198:201], 0
	v_mfma_f32_16x16x32_bf16 v[68:71], v[164:167], v[198:201], 0
	v_mfma_f32_16x16x32_bf16 v[48:51], v[152:155], v[206:209], 0
	v_mfma_f32_16x16x32_bf16 v[52:55], v[164:167], v[206:209], 0
	v_mfma_f32_16x16x32_bf16 v[32:35], v[152:155], v[214:217], 0
	v_mfma_f32_16x16x32_bf16 v[36:39], v[164:167], v[214:217], 0
	v_mfma_f32_16x16x32_bf16 v[16:19], v[152:155], v[222:225], 0
	v_mfma_f32_16x16x32_bf16 v[20:23], v[164:167], v[222:225], 0
	v_mfma_f32_16x16x32_bf16 v[64:67], v[156:159], v[202:205], v[64:67]
	v_mfma_f32_16x16x32_bf16 v[68:71], v[168:171], v[202:205], v[68:71]
	v_mfma_f32_16x16x32_bf16 v[48:51], v[156:159], v[210:213], v[48:51]
	v_mfma_f32_16x16x32_bf16 v[52:55], v[168:171], v[210:213], v[52:55]
	v_mfma_f32_16x16x32_bf16 v[32:35], v[156:159], v[218:221], v[32:35]
	v_mfma_f32_16x16x32_bf16 v[36:39], v[168:171], v[218:221], v[36:39]
	v_mfma_f32_16x16x32_bf16 v[16:19], v[156:159], v[226:229], v[16:19]
	v_mfma_f32_16x16x32_bf16 v[20:23], v[168:171], v[226:229], v[20:23]
	v_mfma_f32_16x16x32_bf16 v[80:83], v[172:175], v[198:201], 0
	v_mfma_f32_16x16x32_bf16 v[84:87], v[190:193], v[198:201], 0
	v_mfma_f32_16x16x32_bf16 v[56:59], v[172:175], v[206:209], 0
	v_mfma_f32_16x16x32_bf16 v[60:63], v[190:193], v[206:209], 0
	v_mfma_f32_16x16x32_bf16 v[40:43], v[172:175], v[214:217], 0
	v_mfma_f32_16x16x32_bf16 v[44:47], v[190:193], v[214:217], 0
	v_mfma_f32_16x16x32_bf16 v[24:27], v[172:175], v[222:225], 0
	v_mfma_f32_16x16x32_bf16 v[28:31], v[190:193], v[222:225], 0
	v_mfma_f32_16x16x32_bf16 v[80:83], v[182:185], v[202:205], v[80:83]
	v_mfma_f32_16x16x32_bf16 v[84:87], v[194:197], v[202:205], v[84:87]
	v_mfma_f32_16x16x32_bf16 v[56:59], v[182:185], v[210:213], v[56:59]
	v_mfma_f32_16x16x32_bf16 v[60:63], v[194:197], v[210:213], v[60:63]
	v_mfma_f32_16x16x32_bf16 v[40:43], v[182:185], v[218:221], v[40:43]
	v_mfma_f32_16x16x32_bf16 v[44:47], v[194:197], v[218:221], v[44:47]
	v_mfma_f32_16x16x32_bf16 v[24:27], v[182:185], v[226:229], v[24:27]
	v_mfma_f32_16x16x32_bf16 v[28:31], v[194:197], v[226:229], v[28:31]
	s_barrier
	v_add_u32_e32 v160, s43, v150
	ds_read_b128 v[152:155], v160
	ds_read_b128 v[156:159], v160 offset:1024
	ds_read_b128 v[164:167], v160 offset:2048
	ds_read_b128 v[168:171], v160 offset:3072
	v_add_u32_e32 v160, s44, v150
	ds_read_b128 v[172:175], v160
	ds_read_b128 v[182:185], v160 offset:1024
	ds_read_b128 v[190:193], v160 offset:2048
	ds_read_b128 v[194:197], v160 offset:3072
	s_add_u32 s22, s22, 0x4000
	s_addc_u32 s23, s23, 0
	s_mov_b32 m0, s31
	ds_read_b128 v[198:201], v151 offset:32768
	ds_read_b128 v[202:205], v151 offset:33792
	ds_read_b128 v[206:209], v151 offset:34816
	ds_read_b128 v[210:213], v151 offset:35840
	ds_read_b128 v[214:217], v151 offset:36864
	ds_read_b128 v[218:221], v151 offset:37888
	ds_read_b128 v[222:225], v151 offset:38912
	ds_read_b128 v[226:229], v151 offset:39936
	global_load_lds_dwordx4 v0, s[22:23] sc1
	s_mov_b32 m0, s35
	s_nop 0
	global_load_lds_dwordx4 v4, s[22:23] sc1
	s_waitcnt vmcnt(8)
	s_waitcnt lgkmcnt(0)
	s_barrier
	s_waitcnt lgkmcnt(0)
	v_mfma_f32_16x16x32_bf16 v[128:131], v[152:155], v[198:201], v[128:131]
	v_mfma_f32_16x16x32_bf16 v[132:135], v[164:167], v[198:201], v[132:135]
	v_mfma_f32_16x16x32_bf16 v[112:115], v[152:155], v[206:209], v[112:115]
	v_mfma_f32_16x16x32_bf16 v[116:119], v[164:167], v[206:209], v[116:119]
	v_mfma_f32_16x16x32_bf16 v[96:99], v[152:155], v[214:217], v[96:99]
	v_mfma_f32_16x16x32_bf16 v[100:103], v[164:167], v[214:217], v[100:103]
	v_mfma_f32_16x16x32_bf16 v[72:75], v[152:155], v[222:225], v[72:75]
	v_mfma_f32_16x16x32_bf16 v[76:79], v[164:167], v[222:225], v[76:79]
	v_mfma_f32_16x16x32_bf16 v[128:131], v[156:159], v[202:205], v[128:131]
	v_mfma_f32_16x16x32_bf16 v[132:135], v[168:171], v[202:205], v[132:135]
	v_mfma_f32_16x16x32_bf16 v[112:115], v[156:159], v[210:213], v[112:115]
	v_mfma_f32_16x16x32_bf16 v[116:119], v[168:171], v[210:213], v[116:119]
	v_mfma_f32_16x16x32_bf16 v[96:99], v[156:159], v[218:221], v[96:99]
	v_mfma_f32_16x16x32_bf16 v[100:103], v[168:171], v[218:221], v[100:103]
	v_mfma_f32_16x16x32_bf16 v[72:75], v[156:159], v[226:229], v[72:75]
	v_mfma_f32_16x16x32_bf16 v[76:79], v[168:171], v[226:229], v[76:79]
	v_mfma_f32_16x16x32_bf16 v[136:139], v[172:175], v[198:201], v[136:139]
	v_mfma_f32_16x16x32_bf16 v[140:143], v[190:193], v[198:201], v[140:143]
	v_mfma_f32_16x16x32_bf16 v[120:123], v[172:175], v[206:209], v[120:123]
	v_mfma_f32_16x16x32_bf16 v[124:127], v[190:193], v[206:209], v[124:127]
	v_mfma_f32_16x16x32_bf16 v[104:107], v[172:175], v[214:217], v[104:107]
	v_mfma_f32_16x16x32_bf16 v[108:111], v[190:193], v[214:217], v[108:111]
	v_mfma_f32_16x16x32_bf16 v[88:91], v[172:175], v[222:225], v[88:91]
	v_mfma_f32_16x16x32_bf16 v[92:95], v[190:193], v[222:225], v[92:95]
	v_mfma_f32_16x16x32_bf16 v[136:139], v[182:185], v[202:205], v[136:139]
	v_mfma_f32_16x16x32_bf16 v[140:143], v[194:197], v[202:205], v[140:143]
	v_mfma_f32_16x16x32_bf16 v[120:123], v[182:185], v[210:213], v[120:123]
	v_mfma_f32_16x16x32_bf16 v[124:127], v[194:197], v[210:213], v[124:127]
	v_mfma_f32_16x16x32_bf16 v[104:107], v[182:185], v[218:221], v[104:107]
	v_mfma_f32_16x16x32_bf16 v[108:111], v[194:197], v[218:221], v[108:111]
	v_mfma_f32_16x16x32_bf16 v[88:91], v[182:185], v[226:229], v[88:91]
	v_mfma_f32_16x16x32_bf16 v[92:95], v[194:197], v[226:229], v[92:95]
	s_barrier
	s_add_u32 s22, s20, 0x8000
	s_addc_u32 s23, s21, 0
	s_add_i32 s56, s43, s27
	s_mov_b32 m0, s56
	ds_read_b128 v[198:201], v151 offset:49152
	ds_read_b128 v[202:205], v151 offset:50176
	ds_read_b128 v[206:209], v151 offset:51200
	ds_read_b128 v[210:213], v151 offset:52224
	ds_read_b128 v[214:217], v151 offset:53248
	ds_read_b128 v[218:221], v151 offset:54272
	ds_read_b128 v[222:225], v151 offset:55296
	ds_read_b128 v[226:229], v151 offset:56320
	global_load_lds_dwordx4 v2, s[22:23] sc1
	s_add_i32 m0, s56, 0x2000
	s_add_u32 s20, s20, 0xc000
	global_load_lds_dwordx4 v6, s[22:23] sc1
	s_addc_u32 s21, s21, 0
	s_add_i32 s22, s44, s27
	s_mov_b32 m0, s22
	s_nop 0
	global_load_lds_dwordx4 v2, s[20:21] sc1
	s_add_i32 m0, s22, 0x2000
	s_nop 0
	global_load_lds_dwordx4 v6, s[20:21] sc1
	s_mov_b32 m0, s38
	s_nop 0
	global_load_lds_dwordx4 v0, s[18:19] sc1
	s_mov_b32 m0, s39
	s_nop 0
	global_load_lds_dwordx4 v4, s[18:19] sc1
	s_waitcnt vmcnt(8)
	s_waitcnt lgkmcnt(0)
	s_barrier
	s_waitcnt lgkmcnt(0)
	v_mfma_f32_16x16x32_bf16 v[64:67], v[152:155], v[198:201], v[64:67]
	v_mfma_f32_16x16x32_bf16 v[68:71], v[164:167], v[198:201], v[68:71]
	v_mfma_f32_16x16x32_bf16 v[48:51], v[152:155], v[206:209], v[48:51]
	v_mfma_f32_16x16x32_bf16 v[52:55], v[164:167], v[206:209], v[52:55]
	v_mfma_f32_16x16x32_bf16 v[32:35], v[152:155], v[214:217], v[32:35]
	v_mfma_f32_16x16x32_bf16 v[36:39], v[164:167], v[214:217], v[36:39]
	v_mfma_f32_16x16x32_bf16 v[16:19], v[152:155], v[222:225], v[16:19]
	v_mfma_f32_16x16x32_bf16 v[20:23], v[164:167], v[222:225], v[20:23]
	v_mfma_f32_16x16x32_bf16 v[64:67], v[156:159], v[202:205], v[64:67]
	v_mfma_f32_16x16x32_bf16 v[68:71], v[168:171], v[202:205], v[68:71]
	v_mfma_f32_16x16x32_bf16 v[48:51], v[156:159], v[210:213], v[48:51]
	v_mfma_f32_16x16x32_bf16 v[52:55], v[168:171], v[210:213], v[52:55]
	v_mfma_f32_16x16x32_bf16 v[32:35], v[156:159], v[218:221], v[32:35]
	v_mfma_f32_16x16x32_bf16 v[36:39], v[168:171], v[218:221], v[36:39]
	v_mfma_f32_16x16x32_bf16 v[16:19], v[156:159], v[226:229], v[16:19]
	v_mfma_f32_16x16x32_bf16 v[20:23], v[168:171], v[226:229], v[20:23]
	v_mfma_f32_16x16x32_bf16 v[80:83], v[172:175], v[198:201], v[80:83]
	v_mfma_f32_16x16x32_bf16 v[84:87], v[190:193], v[198:201], v[84:87]
	v_mfma_f32_16x16x32_bf16 v[56:59], v[172:175], v[206:209], v[56:59]
	v_mfma_f32_16x16x32_bf16 v[60:63], v[190:193], v[206:209], v[60:63]
	v_mfma_f32_16x16x32_bf16 v[40:43], v[172:175], v[214:217], v[40:43]
	v_mfma_f32_16x16x32_bf16 v[44:47], v[190:193], v[214:217], v[44:47]
	v_mfma_f32_16x16x32_bf16 v[24:27], v[172:175], v[222:225], v[24:27]
	v_mfma_f32_16x16x32_bf16 v[28:31], v[190:193], v[222:225], v[28:31]
	v_mfma_f32_16x16x32_bf16 v[80:83], v[182:185], v[202:205], v[80:83]
	v_mfma_f32_16x16x32_bf16 v[84:87], v[194:197], v[202:205], v[84:87]
	v_mfma_f32_16x16x32_bf16 v[56:59], v[182:185], v[210:213], v[56:59]
	v_mfma_f32_16x16x32_bf16 v[60:63], v[194:197], v[210:213], v[60:63]
	v_mfma_f32_16x16x32_bf16 v[40:43], v[182:185], v[218:221], v[40:43]
	v_mfma_f32_16x16x32_bf16 v[44:47], v[194:197], v[218:221], v[44:47]
	v_mfma_f32_16x16x32_bf16 v[24:27], v[182:185], v[226:229], v[24:27]
	v_mfma_f32_16x16x32_bf16 v[28:31], v[194:197], v[226:229], v[28:31]
	s_barrier
	s_add_i32 s55, s55, 2
	s_add_u32 s6, s6, 0x10000
	s_addc_u32 s7, s7, 0
	s_cmp_gt_u32 s55, 41
.LBB0_1249:
	s_add_u32 s11, s12, s6
	v_add_u32_e32 v160, s40, v150
	s_addc_u32 s18, s13, s7
	ds_read_b128 v[152:155], v160
	ds_read_b128 v[156:159], v160 offset:1024
	ds_read_b128 v[164:167], v160 offset:2048
	ds_read_b128 v[168:171], v160 offset:3072
	v_add_u32_e32 v160, s41, v150
	s_add_u32 s11, s11, 0x10000
	ds_read_b128 v[172:175], v160
	ds_read_b128 v[182:185], v160 offset:1024
	ds_read_b128 v[190:193], v160 offset:2048
	ds_read_b128 v[194:197], v160 offset:3072
	s_addc_u32 s18, s18, 0
	s_add_u32 s19, s49, s6
	s_addc_u32 s21, s50, s7
	s_cmp_eq_u32 s6, 0x150000
	s_cselect_b32 s22, s52, s11
	s_cselect_b32 s23, s51, s18
	s_cselect_b32 s20, s54, s19
	s_cselect_b32 s21, s53, s21
	s_add_u32 s18, s22, 0x8000
	s_addc_u32 s19, s23, 0
	s_add_i32 s11, s29, 0xc000
	v_lshl_add_u64 v[160:161], v[144:145], 0, s[6:7]
	s_mov_b32 m0, s11
	s_add_i32 s48, s29, 0xe000
	ds_read_b128 v[198:201], v151
	ds_read_b128 v[202:205], v151 offset:1024
	ds_read_b128 v[206:209], v151 offset:2048
	ds_read_b128 v[210:213], v151 offset:3072
	ds_read_b128 v[214:217], v151 offset:4096
	ds_read_b128 v[218:221], v151 offset:5120
	ds_read_b128 v[222:225], v151 offset:6144
	ds_read_b128 v[226:229], v151 offset:7168
	global_load_lds_dwordx4 v[160:161], off sc1
	v_lshl_add_u64 v[160:161], v[146:147], 0, s[6:7]
	s_mov_b32 m0, s48
	s_nop 0
	global_load_lds_dwordx4 v[160:161], off sc1
	s_waitcnt vmcnt(8)
	s_waitcnt lgkmcnt(0)
	s_barrier
	s_waitcnt lgkmcnt(0)
	v_mfma_f32_16x16x32_bf16 v[128:131], v[152:155], v[198:201], v[128:131]
	v_mfma_f32_16x16x32_bf16 v[132:135], v[164:167], v[198:201], v[132:135]
	v_mfma_f32_16x16x32_bf16 v[112:115], v[152:155], v[206:209], v[112:115]
	v_mfma_f32_16x16x32_bf16 v[116:119], v[164:167], v[206:209], v[116:119]
	v_mfma_f32_16x16x32_bf16 v[96:99], v[152:155], v[214:217], v[96:99]
	v_mfma_f32_16x16x32_bf16 v[100:103], v[164:167], v[214:217], v[100:103]
	v_mfma_f32_16x16x32_bf16 v[72:75], v[152:155], v[222:225], v[72:75]
	v_mfma_f32_16x16x32_bf16 v[76:79], v[164:167], v[222:225], v[76:79]
	v_mfma_f32_16x16x32_bf16 v[128:131], v[156:159], v[202:205], v[128:131]
	v_mfma_f32_16x16x32_bf16 v[132:135], v[168:171], v[202:205], v[132:135]
	v_mfma_f32_16x16x32_bf16 v[112:115], v[156:159], v[210:213], v[112:115]
	v_mfma_f32_16x16x32_bf16 v[116:119], v[168:171], v[210:213], v[116:119]
	v_mfma_f32_16x16x32_bf16 v[96:99], v[156:159], v[218:221], v[96:99]
	v_mfma_f32_16x16x32_bf16 v[100:103], v[168:171], v[218:221], v[100:103]
	v_mfma_f32_16x16x32_bf16 v[72:75], v[156:159], v[226:229], v[72:75]
	v_mfma_f32_16x16x32_bf16 v[76:79], v[168:171], v[226:229], v[76:79]
	v_mfma_f32_16x16x32_bf16 v[136:139], v[172:175], v[198:201], v[136:139]
	v_mfma_f32_16x16x32_bf16 v[140:143], v[190:193], v[198:201], v[140:143]
	v_mfma_f32_16x16x32_bf16 v[120:123], v[172:175], v[206:209], v[120:123]
	v_mfma_f32_16x16x32_bf16 v[124:127], v[190:193], v[206:209], v[124:127]
	v_mfma_f32_16x16x32_bf16 v[104:107], v[172:175], v[214:217], v[104:107]
	v_mfma_f32_16x16x32_bf16 v[108:111], v[190:193], v[214:217], v[108:111]
	v_mfma_f32_16x16x32_bf16 v[88:91], v[172:175], v[222:225], v[88:91]
	v_mfma_f32_16x16x32_bf16 v[92:95], v[190:193], v[222:225], v[92:95]
	v_mfma_f32_16x16x32_bf16 v[136:139], v[182:185], v[202:205], v[136:139]
	v_mfma_f32_16x16x32_bf16 v[140:143], v[194:197], v[202:205], v[140:143]
	v_mfma_f32_16x16x32_bf16 v[120:123], v[182:185], v[210:213], v[120:123]
	v_mfma_f32_16x16x32_bf16 v[124:127], v[194:197], v[210:213], v[124:127]
	v_mfma_f32_16x16x32_bf16 v[104:107], v[182:185], v[218:221], v[104:107]
	v_mfma_f32_16x16x32_bf16 v[108:111], v[194:197], v[218:221], v[108:111]
	v_mfma_f32_16x16x32_bf16 v[88:91], v[182:185], v[226:229], v[88:91]
	v_mfma_f32_16x16x32_bf16 v[92:95], v[194:197], v[226:229], v[92:95]
	s_barrier
	s_add_i32 s56, s40, s27
	s_mov_b32 m0, s56
	ds_read_b128 v[198:201], v151 offset:16384
	ds_read_b128 v[202:205], v151 offset:17408
	ds_read_b128 v[206:209], v151 offset:18432
	ds_read_b128 v[210:213], v151 offset:19456
	ds_read_b128 v[214:217], v151 offset:20480
	ds_read_b128 v[218:221], v151 offset:21504
	ds_read_b128 v[222:225], v151 offset:22528
	ds_read_b128 v[226:229], v151 offset:23552
	global_load_lds_dwordx4 v2, s[20:21] sc1
	s_add_i32 m0, s56, 0x2000
	s_add_u32 s56, s20, 0x4000
	s_addc_u32 s57, s21, 0
	s_add_i32 s58, s41, s27
	global_load_lds_dwordx4 v6, s[20:21] sc1
	s_mov_b32 m0, s58
	s_nop 0
	global_load_lds_dwordx4 v2, s[56:57] sc1
	s_add_i32 m0, s58, 0x2000
	s_nop 0
	global_load_lds_dwordx4 v6, s[56:57] sc1
	s_mov_b32 m0, s29
	s_nop 0
	global_load_lds_dwordx4 v0, s[22:23] sc1
	s_mov_b32 m0, s30
	s_nop 0
	global_load_lds_dwordx4 v4, s[22:23] sc1
	s_waitcnt vmcnt(8)
	s_waitcnt lgkmcnt(0)
	s_barrier
	s_waitcnt lgkmcnt(0)
	v_mfma_f32_16x16x32_bf16 v[64:67], v[152:155], v[198:201], v[64:67]
	v_mfma_f32_16x16x32_bf16 v[68:71], v[164:167], v[198:201], v[68:71]
	v_mfma_f32_16x16x32_bf16 v[48:51], v[152:155], v[206:209], v[48:51]
	v_mfma_f32_16x16x32_bf16 v[52:55], v[164:167], v[206:209], v[52:55]
	v_mfma_f32_16x16x32_bf16 v[32:35], v[152:155], v[214:217], v[32:35]
	v_mfma_f32_16x16x32_bf16 v[36:39], v[164:167], v[214:217], v[36:39]
	v_mfma_f32_16x16x32_bf16 v[16:19], v[152:155], v[222:225], v[16:19]
	v_mfma_f32_16x16x32_bf16 v[20:23], v[164:167], v[222:225], v[20:23]
	v_mfma_f32_16x16x32_bf16 v[64:67], v[156:159], v[202:205], v[64:67]
	v_mfma_f32_16x16x32_bf16 v[68:71], v[168:171], v[202:205], v[68:71]
	v_mfma_f32_16x16x32_bf16 v[48:51], v[156:159], v[210:213], v[48:51]
	v_mfma_f32_16x16x32_bf16 v[52:55], v[168:171], v[210:213], v[52:55]
	v_mfma_f32_16x16x32_bf16 v[32:35], v[156:159], v[218:221], v[32:35]
	v_mfma_f32_16x16x32_bf16 v[36:39], v[168:171], v[218:221], v[36:39]
	v_mfma_f32_16x16x32_bf16 v[16:19], v[156:159], v[226:229], v[16:19]
	v_mfma_f32_16x16x32_bf16 v[20:23], v[168:171], v[226:229], v[20:23]
	v_mfma_f32_16x16x32_bf16 v[80:83], v[172:175], v[198:201], v[80:83]
	v_mfma_f32_16x16x32_bf16 v[84:87], v[190:193], v[198:201], v[84:87]
	v_mfma_f32_16x16x32_bf16 v[56:59], v[172:175], v[206:209], v[56:59]
	v_mfma_f32_16x16x32_bf16 v[60:63], v[190:193], v[206:209], v[60:63]
	v_mfma_f32_16x16x32_bf16 v[40:43], v[172:175], v[214:217], v[40:43]
	v_mfma_f32_16x16x32_bf16 v[44:47], v[190:193], v[214:217], v[44:47]
	v_mfma_f32_16x16x32_bf16 v[24:27], v[172:175], v[222:225], v[24:27]
	v_mfma_f32_16x16x32_bf16 v[28:31], v[190:193], v[222:225], v[28:31]
	v_mfma_f32_16x16x32_bf16 v[80:83], v[182:185], v[202:205], v[80:83]
	v_mfma_f32_16x16x32_bf16 v[84:87], v[194:197], v[202:205], v[84:87]
	v_mfma_f32_16x16x32_bf16 v[56:59], v[182:185], v[210:213], v[56:59]
	v_mfma_f32_16x16x32_bf16 v[60:63], v[194:197], v[210:213], v[60:63]
	v_mfma_f32_16x16x32_bf16 v[40:43], v[182:185], v[218:221], v[40:43]
	v_mfma_f32_16x16x32_bf16 v[44:47], v[194:197], v[218:221], v[44:47]
	v_mfma_f32_16x16x32_bf16 v[24:27], v[182:185], v[226:229], v[24:27]
	v_mfma_f32_16x16x32_bf16 v[28:31], v[194:197], v[226:229], v[28:31]
	s_barrier
	v_add_u32_e32 v160, s43, v150
	ds_read_b128 v[152:155], v160
	ds_read_b128 v[156:159], v160 offset:1024
	ds_read_b128 v[164:167], v160 offset:2048
	ds_read_b128 v[168:171], v160 offset:3072
	v_add_u32_e32 v160, s44, v150
	ds_read_b128 v[172:175], v160
	ds_read_b128 v[182:185], v160 offset:1024
	ds_read_b128 v[190:193], v160 offset:2048
	ds_read_b128 v[194:197], v160 offset:3072
	s_add_u32 s22, s22, 0x4000
	s_addc_u32 s23, s23, 0
	s_mov_b32 m0, s31
	ds_read_b128 v[198:201], v151 offset:32768
	ds_read_b128 v[202:205], v151 offset:33792
	ds_read_b128 v[206:209], v151 offset:34816
	ds_read_b128 v[210:213], v151 offset:35840
	ds_read_b128 v[214:217], v151 offset:36864
	ds_read_b128 v[218:221], v151 offset:37888
	ds_read_b128 v[222:225], v151 offset:38912
	ds_read_b128 v[226:229], v151 offset:39936
	global_load_lds_dwordx4 v0, s[22:23] sc1
	s_mov_b32 m0, s35
	s_nop 0
	global_load_lds_dwordx4 v4, s[22:23] sc1
	s_waitcnt vmcnt(8)
	s_waitcnt lgkmcnt(0)
	s_barrier
	s_waitcnt lgkmcnt(0)
	v_mfma_f32_16x16x32_bf16 v[128:131], v[152:155], v[198:201], v[128:131]
	v_mfma_f32_16x16x32_bf16 v[132:135], v[164:167], v[198:201], v[132:135]
	v_mfma_f32_16x16x32_bf16 v[112:115], v[152:155], v[206:209], v[112:115]
	v_mfma_f32_16x16x32_bf16 v[116:119], v[164:167], v[206:209], v[116:119]
	v_mfma_f32_16x16x32_bf16 v[96:99], v[152:155], v[214:217], v[96:99]
	v_mfma_f32_16x16x32_bf16 v[100:103], v[164:167], v[214:217], v[100:103]
	v_mfma_f32_16x16x32_bf16 v[72:75], v[152:155], v[222:225], v[72:75]
	v_mfma_f32_16x16x32_bf16 v[76:79], v[164:167], v[222:225], v[76:79]
	v_mfma_f32_16x16x32_bf16 v[128:131], v[156:159], v[202:205], v[128:131]
	v_mfma_f32_16x16x32_bf16 v[132:135], v[168:171], v[202:205], v[132:135]
	v_mfma_f32_16x16x32_bf16 v[112:115], v[156:159], v[210:213], v[112:115]
	v_mfma_f32_16x16x32_bf16 v[116:119], v[168:171], v[210:213], v[116:119]
	v_mfma_f32_16x16x32_bf16 v[96:99], v[156:159], v[218:221], v[96:99]
	v_mfma_f32_16x16x32_bf16 v[100:103], v[168:171], v[218:221], v[100:103]
	v_mfma_f32_16x16x32_bf16 v[72:75], v[156:159], v[226:229], v[72:75]
	v_mfma_f32_16x16x32_bf16 v[76:79], v[168:171], v[226:229], v[76:79]
	v_mfma_f32_16x16x32_bf16 v[136:139], v[172:175], v[198:201], v[136:139]
	v_mfma_f32_16x16x32_bf16 v[140:143], v[190:193], v[198:201], v[140:143]
	v_mfma_f32_16x16x32_bf16 v[120:123], v[172:175], v[206:209], v[120:123]
	v_mfma_f32_16x16x32_bf16 v[124:127], v[190:193], v[206:209], v[124:127]
	v_mfma_f32_16x16x32_bf16 v[104:107], v[172:175], v[214:217], v[104:107]
	v_mfma_f32_16x16x32_bf16 v[108:111], v[190:193], v[214:217], v[108:111]
	v_mfma_f32_16x16x32_bf16 v[88:91], v[172:175], v[222:225], v[88:91]
	v_mfma_f32_16x16x32_bf16 v[92:95], v[190:193], v[222:225], v[92:95]
	v_mfma_f32_16x16x32_bf16 v[136:139], v[182:185], v[202:205], v[136:139]
	v_mfma_f32_16x16x32_bf16 v[140:143], v[194:197], v[202:205], v[140:143]
	v_mfma_f32_16x16x32_bf16 v[120:123], v[182:185], v[210:213], v[120:123]
	v_mfma_f32_16x16x32_bf16 v[124:127], v[194:197], v[210:213], v[124:127]
	v_mfma_f32_16x16x32_bf16 v[104:107], v[182:185], v[218:221], v[104:107]
	v_mfma_f32_16x16x32_bf16 v[108:111], v[194:197], v[218:221], v[108:111]
	v_mfma_f32_16x16x32_bf16 v[88:91], v[182:185], v[226:229], v[88:91]
	v_mfma_f32_16x16x32_bf16 v[92:95], v[194:197], v[226:229], v[92:95]
	s_barrier
	s_add_u32 s22, s20, 0x8000
	s_addc_u32 s23, s21, 0
	s_add_i32 s56, s43, s27
	s_mov_b32 m0, s56
	ds_read_b128 v[198:201], v151 offset:49152
	ds_read_b128 v[202:205], v151 offset:50176
	ds_read_b128 v[206:209], v151 offset:51200
	ds_read_b128 v[210:213], v151 offset:52224
	ds_read_b128 v[214:217], v151 offset:53248
	ds_read_b128 v[218:221], v151 offset:54272
	ds_read_b128 v[222:225], v151 offset:55296
	ds_read_b128 v[226:229], v151 offset:56320
	global_load_lds_dwordx4 v2, s[22:23] sc1
	s_add_i32 m0, s56, 0x2000
	s_add_u32 s20, s20, 0xc000
	global_load_lds_dwordx4 v6, s[22:23] sc1
	s_addc_u32 s21, s21, 0
	s_add_i32 s22, s44, s27
	s_mov_b32 m0, s22
	s_nop 0
	global_load_lds_dwordx4 v2, s[20:21] sc1
	s_add_i32 m0, s22, 0x2000
	s_nop 0
	global_load_lds_dwordx4 v6, s[20:21] sc1
	s_mov_b32 m0, s38
	s_nop 0
	global_load_lds_dwordx4 v0, s[18:19] sc1
	s_mov_b32 m0, s39
	s_nop 0
	global_load_lds_dwordx4 v4, s[18:19] sc1
	s_waitcnt vmcnt(8)
	s_waitcnt lgkmcnt(0)
	s_barrier
	s_waitcnt lgkmcnt(0)
	v_mfma_f32_16x16x32_bf16 v[64:67], v[152:155], v[198:201], v[64:67]
	v_mfma_f32_16x16x32_bf16 v[68:71], v[164:167], v[198:201], v[68:71]
	v_mfma_f32_16x16x32_bf16 v[48:51], v[152:155], v[206:209], v[48:51]
	v_mfma_f32_16x16x32_bf16 v[52:55], v[164:167], v[206:209], v[52:55]
	v_mfma_f32_16x16x32_bf16 v[32:35], v[152:155], v[214:217], v[32:35]
	v_mfma_f32_16x16x32_bf16 v[36:39], v[164:167], v[214:217], v[36:39]
	v_mfma_f32_16x16x32_bf16 v[16:19], v[152:155], v[222:225], v[16:19]
	v_mfma_f32_16x16x32_bf16 v[20:23], v[164:167], v[222:225], v[20:23]
	v_mfma_f32_16x16x32_bf16 v[64:67], v[156:159], v[202:205], v[64:67]
	v_mfma_f32_16x16x32_bf16 v[68:71], v[168:171], v[202:205], v[68:71]
	v_mfma_f32_16x16x32_bf16 v[48:51], v[156:159], v[210:213], v[48:51]
	v_mfma_f32_16x16x32_bf16 v[52:55], v[168:171], v[210:213], v[52:55]
	v_mfma_f32_16x16x32_bf16 v[32:35], v[156:159], v[218:221], v[32:35]
	v_mfma_f32_16x16x32_bf16 v[36:39], v[168:171], v[218:221], v[36:39]
	v_mfma_f32_16x16x32_bf16 v[16:19], v[156:159], v[226:229], v[16:19]
	v_mfma_f32_16x16x32_bf16 v[20:23], v[168:171], v[226:229], v[20:23]
	v_mfma_f32_16x16x32_bf16 v[80:83], v[172:175], v[198:201], v[80:83]
	v_mfma_f32_16x16x32_bf16 v[84:87], v[190:193], v[198:201], v[84:87]
	v_mfma_f32_16x16x32_bf16 v[56:59], v[172:175], v[206:209], v[56:59]
	v_mfma_f32_16x16x32_bf16 v[60:63], v[190:193], v[206:209], v[60:63]
	v_mfma_f32_16x16x32_bf16 v[40:43], v[172:175], v[214:217], v[40:43]
	v_mfma_f32_16x16x32_bf16 v[44:47], v[190:193], v[214:217], v[44:47]
	v_mfma_f32_16x16x32_bf16 v[24:27], v[172:175], v[222:225], v[24:27]
	v_mfma_f32_16x16x32_bf16 v[28:31], v[190:193], v[222:225], v[28:31]
	v_mfma_f32_16x16x32_bf16 v[80:83], v[182:185], v[202:205], v[80:83]
	v_mfma_f32_16x16x32_bf16 v[84:87], v[194:197], v[202:205], v[84:87]
	v_mfma_f32_16x16x32_bf16 v[56:59], v[182:185], v[210:213], v[56:59]
	v_mfma_f32_16x16x32_bf16 v[60:63], v[194:197], v[210:213], v[60:63]
	v_mfma_f32_16x16x32_bf16 v[40:43], v[182:185], v[218:221], v[40:43]
	v_mfma_f32_16x16x32_bf16 v[44:47], v[194:197], v[218:221], v[44:47]
	v_mfma_f32_16x16x32_bf16 v[24:27], v[182:185], v[226:229], v[24:27]
	v_mfma_f32_16x16x32_bf16 v[28:31], v[194:197], v[226:229], v[28:31]
	s_barrier
	s_add_i32 s55, s55, 2
	s_add_u32 s6, s6, 0x10000
	s_addc_u32 s7, s7, 0
	s_cmp_gt_u32 s55, 41
	s_cbranch_scc0 .LBB0_1249
	s_add_u32 s6, s49, 0xffff0000
	s_addc_u32 s7, s50, -1
	s_and_b64 vcc, exec, s[4:5]
	s_cbranch_vccnz .LBB0_1236
	s_mov_b32 s8, s45
	s_mov_b32 s10, s46
	s_mov_b64 s[12:13], s[16:17]
	s_mov_b32 s42, s47
	s_andn2_b64 vcc, exec, s[0:1]
	s_cbranch_vccnz .LBB0_1237
